# inproj GEMM epilogue rewritten (permuted A rows -> 8-byte transposed stores), unit-head vmcnt(0) removed, NA local step de-serialised (bias lookups/K/V LDS reads hoisted)
# speedup vs baseline: 1.0560x; 1.0198x over previous
.LBB0_103:
	s_ashr_i32 s23, s22, 31
	s_lshl_b64 s[2:3], s[22:23], 19
	s_add_u32 s58, s90, s2
	s_addc_u32 s59, s77, s3
	s_and_b64 s[2:3], s[46:47], exec
	s_cselect_b32 s1, s59, s49
	s_cselect_b32 s23, s58, s48
	s_add_u32 s34, s34, 0x3e080
	s_addc_u32 s35, s35, 0
	s_add_u32 s51, s48, 0x100
	v_mov_b32_e32 v2, 0
	s_addc_u32 s52, s49, 0
	s_mov_b32 s53, -2
	v_mov_b32_e32 v3, v2
	v_mov_b32_e32 v4, v2
	v_mov_b32_e32 v5, v2
	v_mov_b32_e32 v6, v2
	v_mov_b32_e32 v7, v2
	v_mov_b32_e32 v8, v2
	v_mov_b32_e32 v9, v2
	v_mov_b32_e32 v10, v2
	v_mov_b32_e32 v11, v2
	v_mov_b32_e32 v12, v2
	v_mov_b32_e32 v13, v2
	v_mov_b32_e32 v14, v2
	v_mov_b32_e32 v15, v2
	v_mov_b32_e32 v16, v2
	v_mov_b32_e32 v17, v2
	v_mov_b32_e32 v18, v2
	v_mov_b32_e32 v19, v2
	v_mov_b32_e32 v20, v2
	v_mov_b32_e32 v21, v2
	v_mov_b32_e32 v22, v2
	v_mov_b32_e32 v23, v2
	v_mov_b32_e32 v24, v2
	v_mov_b32_e32 v25, v2
	v_mov_b32_e32 v26, v2
	v_mov_b32_e32 v27, v2
	v_mov_b32_e32 v28, v2
	v_mov_b32_e32 v29, v2
	v_mov_b32_e32 v30, v2
	v_mov_b32_e32 v31, v2
	v_mov_b32_e32 v32, v2
	v_mov_b32_e32 v33, v2
	v_mov_b32_e32 v66, v2
	v_mov_b32_e32 v67, v2
	v_mov_b32_e32 v68, v2
	v_mov_b32_e32 v69, v2
	v_mov_b32_e32 v70, v2
	v_mov_b32_e32 v71, v2
	v_mov_b32_e32 v72, v2
	v_mov_b32_e32 v73, v2
	v_mov_b32_e32 v74, v2
	v_mov_b32_e32 v75, v2
	v_mov_b32_e32 v76, v2
	v_mov_b32_e32 v77, v2
	v_mov_b32_e32 v78, v2
	v_mov_b32_e32 v79, v2
	v_mov_b32_e32 v80, v2
	v_mov_b32_e32 v81, v2
	v_mov_b32_e32 v82, v2
	v_mov_b32_e32 v83, v2
	v_mov_b32_e32 v84, v2
	v_mov_b32_e32 v85, v2
	v_mov_b32_e32 v86, v2
	v_mov_b32_e32 v87, v2
	v_mov_b32_e32 v88, v2
	v_mov_b32_e32 v89, v2
	v_mov_b32_e32 v90, v2
	v_mov_b32_e32 v91, v2
	v_mov_b32_e32 v92, v2
	v_mov_b32_e32 v93, v2
	v_mov_b32_e32 v94, v2
	v_mov_b32_e32 v95, v2
	v_mov_b32_e32 v96, v2
	v_mov_b32_e32 v97, v2
	v_mov_b32_e32 v34, v2
	v_mov_b32_e32 v35, v2
	v_mov_b32_e32 v36, v2
	v_mov_b32_e32 v37, v2
	v_mov_b32_e32 v38, v2
	v_mov_b32_e32 v39, v2
	v_mov_b32_e32 v40, v2
	v_mov_b32_e32 v41, v2
	v_mov_b32_e32 v42, v2
	v_mov_b32_e32 v43, v2
	v_mov_b32_e32 v44, v2
	v_mov_b32_e32 v45, v2
	v_mov_b32_e32 v46, v2
	v_mov_b32_e32 v47, v2
	v_mov_b32_e32 v48, v2
	v_mov_b32_e32 v49, v2
	v_mov_b32_e32 v50, v2
	v_mov_b32_e32 v51, v2
	v_mov_b32_e32 v52, v2
	v_mov_b32_e32 v53, v2
	v_mov_b32_e32 v54, v2
	v_mov_b32_e32 v55, v2
	v_mov_b32_e32 v56, v2
	v_mov_b32_e32 v57, v2
	v_mov_b32_e32 v58, v2
	v_mov_b32_e32 v59, v2
	v_mov_b32_e32 v60, v2
	v_mov_b32_e32 v61, v2
	v_mov_b32_e32 v62, v2
	v_mov_b32_e32 v63, v2
	v_mov_b32_e32 v64, v2
	v_mov_b32_e32 v65, v2
	v_mov_b32_e32 v130, v2
	v_mov_b32_e32 v131, v2
	v_mov_b32_e32 v132, v2
	v_mov_b32_e32 v133, v2
	v_mov_b32_e32 v134, v2
	v_mov_b32_e32 v135, v2
	v_mov_b32_e32 v136, v2
	v_mov_b32_e32 v137, v2
	v_mov_b32_e32 v138, v2
	v_mov_b32_e32 v139, v2
	v_mov_b32_e32 v140, v2
	v_mov_b32_e32 v141, v2
	v_mov_b32_e32 v142, v2
	v_mov_b32_e32 v143, v2
	v_mov_b32_e32 v144, v2
	v_mov_b32_e32 v145, v2
	v_mov_b32_e32 v146, v2
	v_mov_b32_e32 v147, v2
	v_mov_b32_e32 v148, v2
	v_mov_b32_e32 v149, v2
	v_mov_b32_e32 v150, v2
	v_mov_b32_e32 v151, v2
	v_mov_b32_e32 v152, v2
	v_mov_b32_e32 v153, v2
	v_mov_b32_e32 v154, v2
	v_mov_b32_e32 v155, v2
	v_mov_b32_e32 v156, v2
	v_mov_b32_e32 v157, v2
	v_mov_b32_e32 v158, v2
	v_mov_b32_e32 v159, v2
	v_mov_b32_e32 v160, v2
	v_mov_b32_e32 v161, v2

.LBB0_181:
	s_add_i32 s88, s44, -2
	s_add_u32 s34, s34, 0x80
	s_addc_u32 s35, s35, 0
	s_add_u32 s89, s42, 0x100
	v_mov_b32_e32 v2, 0
	s_addc_u32 s90, s43, 0
	s_mov_b32 s2, 0
	v_mov_b32_e32 v3, v2
	v_mov_b32_e32 v4, v2
	v_mov_b32_e32 v5, v2
	v_mov_b32_e32 v6, v2
	v_mov_b32_e32 v7, v2
	v_mov_b32_e32 v8, v2
	v_mov_b32_e32 v9, v2
	v_mov_b32_e32 v10, v2
	v_mov_b32_e32 v11, v2
	v_mov_b32_e32 v12, v2
	v_mov_b32_e32 v13, v2
	v_mov_b32_e32 v14, v2
	v_mov_b32_e32 v15, v2
	v_mov_b32_e32 v16, v2
	v_mov_b32_e32 v17, v2
	v_mov_b32_e32 v18, v2
	v_mov_b32_e32 v19, v2
	v_mov_b32_e32 v20, v2
	v_mov_b32_e32 v21, v2
	v_mov_b32_e32 v22, v2
	v_mov_b32_e32 v23, v2
	v_mov_b32_e32 v24, v2
	v_mov_b32_e32 v25, v2
	v_mov_b32_e32 v26, v2
	v_mov_b32_e32 v27, v2
	v_mov_b32_e32 v28, v2
	v_mov_b32_e32 v29, v2
	v_mov_b32_e32 v30, v2
	v_mov_b32_e32 v31, v2
	v_mov_b32_e32 v32, v2
	v_mov_b32_e32 v33, v2
	v_mov_b32_e32 v66, v2
	v_mov_b32_e32 v67, v2
	v_mov_b32_e32 v68, v2
	v_mov_b32_e32 v69, v2
	v_mov_b32_e32 v70, v2
	v_mov_b32_e32 v71, v2
	v_mov_b32_e32 v72, v2
	v_mov_b32_e32 v73, v2
	v_mov_b32_e32 v74, v2
	v_mov_b32_e32 v75, v2
	v_mov_b32_e32 v76, v2
	v_mov_b32_e32 v77, v2
	v_mov_b32_e32 v78, v2
	v_mov_b32_e32 v79, v2
	v_mov_b32_e32 v80, v2
	v_mov_b32_e32 v81, v2
	v_mov_b32_e32 v82, v2
	v_mov_b32_e32 v83, v2
	v_mov_b32_e32 v84, v2
	v_mov_b32_e32 v85, v2
	v_mov_b32_e32 v86, v2
	v_mov_b32_e32 v87, v2
	v_mov_b32_e32 v88, v2
	v_mov_b32_e32 v89, v2
	v_mov_b32_e32 v90, v2
	v_mov_b32_e32 v91, v2
	v_mov_b32_e32 v92, v2
	v_mov_b32_e32 v93, v2
	v_mov_b32_e32 v94, v2
	v_mov_b32_e32 v95, v2
	v_mov_b32_e32 v96, v2
	v_mov_b32_e32 v97, v2
	v_mov_b32_e32 v34, v2
	v_mov_b32_e32 v35, v2
	v_mov_b32_e32 v36, v2
	v_mov_b32_e32 v37, v2
	v_mov_b32_e32 v38, v2
	v_mov_b32_e32 v39, v2
	v_mov_b32_e32 v40, v2
	v_mov_b32_e32 v41, v2
	v_mov_b32_e32 v42, v2
	v_mov_b32_e32 v43, v2
	v_mov_b32_e32 v44, v2
	v_mov_b32_e32 v45, v2
	v_mov_b32_e32 v46, v2
	v_mov_b32_e32 v47, v2
	v_mov_b32_e32 v48, v2
	v_mov_b32_e32 v49, v2
	v_mov_b32_e32 v50, v2
	v_mov_b32_e32 v51, v2
	v_mov_b32_e32 v52, v2
	v_mov_b32_e32 v53, v2
	v_mov_b32_e32 v54, v2
	v_mov_b32_e32 v55, v2
	v_mov_b32_e32 v56, v2
	v_mov_b32_e32 v57, v2
	v_mov_b32_e32 v58, v2
	v_mov_b32_e32 v59, v2
	v_mov_b32_e32 v60, v2
	v_mov_b32_e32 v61, v2
	v_mov_b32_e32 v62, v2
	v_mov_b32_e32 v63, v2
	v_mov_b32_e32 v64, v2
	v_mov_b32_e32 v65, v2
	v_mov_b32_e32 v98, v2
	v_mov_b32_e32 v99, v2
	v_mov_b32_e32 v100, v2
	v_mov_b32_e32 v101, v2
	v_mov_b32_e32 v102, v2
	v_mov_b32_e32 v103, v2
	v_mov_b32_e32 v104, v2
	v_mov_b32_e32 v105, v2
	v_mov_b32_e32 v106, v2
	v_mov_b32_e32 v107, v2
	v_mov_b32_e32 v108, v2
	v_mov_b32_e32 v109, v2
	v_mov_b32_e32 v110, v2
	v_mov_b32_e32 v111, v2
	v_mov_b32_e32 v112, v2
	v_mov_b32_e32 v113, v2
	v_mov_b32_e32 v114, v2
	v_mov_b32_e32 v115, v2
	v_mov_b32_e32 v116, v2
	v_mov_b32_e32 v117, v2
	v_mov_b32_e32 v118, v2
	v_mov_b32_e32 v119, v2
	v_mov_b32_e32 v120, v2
	v_mov_b32_e32 v121, v2
	v_mov_b32_e32 v122, v2
	v_mov_b32_e32 v123, v2
	v_mov_b32_e32 v124, v2
	v_mov_b32_e32 v125, v2
	v_mov_b32_e32 v126, v2
	v_mov_b32_e32 v127, v2
	v_mov_b32_e32 v128, v2
	v_mov_b32_e32 v129, v2

.LBB0_247:
	s_or_b64 exec, exec, s[0:1]
	v_max_f32_e32 v70, v136, v136
	v_max_f32_e32 v71, v181, v181
	v_max_f32_e32 v70, v71, v70
	v_max_f32_e32 v71, v72, v72
	v_max_f32_e32 v75, v182, v182
	v_max_f32_e32 v71, v75, v71
	v_max_f32_e32 v75, v68, v68
	v_max_f32_e32 v160, v69, v69
	v_max_f32_e32 v75, v160, v75
	v_max3_f32 v75, v74, v73, v75
	v_cmp_lt_i32_e32 vcc, v210, v208
	v_max3_f32 v70, v70, v71, v75
	s_nop 0
	v_cndmask_b32_e32 v71, v207, v210, vcc
	v_lshlrev_b32_e32 v71, 2, v71
	ds_bpermute_b32 v71, v71, v70
	v_cmp_lt_i32_e32 vcc, v209, v208
	s_waitcnt lgkmcnt(0)
	v_max_f32_e32 v71, v71, v71
	v_max_f32_e32 v70, v70, v71
	v_cndmask_b32_e32 v71, v207, v209, vcc
	v_lshlrev_b32_e32 v71, 2, v71
	ds_bpermute_b32 v71, v71, v70
	s_waitcnt lgkmcnt(0)
	v_max3_f32 v160, v177, v70, v71
	v_sub_f32_e32 v71, v181, v160
	v_exp_f32_e32 v71, v71
	v_sub_f32_e32 v136, v136, v160
	v_sub_f32_e32 v70, v177, v160
	v_exp_f32_e32 v177, v136
	v_sub_f32_e32 v136, v182, v160
	v_exp_f32_e32 v181, v136
	v_sub_f32_e32 v72, v72, v160
	v_exp_f32_e32 v72, v72
	v_sub_f32_e32 v74, v74, v160
	v_add_f32_e32 v75, 0, v71
	v_exp_f32_e32 v74, v74
	v_sub_f32_e32 v73, v73, v160
	v_add_f32_e32 v75, v177, v75
	v_exp_f32_e32 v73, v73
	v_sub_f32_e32 v69, v69, v160
	v_add_f32_e32 v75, v181, v75
	v_exp_f32_e32 v183, v69
	v_add_f32_e32 v75, v72, v75
	v_add_f32_e32 v75, v74, v75
	v_add_f32_e32 v75, v73, v75
	v_sub_f32_e32 v68, v68, v160
	v_add_f32_e32 v69, v183, v75
	v_exp_f32_e32 v75, v68
	v_exp_f32_e32 v182, v70
	v_cvt_pk_bf16_f32 v68, v71, v177
	v_cvt_pk_bf16_f32 v70, v74, v73
	v_add_f32_e32 v136, v75, v69
	v_fmac_f32_e32 v136, v0, v182
	v_cvt_pk_bf16_f32 v69, v181, v72
	v_cvt_pk_bf16_f32 v71, v183, v75
	v_pk_mul_f32 v[30:31], v[30:31], v[182:183] op_sel_hi:[1,0]
	v_pk_mul_f32 v[28:29], v[28:29], v[182:183] op_sel_hi:[1,0]
	v_pk_mul_f32 v[38:39], v[38:39], v[182:183] op_sel_hi:[1,0]
	v_pk_mul_f32 v[36:37], v[36:37], v[182:183] op_sel_hi:[1,0]
	s_waitcnt lgkmcnt(0)
	v_mfma_f32_16x16x32_bf16 v[28:31], v[226:229], v[68:71], v[28:31]
	v_pk_mul_f32 v[42:43], v[42:43], v[182:183] op_sel_hi:[1,0]
	v_pk_mul_f32 v[40:41], v[40:41], v[182:183] op_sel_hi:[1,0]
	v_mfma_f32_16x16x32_bf16 v[36:39], v[230:233], v[68:71], v[36:39]
	v_pk_mul_f32 v[50:51], v[50:51], v[182:183] op_sel_hi:[1,0]
	v_pk_mul_f32 v[48:49], v[48:49], v[182:183] op_sel_hi:[1,0]
	v_mfma_f32_16x16x32_bf16 v[40:43], v[234:237], v[68:71], v[40:43]
	v_mov_b32_e32 v177, v160
	v_mov_b32_e32 v0, v136
	v_mfma_f32_16x16x32_bf16 v[48:51], v[242:245], v[68:71], v[48:51]

.LBB0_249:
	s_add_i32 s0, s79, 4
	s_min_i32 s12, s0, s2
	v_mov_b32_e32 v68, 0x5c000
	v_mad_i64_i32 v[68:69], s[0:1], s12, v68, v[76:77]
	s_add_i32 s0, s78, 0xc000
	s_and_b32 s0, s0, 0xc000
	s_add_i32 s0, s0, 0
	s_add_i32 s13, s0, s3
	s_lshl_b32 s0, s12, 6
	s_waitcnt vmcnt(4)
	s_barrier
	s_add_i32 m0, s13, 0x10000
	s_ashr_i32 s1, s0, 31
	global_load_lds_dwordx4 v[68:69], off
	v_lshl_add_u64 v[68:69], s[0:1], 1, v[78:79]
	s_add_i32 m0, s13, 0x12000
	s_add_i32 s79, s79, 1
	global_load_lds_dwordx4 v[68:69], off
	s_and_b32 s12, s78, 0xc000
	v_cmp_ge_u32_e32 vcc, s79, v120
	s_add_i32 s80, s12, 0
	v_cmp_lt_u32_e64 s[0:1], s79, v121
	s_and_b64 s[82:83], s[16:17], vcc
	s_add_i32 s80, s80, 0x10000
	s_and_b64 s[0:1], s[82:83], s[0:1]
	v_add_u32_e32 v68, s80, v80
	v_add_u32_e32 v69, s80, v83
	s_andn2_b64 vcc, exec, s[0:1]
	v_add_u32_e32 v183, v68, v81
	v_add_u32_e32 v184, v68, v82
	v_add_u32_e32 v181, v69, v116
	v_add_u32_e32 v182, v69, v117
	s_cbranch_vccnz .LBB0_267
	ds_read_b128 v[68:71], v183
	ds_read_b128 v[72:75], v184
	ds_read_b128 v[198:201], v181
	ds_read_b128 v[186:189], v182
	v_add_u32_e32 v190, s77, v175
	ds_read_b32 v190, v190
	v_add_u32_e32 v191, s77, v174
	ds_read_b32 v191, v191
	v_add_u32_e32 v192, s77, v173
	ds_read_b32 v192, v192
	v_add_u32_e32 v193, s77, v172
	ds_read_b32 v193, v193
	v_add_u32_e32 v194, s77, v171
	ds_read_b32 v194, v194
	v_add_u32_e32 v195, s77, v170
	ds_read_b32 v195, v195
	v_add_u32_e32 v196, s77, v169
	ds_read_b32 v196, v196
	v_add_u32_e32 v197, s77, v168
	ds_read_b32 v197, v197
	v_add3_u32 v246, s80, v118, v119
	v_mov_b32_e32 v141, 0xf149f2ca
	v_mov_b32_e32 v185, 0xf149f2ca
	s_waitcnt lgkmcnt(10)
	v_mfma_f32_16x16x32_bf16 v[68:71], v[68:71], v[52:55], 0
	s_waitcnt lgkmcnt(8)
	v_mfma_f32_16x16x32_bf16 v[198:201], v[198:201], v[52:55], 0
	v_mfma_f32_16x16x32_bf16 v[72:75], v[72:75], v[56:59], v[68:71]
	v_mfma_f32_16x16x32_bf16 v[198:201], v[186:189], v[56:59], v[198:201]
	ds_read_b128 v[226:229], v246 offset:8192
	ds_read_b128 v[230:233], v246 offset:10240
	ds_read_b128 v[234:237], v246 offset:12288
	ds_read_b128 v[242:245], v246 offset:14336
	s_waitcnt lgkmcnt(4)
	s_nop 1
	v_add_f32_e32 v190, v72, v190
	v_cndmask_b32_e64 v185, v185, v190, s[22:23]
	v_add_f32_e32 v191, v73, v191
	v_cndmask_b32_e64 v141, v141, v191, s[38:39]
	v_mov_b32_e32 v72, 0xf149f2ca
	v_mov_b32_e32 v186, 0xf149f2ca
	v_add_f32_e32 v192, v74, v192
	v_cndmask_b32_e64 v186, v186, v192, s[48:49]
	v_add_f32_e32 v193, v75, v193
	v_cndmask_b32_e64 v72, v72, v193, s[58:59]
	v_mov_b32_e32 v73, 0xf149f2ca
	v_mov_b32_e32 v74, 0xf149f2ca
	v_add_f32_e32 v194, v198, v194
	v_cndmask_b32_e64 v74, v74, v194, s[96:97]
	v_add_f32_e32 v195, v199, v195
	v_cndmask_b32_e64 v73, v73, v195, s[42:43]
	v_mov_b32_e32 v68, 0xf149f2ca
	v_mov_b32_e32 v69, 0xf149f2ca
	v_add_f32_e32 v196, v200, v196
	v_cndmask_b32_e64 v69, v69, v196, s[44:45]
	v_add_f32_e32 v197, v201, v197
	v_cndmask_b32_e64 v68, v68, v197, s[46:47]
	v_max_f32_e32 v70, v141, v141
	v_max_f32_e32 v71, v185, v185
	v_max_f32_e32 v70, v71, v70
	v_max_f32_e32 v71, v72, v72
	v_max_f32_e32 v75, v186, v186
	v_max_f32_e32 v71, v75, v71
	v_max_f32_e32 v75, v68, v68
	v_max_f32_e32 v165, v69, v69
	v_max_f32_e32 v75, v165, v75
	v_max3_f32 v75, v74, v73, v75
	v_cmp_lt_i32_e32 vcc, v210, v208
	v_max3_f32 v70, v70, v71, v75
	s_nop 0
	v_cndmask_b32_e32 v71, v207, v210, vcc
	v_lshlrev_b32_e32 v71, 2, v71
	ds_bpermute_b32 v71, v71, v70
	v_cmp_lt_i32_e32 vcc, v209, v208
	s_waitcnt lgkmcnt(0)
	v_max_f32_e32 v71, v71, v71
	v_max_f32_e32 v70, v70, v71
	v_cndmask_b32_e32 v71, v207, v209, vcc
	v_lshlrev_b32_e32 v71, 2, v71
	ds_bpermute_b32 v71, v71, v70
	s_waitcnt lgkmcnt(0)
	v_max3_f32 v165, v180, v70, v71
	v_sub_f32_e32 v71, v185, v165
	v_exp_f32_e32 v71, v71
	v_sub_f32_e32 v141, v141, v165
	v_exp_f32_e32 v185, v141
	v_sub_f32_e32 v141, v186, v165
	v_exp_f32_e32 v186, v141
	v_sub_f32_e32 v72, v72, v165
	v_exp_f32_e32 v72, v72
	v_sub_f32_e32 v74, v74, v165
	v_add_f32_e32 v75, 0, v71
	v_exp_f32_e32 v74, v74
	v_sub_f32_e32 v73, v73, v165
	v_add_f32_e32 v75, v185, v75
	v_exp_f32_e32 v73, v73
	v_sub_f32_e32 v69, v69, v165
	v_add_f32_e32 v75, v186, v75
	v_exp_f32_e32 v187, v69
	v_add_f32_e32 v75, v72, v75
	v_add_f32_e32 v75, v74, v75
	v_add_f32_e32 v75, v73, v75
	v_sub_f32_e32 v68, v68, v165
	v_sub_f32_e32 v70, v180, v165
	v_add_f32_e32 v69, v187, v75
	v_exp_f32_e32 v75, v68
	v_exp_f32_e32 v180, v70
	v_cvt_pk_bf16_f32 v68, v71, v185
	v_cvt_pk_bf16_f32 v70, v74, v73
	v_add_f32_e32 v141, v75, v69
	v_fmac_f32_e32 v141, v176, v180
	v_cvt_pk_bf16_f32 v69, v186, v72
	v_cvt_pk_bf16_f32 v71, v187, v75
	v_pk_mul_f32 v[102:103], v[102:103], v[180:181] op_sel_hi:[1,0]
	v_pk_mul_f32 v[100:101], v[100:101], v[180:181] op_sel_hi:[1,0]
	v_pk_mul_f32 v[106:107], v[106:107], v[180:181] op_sel_hi:[1,0]
	v_pk_mul_f32 v[104:105], v[104:105], v[180:181] op_sel_hi:[1,0]
	s_waitcnt lgkmcnt(0)
	v_mfma_f32_16x16x32_bf16 v[100:103], v[226:229], v[68:71], v[100:103]
	v_pk_mul_f32 v[110:111], v[110:111], v[180:181] op_sel_hi:[1,0]
	v_pk_mul_f32 v[108:109], v[108:109], v[180:181] op_sel_hi:[1,0]
	v_mfma_f32_16x16x32_bf16 v[104:107], v[230:233], v[68:71], v[104:107]
	v_pk_mul_f32 v[114:115], v[114:115], v[180:181] op_sel_hi:[1,0]
	v_pk_mul_f32 v[112:113], v[112:113], v[180:181] op_sel_hi:[1,0]
	v_mfma_f32_16x16x32_bf16 v[108:111], v[234:237], v[68:71], v[108:111]
	v_mov_b32_e32 v180, v165
	v_mov_b32_e32 v176, v141
	v_mfma_f32_16x16x32_bf16 v[112:115], v[242:245], v[68:71], v[112:115]
.LBB0_267:
	v_cmp_ge_u32_e32 vcc, s79, v122
	v_cmp_lt_u32_e64 s[0:1], s79, v123
	s_and_b64 s[82:83], s[18:19], vcc
	s_and_b64 s[0:1], s[82:83], s[0:1]
	s_andn2_b64 vcc, exec, s[0:1]
	s_cbranch_vccnz .LBB0_285
	ds_read_b128 v[68:71], v183
	ds_read_b128 v[72:75], v184
	ds_read_b128 v[198:201], v181
	ds_read_b128 v[186:189], v182
	v_add_u32_e32 v190, s77, v167
	ds_read_b32 v190, v190
	v_add_u32_e32 v191, s77, v162
	ds_read_b32 v191, v191
	v_add_u32_e32 v192, s77, v155
	ds_read_b32 v192, v192
	v_add_u32_e32 v193, s77, v154
	ds_read_b32 v193, v193
	v_add_u32_e32 v194, s77, v153
	ds_read_b32 v194, v194
	v_add_u32_e32 v195, s77, v152
	ds_read_b32 v195, v195
	v_add_u32_e32 v196, s77, v151
	ds_read_b32 v196, v196
	v_add_u32_e32 v197, s77, v150
	ds_read_b32 v197, v197
	v_add3_u32 v246, s80, v118, v119
	v_mov_b32_e32 v140, 0xf149f2ca
	v_mov_b32_e32 v185, 0xf149f2ca
	s_waitcnt lgkmcnt(10)
	v_mfma_f32_16x16x32_bf16 v[68:71], v[68:71], v[60:63], 0
	s_waitcnt lgkmcnt(8)
	v_mfma_f32_16x16x32_bf16 v[198:201], v[198:201], v[60:63], 0
	v_mfma_f32_16x16x32_bf16 v[72:75], v[72:75], v[64:67], v[68:71]
	v_mfma_f32_16x16x32_bf16 v[198:201], v[186:189], v[64:67], v[198:201]
	ds_read_b128 v[226:229], v246 offset:8192
	ds_read_b128 v[230:233], v246 offset:10240
	ds_read_b128 v[234:237], v246 offset:12288
	ds_read_b128 v[242:245], v246 offset:14336
	s_waitcnt lgkmcnt(4)
	s_nop 1
	v_add_f32_e32 v190, v72, v190
	v_cndmask_b32_e64 v185, v185, v190, s[22:23]
	v_add_f32_e32 v191, v73, v191
	v_cndmask_b32_e64 v140, v140, v191, s[38:39]
	v_mov_b32_e32 v72, 0xf149f2ca
	v_mov_b32_e32 v186, 0xf149f2ca
	v_add_f32_e32 v192, v74, v192
	v_cndmask_b32_e64 v186, v186, v192, s[48:49]
	v_add_f32_e32 v193, v75, v193
	v_cndmask_b32_e64 v72, v72, v193, s[58:59]
	v_mov_b32_e32 v73, 0xf149f2ca
	v_mov_b32_e32 v74, 0xf149f2ca
	v_add_f32_e32 v194, v198, v194
	v_cndmask_b32_e64 v74, v74, v194, s[96:97]
	v_add_f32_e32 v195, v199, v195
	v_cndmask_b32_e64 v73, v73, v195, s[42:43]
	v_mov_b32_e32 v68, 0xf149f2ca
	v_mov_b32_e32 v69, 0xf149f2ca
	v_add_f32_e32 v196, v200, v196
	v_cndmask_b32_e64 v69, v69, v196, s[44:45]
	v_add_f32_e32 v197, v201, v197
	v_cndmask_b32_e64 v68, v68, v197, s[46:47]
	v_max_f32_e32 v70, v140, v140
	v_max_f32_e32 v71, v185, v185
	v_max_f32_e32 v70, v71, v70
	v_max_f32_e32 v71, v72, v72
	v_max_f32_e32 v75, v186, v186
	v_max_f32_e32 v71, v75, v71
	v_max_f32_e32 v75, v68, v68
	v_max_f32_e32 v166, v69, v69
	v_max_f32_e32 v75, v166, v75
	v_max3_f32 v75, v74, v73, v75
	v_cmp_lt_i32_e32 vcc, v210, v208
	v_max3_f32 v70, v70, v71, v75
	s_nop 0
	v_cndmask_b32_e32 v71, v207, v210, vcc
	v_lshlrev_b32_e32 v71, 2, v71
	ds_bpermute_b32 v71, v71, v70
	v_cmp_lt_i32_e32 vcc, v209, v208
	s_waitcnt lgkmcnt(0)
	v_max_f32_e32 v71, v71, v71
	v_max_f32_e32 v70, v70, v71
	v_cndmask_b32_e32 v71, v207, v209, vcc
	v_lshlrev_b32_e32 v71, 2, v71
	ds_bpermute_b32 v71, v71, v70
	s_waitcnt lgkmcnt(0)
	v_max3_f32 v166, v179, v70, v71
	v_sub_f32_e32 v71, v185, v166
	v_exp_f32_e32 v71, v71
	v_sub_f32_e32 v140, v140, v166
	v_sub_f32_e32 v70, v179, v166
	v_exp_f32_e32 v179, v140
	v_sub_f32_e32 v140, v186, v166
	v_exp_f32_e32 v185, v140
	v_sub_f32_e32 v72, v72, v166
	v_exp_f32_e32 v72, v72
	v_sub_f32_e32 v74, v74, v166
	v_add_f32_e32 v75, 0, v71
	v_exp_f32_e32 v74, v74
	v_sub_f32_e32 v73, v73, v166
	v_add_f32_e32 v75, v179, v75
	v_exp_f32_e32 v73, v73
	v_sub_f32_e32 v69, v69, v166
	v_add_f32_e32 v75, v185, v75
	v_exp_f32_e32 v187, v69
	v_add_f32_e32 v75, v72, v75
	v_add_f32_e32 v75, v74, v75
	v_add_f32_e32 v75, v73, v75
	v_sub_f32_e32 v68, v68, v166
	v_add_f32_e32 v69, v187, v75
	v_exp_f32_e32 v75, v68
	v_exp_f32_e32 v186, v70
	v_cvt_pk_bf16_f32 v68, v71, v179
	v_cvt_pk_bf16_f32 v70, v74, v73
	v_add_f32_e32 v140, v75, v69
	v_fmac_f32_e32 v140, v3, v186
	v_cvt_pk_bf16_f32 v69, v185, v72
	v_cvt_pk_bf16_f32 v71, v187, v75
	v_pk_mul_f32 v[94:95], v[94:95], v[186:187] op_sel_hi:[1,0]
	v_pk_mul_f32 v[92:93], v[92:93], v[186:187] op_sel_hi:[1,0]
	v_pk_mul_f32 v[90:91], v[90:91], v[186:187] op_sel_hi:[1,0]
	v_pk_mul_f32 v[88:89], v[88:89], v[186:187] op_sel_hi:[1,0]
	s_waitcnt lgkmcnt(0)
	v_mfma_f32_16x16x32_bf16 v[92:95], v[226:229], v[68:71], v[92:95]
	v_pk_mul_f32 v[86:87], v[86:87], v[186:187] op_sel_hi:[1,0]
	v_pk_mul_f32 v[84:85], v[84:85], v[186:187] op_sel_hi:[1,0]
	v_mfma_f32_16x16x32_bf16 v[88:91], v[230:233], v[68:71], v[88:91]
	v_pk_mul_f32 v[98:99], v[98:99], v[186:187] op_sel_hi:[1,0]
	v_pk_mul_f32 v[96:97], v[96:97], v[186:187] op_sel_hi:[1,0]
	v_mfma_f32_16x16x32_bf16 v[84:87], v[234:237], v[68:71], v[84:87]
	v_mov_b32_e32 v179, v166
	v_mov_b32_e32 v3, v140
	v_mfma_f32_16x16x32_bf16 v[96:99], v[242:245], v[68:71], v[96:99]
.LBB0_285:
	v_cmp_ge_u32_e32 vcc, s79, v124
	v_cmp_lt_u32_e64 s[0:1], s79, v125
	s_and_b64 s[82:83], s[40:41], vcc
	s_and_b64 s[0:1], s[82:83], s[0:1]
	s_andn2_b64 vcc, exec, s[0:1]
	s_cbranch_vccnz .LBB0_303
	ds_read_b128 v[68:71], v183
	ds_read_b128 v[72:75], v184
	ds_read_b128 v[198:201], v181
	ds_read_b128 v[186:189], v182
	v_add_u32_e32 v190, s77, v149
	ds_read_b32 v190, v190
	v_add_u32_e32 v191, s77, v148
	ds_read_b32 v191, v191
	v_add_u32_e32 v192, s77, v147
	ds_read_b32 v192, v192
	v_add_u32_e32 v193, s77, v146
	ds_read_b32 v193, v193
	v_add_u32_e32 v194, s77, v145
	ds_read_b32 v194, v194
	v_add_u32_e32 v195, s77, v144
	ds_read_b32 v195, v195
	v_add_u32_e32 v196, s77, v143
	ds_read_b32 v196, v196
	v_add_u32_e32 v197, s77, v142
	ds_read_b32 v197, v197
	v_add3_u32 v246, s80, v118, v119
	v_mov_b32_e32 v137, 0xf149f2ca
	v_mov_b32_e32 v185, 0xf149f2ca
	s_waitcnt lgkmcnt(10)
	v_mfma_f32_16x16x32_bf16 v[68:71], v[68:71], v[4:7], 0
	s_waitcnt lgkmcnt(8)
	v_mfma_f32_16x16x32_bf16 v[198:201], v[198:201], v[4:7], 0
	v_mfma_f32_16x16x32_bf16 v[72:75], v[72:75], v[8:11], v[68:71]
	v_mfma_f32_16x16x32_bf16 v[198:201], v[186:189], v[8:11], v[198:201]
	ds_read_b128 v[226:229], v246 offset:8192
	ds_read_b128 v[230:233], v246 offset:10240
	ds_read_b128 v[234:237], v246 offset:12288
	ds_read_b128 v[242:245], v246 offset:14336
	s_waitcnt lgkmcnt(4)
	s_nop 1
	v_add_f32_e32 v190, v72, v190
	v_cndmask_b32_e64 v185, v185, v190, s[22:23]
	v_add_f32_e32 v191, v73, v191
	v_cndmask_b32_e64 v137, v137, v191, s[38:39]
	v_mov_b32_e32 v72, 0xf149f2ca
	v_mov_b32_e32 v186, 0xf149f2ca
	v_add_f32_e32 v192, v74, v192
	v_cndmask_b32_e64 v186, v186, v192, s[48:49]
	v_add_f32_e32 v193, v75, v193
	v_cndmask_b32_e64 v72, v72, v193, s[58:59]
	v_mov_b32_e32 v73, 0xf149f2ca
	v_mov_b32_e32 v74, 0xf149f2ca
	v_add_f32_e32 v194, v198, v194
	v_cndmask_b32_e64 v74, v74, v194, s[96:97]
	v_add_f32_e32 v195, v199, v195
	v_cndmask_b32_e64 v73, v73, v195, s[42:43]
	v_mov_b32_e32 v68, 0xf149f2ca
	v_mov_b32_e32 v69, 0xf149f2ca
	v_add_f32_e32 v196, v200, v196
	v_cndmask_b32_e64 v69, v69, v196, s[44:45]
	v_add_f32_e32 v197, v201, v197
	v_cndmask_b32_e64 v68, v68, v197, s[46:47]
	v_max_f32_e32 v70, v137, v137
	v_max_f32_e32 v71, v185, v185
	v_max_f32_e32 v70, v71, v70
	v_max_f32_e32 v71, v72, v72
	v_max_f32_e32 v75, v186, v186
	v_max_f32_e32 v71, v75, v71
	v_max_f32_e32 v75, v68, v68
	v_max_f32_e32 v161, v69, v69
	v_max_f32_e32 v75, v161, v75
	v_max3_f32 v75, v74, v73, v75
	v_cmp_lt_i32_e32 vcc, v210, v208
	v_max3_f32 v70, v70, v71, v75
	s_nop 0
	v_cndmask_b32_e32 v71, v207, v210, vcc
	v_lshlrev_b32_e32 v71, 2, v71
	ds_bpermute_b32 v71, v71, v70
	v_cmp_lt_i32_e32 vcc, v209, v208
	s_waitcnt lgkmcnt(0)
	v_max_f32_e32 v71, v71, v71
	v_max_f32_e32 v70, v70, v71
	v_cndmask_b32_e32 v71, v207, v209, vcc
	v_lshlrev_b32_e32 v71, 2, v71
	ds_bpermute_b32 v71, v71, v70
	s_waitcnt lgkmcnt(0)
	v_max3_f32 v161, v178, v70, v71
	v_sub_f32_e32 v71, v185, v161
	v_exp_f32_e32 v71, v71
	v_sub_f32_e32 v137, v137, v161
	v_exp_f32_e32 v185, v137
	v_sub_f32_e32 v137, v186, v161
	v_exp_f32_e32 v186, v137
	v_sub_f32_e32 v72, v72, v161
	v_exp_f32_e32 v72, v72
	v_sub_f32_e32 v74, v74, v161
	v_add_f32_e32 v75, 0, v71
	v_exp_f32_e32 v74, v74
	v_sub_f32_e32 v73, v73, v161
	v_add_f32_e32 v75, v185, v75
	v_exp_f32_e32 v73, v73
	v_sub_f32_e32 v69, v69, v161
	v_add_f32_e32 v75, v186, v75
	v_exp_f32_e32 v187, v69
	v_add_f32_e32 v75, v72, v75
	v_add_f32_e32 v75, v74, v75
	v_add_f32_e32 v75, v73, v75
	v_sub_f32_e32 v68, v68, v161
	v_sub_f32_e32 v70, v178, v161
	v_add_f32_e32 v69, v187, v75
	v_exp_f32_e32 v75, v68
	v_exp_f32_e32 v178, v70
	v_cvt_pk_bf16_f32 v68, v71, v185
	v_cvt_pk_bf16_f32 v70, v74, v73
	v_add_f32_e32 v137, v75, v69
	v_fmac_f32_e32 v137, v2, v178
	v_cvt_pk_bf16_f32 v69, v186, v72
	v_cvt_pk_bf16_f32 v71, v187, v75
	v_pk_mul_f32 v[22:23], v[22:23], v[178:179] op_sel_hi:[1,0]
	v_pk_mul_f32 v[20:21], v[20:21], v[178:179] op_sel_hi:[1,0]
	v_pk_mul_f32 v[26:27], v[26:27], v[178:179] op_sel_hi:[1,0]
	v_pk_mul_f32 v[24:25], v[24:25], v[178:179] op_sel_hi:[1,0]
	s_waitcnt lgkmcnt(0)
	v_mfma_f32_16x16x32_bf16 v[20:23], v[226:229], v[68:71], v[20:23]
	v_pk_mul_f32 v[34:35], v[34:35], v[178:179] op_sel_hi:[1,0]
	v_pk_mul_f32 v[32:33], v[32:33], v[178:179] op_sel_hi:[1,0]
	v_mfma_f32_16x16x32_bf16 v[24:27], v[230:233], v[68:71], v[24:27]
	v_pk_mul_f32 v[46:47], v[46:47], v[178:179] op_sel_hi:[1,0]
	v_pk_mul_f32 v[44:45], v[44:45], v[178:179] op_sel_hi:[1,0]
	v_mfma_f32_16x16x32_bf16 v[32:35], v[234:237], v[68:71], v[32:35]
	v_mov_b32_e32 v178, v161
	v_mov_b32_e32 v2, v137
	v_mfma_f32_16x16x32_bf16 v[44:47], v[242:245], v[68:71], v[44:47]
.LBB0_303:
	v_cmp_ge_u32_e32 vcc, s79, v126
	v_cmp_lt_u32_e64 s[0:1], s79, v127
	s_and_b64 s[82:83], s[52:53], vcc
	s_and_b64 s[0:1], s[82:83], s[0:1]
	s_andn2_b64 vcc, exec, s[0:1]
	s_cbranch_vccnz .LBB0_248
	ds_read_b128 v[68:71], v183
	ds_read_b128 v[72:75], v184
	ds_read_b128 v[198:201], v181
	ds_read_b128 v[182:185], v182
	v_add_u32_e32 v190, s77, v135
	ds_read_b32 v190, v190
	v_add_u32_e32 v191, s77, v134
	ds_read_b32 v191, v191
	v_add_u32_e32 v192, s77, v133
	ds_read_b32 v192, v192
	v_add_u32_e32 v193, s77, v132
	ds_read_b32 v193, v193
	v_add_u32_e32 v194, s77, v131
	ds_read_b32 v194, v194
	v_add_u32_e32 v195, s77, v130
	ds_read_b32 v195, v195
	v_add_u32_e32 v196, s77, v129
	ds_read_b32 v196, v196
	v_add_u32_e32 v197, s77, v128
	ds_read_b32 v197, v197
	v_add3_u32 v246, s80, v118, v119
	v_mov_b32_e32 v136, 0xf149f2ca
	v_mov_b32_e32 v181, 0xf149f2ca
	s_waitcnt lgkmcnt(10)
	v_mfma_f32_16x16x32_bf16 v[68:71], v[68:71], v[12:15], 0
	s_waitcnt lgkmcnt(8)
	v_mfma_f32_16x16x32_bf16 v[198:201], v[198:201], v[12:15], 0
	v_mfma_f32_16x16x32_bf16 v[72:75], v[72:75], v[16:19], v[68:71]
	v_mfma_f32_16x16x32_bf16 v[198:201], v[182:185], v[16:19], v[198:201]
	ds_read_b128 v[226:229], v246 offset:8192
	ds_read_b128 v[230:233], v246 offset:10240
	ds_read_b128 v[234:237], v246 offset:12288
	ds_read_b128 v[242:245], v246 offset:14336
	s_waitcnt lgkmcnt(4)
	s_nop 1
	v_add_f32_e32 v190, v72, v190
	v_cndmask_b32_e64 v181, v181, v190, s[22:23]
	v_add_f32_e32 v191, v73, v191
	v_cndmask_b32_e64 v136, v136, v191, s[38:39]
	v_mov_b32_e32 v72, 0xf149f2ca
	v_mov_b32_e32 v182, 0xf149f2ca
	v_add_f32_e32 v192, v74, v192
	v_cndmask_b32_e64 v182, v182, v192, s[48:49]
	v_add_f32_e32 v193, v75, v193
	v_cndmask_b32_e64 v72, v72, v193, s[58:59]
	v_mov_b32_e32 v73, 0xf149f2ca
	v_mov_b32_e32 v74, 0xf149f2ca
	v_add_f32_e32 v194, v198, v194
	v_cndmask_b32_e64 v74, v74, v194, s[96:97]
	v_add_f32_e32 v195, v199, v195
	v_cndmask_b32_e64 v73, v73, v195, s[42:43]
	v_mov_b32_e32 v68, 0xf149f2ca
	v_mov_b32_e32 v69, 0xf149f2ca
	v_add_f32_e32 v196, v200, v196
	v_cndmask_b32_e64 v69, v69, v196, s[44:45]
	v_add_f32_e32 v197, v201, v197
	v_cndmask_b32_e64 v68, v68, v197, s[46:47]
	s_branch .LBB0_247

.LBB0_354:
	s_and_b64 vcc, exec, s[0:1]
	s_cbranch_vccnz .LBB0_482
	v_ashrrev_i32_e32 v0, 31, v10
	v_lshrrev_b32_e32 v0, 26, v0
	v_add_u32_e32 v0, v10, v0
	v_ashrrev_i32_e32 v11, 6, v0
	v_bfe_i32 v0, v10, 27, 1
	v_lshlrev_b32_e32 v2, 4, v10
	v_lshrrev_b32_e32 v0, 22, v0
	v_add_u32_e32 v0, v2, v0
	v_and_b32_e32 v0, 0xfffffc00, v0
	v_sub_u32_e32 v0, v2, v0
	v_lshrrev_b32_e32 v3, 4, v0
	v_bitop3_b32 v3, v3, v0, 32 bitop3:0x6c
	v_ashrrev_i32_e32 v0, 31, v0
	v_lshrrev_b32_e32 v0, 26, v0
	v_add_u32_e32 v0, v3, v0
	v_ashrrev_i32_e32 v12, 6, v0
	v_mul_i32_i24_e32 v5, 64, v12
	v_sub_u32_e32 v3, v3, v5
	v_lshlrev_b32_e32 v4, 3, v11
	v_lshlrev_b32_e32 v0, 5, v11
	v_ashrrev_i16_sdwa v3, v206, sext(v3) dst_sel:DWORD dst_unused:UNUSED_PAD src0_sel:DWORD src1_sel:BYTE_0
	v_and_b32_e32 v4, 0x1ffff0, v4
	v_and_b32_e32 v0, 32, v0
	v_bfe_i32 v13, v3, 0, 16
	v_add_u32_e32 v0, v0, v13
	v_add_lshl_u32 v3, v12, v4, 11
	v_add_u32_e32 v2, 0x2000, v2
	v_lshl_add_u32 v0, v0, 1, v3
	v_ashrrev_i32_e32 v3, 31, v2
	v_lshrrev_b32_e32 v3, 22, v3
	s_mul_i32 s1, s62, 0x1880000
	v_add_u32_e32 v3, v2, v3
	s_mul_hi_i32 s0, s62, 0x1880000
	s_add_u32 s23, s46, s1
	v_ashrrev_i32_e32 v14, 10, v3
	s_addc_u32 s34, s47, s0
	s_ashr_i32 s2, s22, 6
	v_mul_i32_i24_e32 v3, 0x400, v14
	s_lshl_b32 s0, s42, 8
	v_sub_u32_e32 v2, v2, v3
	s_ashr_i32 s3, s22, 8
	s_lshl_b32 s35, s2, 10
	s_or_b32 s0, s0, 1
	v_lshrrev_b32_e32 v3, 4, v2
	s_cmp_lt_i32 s42, 64
	v_bitop3_b32 v2, v3, v2, 32 bitop3:0x6c
	s_cselect_b32 s0, s0, 0x4003
	v_ashrrev_i32_e32 v4, 31, v2
	s_ashr_i32 s1, s0, 31
	v_lshrrev_b32_e32 v4, 26, v4
	s_lshl_b64 s[0:1], s[0:1], 11
	v_readlane_b32 s12, v252, 20
	v_add_u32_e32 v4, v2, v4
	v_readlane_b32 s13, v252, 21
	s_add_u32 s0, s12, s0
	v_ashrrev_i32_e32 v15, 6, v4
	v_and_b32_e32 v4, 0xc0, v4
	s_addc_u32 s1, s13, s1
	s_ashr_i32 s15, s14, 31
	v_sub_u32_e32 v2, v2, v4
	s_lshl_b64 s[16:17], s[14:15], 19
	v_lshlrev_b32_e32 v3, 3, v14
	v_lshlrev_b32_e32 v5, 5, v14
	v_ashrrev_i16_sdwa v2, v206, sext(v2) dst_sel:DWORD dst_unused:UNUSED_PAD src0_sel:DWORD src1_sel:BYTE_0
	s_add_u32 s16, s23, s16
	v_and_b32_e32 v3, 0x1ffff0, v3
	v_and_b32_e32 v5, 32, v5
	v_bfe_i32 v16, v2, 0, 16
	s_addc_u32 s17, s34, s17
	s_add_i32 s54, s35, 0
	v_add_u32_e32 v2, v5, v16
	v_add_lshl_u32 v3, v15, v3, 11
	s_add_i32 m0, s54, 0x10000
	v_lshl_add_u32 v154, v2, 1, v3
	v_lshrrev_b32_e32 v5, 7, v202
	v_and_b32_e32 v4, 60, v202
	v_bfe_u32 v6, v202, 2, 4
	v_or_b32_e32 v4, v4, v5
	v_lshl_or_b32 v5, v5, 4, v6
	v_sub_u32_e32 v4, v4, v5
	v_lshlrev_b32_e32 v4, 11, v4
	v_add_u32_e32 v250, v0, v4
	v_add_u32_e32 v251, v154, v4
	global_load_lds_dwordx4 v0, s[16:17]
	s_add_i32 m0, s54, 0x12000
	s_add_i32 s55, s54, 0x2000
	global_load_lds_dwordx4 v154, s[16:17]
	s_mov_b32 m0, s54
	s_add_u32 s18, s16, 0x40000
	global_load_lds_dwordx4 v250, s[0:1]
	s_mov_b32 m0, s55
	s_addc_u32 s19, s17, 0
	global_load_lds_dwordx4 v251, s[0:1]
	s_add_i32 m0, s54, 0x14000
	v_writelane_b32 v255, s50, 17
	global_load_lds_dwordx4 v0, s[18:19]
	s_add_i32 m0, s54, 0x16000
	v_mov_b32_e32 v155, v1
	global_load_lds_dwordx4 v154, s[18:19]
	s_add_u32 s18, s0, 0x40000
	s_addc_u32 s19, s1, 0
	s_add_i32 s58, s54, 0x4000
	s_mov_b32 m0, s58
	s_add_i32 s59, s54, 0x6000
	global_load_lds_dwordx4 v250, s[18:19]
	s_mov_b32 m0, s59
	v_writelane_b32 v255, s51, 18
	global_load_lds_dwordx4 v251, s[18:19]
	v_lshl_add_u64 v[8:9], s[16:17], 0, v[0:1]
	v_lshl_add_u64 v[6:7], s[16:17], 0, v[154:155]
	v_lshl_add_u64 v[4:5], s[0:1], 0, v[0:1]
	s_cmp_lg_u32 s3, 1
	v_lshl_add_u64 v[2:3], s[0:1], 0, v[154:155]
	s_cbranch_scc1 .LBB0_357
	s_barrier
.LBB0_357:
	s_and_b32 s2, s2, 3
	s_add_i32 m0, s54, 0x18000
	v_lshl_add_u64 v[8:9], v[8:9], 0, s[20:21]
	s_lshl_b32 s92, s3, 6
	s_lshl_b32 s12, s3, 13
	s_lshl_b32 s93, s2, 5
	s_lshl_b32 s13, s2, 12
	s_waitcnt vmcnt(4)
	s_barrier
	global_load_lds_dwordx4 v[8:9], off
	v_lshl_add_u64 v[6:7], v[6:7], 0, s[20:21]
	s_add_i32 m0, s54, 0x1a000
	s_add_i32 s96, s54, 0x8000
	s_add_i32 s97, s54, 0xa000
	global_load_lds_dwordx4 v[6:7], off
	s_nop 0
	s_add_i32 m0, s96, 0xffffff80
	s_add_u32 s2, s16, 0x40080
	global_load_lds_dwordx4 v250, s[0:1] offset:128
	s_nop 0
	s_add_i32 m0, s97, 0xffffff80
	s_addc_u32 s3, s17, 0
	global_load_lds_dwordx4 v251, s[0:1] offset:128
	s_add_i32 m0, s54, 0x1c000
	v_lshl_add_u64 v[2:3], s[2:3], 0, v[0:1]
	global_load_lds_dwordx4 v[2:3], off
	v_lshl_add_u64 v[2:3], s[2:3], 0, v[154:155]
	s_add_i32 m0, s54, 0x1e000
	v_and_b32_e32 v226, 15, v10
	global_load_lds_dwordx4 v[2:3], off
	v_bfe_u32 v3, v10, 4, 2
	v_lshlrev_b32_e32 v2, 4, v3
	v_lshlrev_b32_e32 v5, 2, v10
	v_lshl_or_b32 v4, v226, 6, v2
	v_and_b32_e32 v5, 32, v5
	v_readlane_b32 s2, v252, 28
	v_bitop3_b32 v6, v4, s12, v5 bitop3:0xde
	v_bitop3_b32 v227, v4, s13, v5 bitop3:0xde
	v_lshlrev_b32_e32 v4, 3, v3
	v_mov_b32_e32 v5, v1
	v_readlane_b32 s3, v252, 29
	v_lshlrev_b32_e32 v228, 2, v3
	v_mov_b32_e32 v3, v1
	v_lshl_add_u64 v[156:157], s[2:3], 0, v[4:5]
	v_readlane_b32 s2, v252, 49
	v_readlane_b32 s3, v252, 50
	v_lshl_add_u64 v[158:159], s[44:45], 0, v[2:3]
	s_waitcnt vmcnt(6)
	s_bitcmp0_b32 s22, 6
	v_lshl_add_u64 v[160:161], s[2:3], 0, v[2:3]
	v_lshlrev_b32_e32 v2, 14, v11
	v_and_b32_e32 v2, 0xffff8000, v2
	v_lshl_add_u32 v2, v12, 11, v2
	v_and_b32_e32 v3, 1, v11
	v_lshl_or_b32 v2, v3, 6, v2
	v_lshl_add_u32 v162, v13, 1, v2
	v_lshlrev_b32_e32 v2, 14, v14
	v_and_b32_e32 v2, 0xffff8000, v2
	v_lshl_add_u32 v2, v15, 11, v2
	v_and_b32_e32 v3, 1, v14
	v_lshl_or_b32 v2, v3, 6, v2
	v_readlane_b32 s82, v252, 51
	s_mov_b32 s90, 0
	s_cselect_b64 s[38:39], -1, 0
	v_or_b32_e32 v229, 0xfffff900, v228
	v_or_b32_e32 v230, 16, v226
	v_or_b32_e32 v231, 32, v226
	v_or_b32_e32 v232, 48, v226
	s_mul_i32 s81, s62, 6
	v_mov_b32_e32 v163, v1
	v_lshl_add_u32 v164, v16, 1, v2
	v_lshrrev_b32_e32 v131, 7, v202
	v_and_b32_e32 v130, 60, v202
	v_bfe_u32 v132, v202, 2, 4
	v_or_b32_e32 v130, v130, v131
	v_lshl_or_b32 v131, v131, 4, v132
	v_sub_u32_e32 v130, v130, v131
	v_lshlrev_b32_e32 v130, 11, v130
	v_add_u32_e32 v162, v162, v130
	v_add_u32_e32 v164, v164, v130
	v_mov_b32_e32 v165, v1
	v_add_u32_e32 v233, 0, v6
	v_readlane_b32 s83, v252, 52
	s_mov_b32 s77, 0x8200
	s_mov_b32 s80, 0x10000
	s_mov_b32 s84, 0x8000
	s_mov_b32 s85, 0x82000
	s_movk_i32 s86, 0xf780
	s_movk_i32 s87, 0xfa80
	s_movk_i32 s88, 0x7f
	s_movk_i32 s89, 0x3f80
	s_movk_i32 s91, 0x3f70
	s_barrier
	s_branch .LBB0_359

.LBB0_365:
	v_mov_b64_e32 v[2:3], 0x30c
	v_cmp_lt_i64_e32 vcc, s[2:3], v[2:3]
	s_lshl_b32 s2, s18, 8
	s_or_b32 s2, s2, 1
	s_cmp_lt_i32 s18, 64
	s_cselect_b32 s2, s2, 0x4003
	s_ashr_i32 s3, s2, 31
	s_lshl_b64 s[2:3], s[2:3], 11
	v_readlane_b32 s12, v252, 20
	v_readlane_b32 s13, v252, 21
	s_add_u32 s52, s12, s2
	s_addc_u32 s53, s13, s3
	s_and_b64 s[2:3], vcc, exec
	s_cselect_b32 s15, s53, s1
	s_cselect_b32 s19, s52, s0
	s_ashr_i32 s51, s50, 31
	s_lshl_b64 s[2:3], s[50:51], 19
	s_add_u32 s48, s23, s2
	s_addc_u32 s49, s34, s3
	s_and_b64 s[2:3], vcc, exec
	s_cselect_b32 s43, s49, s17
	s_cselect_b32 s44, s48, s16
	s_add_u32 s0, s0, 0x40080
	s_addc_u32 s1, s1, 0
	s_add_u32 s45, s16, 0x100
	v_mov_b32_e32 v2, 0
	s_addc_u32 s46, s17, 0
	s_mov_b32 s47, -2
	v_mov_b32_e32 v3, v2
	v_mov_b32_e32 v4, v2
	v_mov_b32_e32 v5, v2
	v_mov_b32_e32 v6, v2
	v_mov_b32_e32 v7, v2
	v_mov_b32_e32 v8, v2
	v_mov_b32_e32 v9, v2
	v_mov_b32_e32 v10, v2
	v_mov_b32_e32 v11, v2
	v_mov_b32_e32 v12, v2
	v_mov_b32_e32 v13, v2
	v_mov_b32_e32 v14, v2
	v_mov_b32_e32 v15, v2
	v_mov_b32_e32 v16, v2
	v_mov_b32_e32 v17, v2
	v_mov_b32_e32 v18, v2
	v_mov_b32_e32 v19, v2
	v_mov_b32_e32 v20, v2
	v_mov_b32_e32 v21, v2
	v_mov_b32_e32 v22, v2
	v_mov_b32_e32 v23, v2
	v_mov_b32_e32 v24, v2
	v_mov_b32_e32 v25, v2
	v_mov_b32_e32 v26, v2
	v_mov_b32_e32 v27, v2
	v_mov_b32_e32 v28, v2
	v_mov_b32_e32 v29, v2
	v_mov_b32_e32 v30, v2
	v_mov_b32_e32 v31, v2
	v_mov_b32_e32 v32, v2
	v_mov_b32_e32 v33, v2
	v_mov_b32_e32 v66, v2
	v_mov_b32_e32 v67, v2
	v_mov_b32_e32 v68, v2
	v_mov_b32_e32 v69, v2
	v_mov_b32_e32 v70, v2
	v_mov_b32_e32 v71, v2
	v_mov_b32_e32 v72, v2
	v_mov_b32_e32 v73, v2
	v_mov_b32_e32 v74, v2
	v_mov_b32_e32 v75, v2
	v_mov_b32_e32 v76, v2
	v_mov_b32_e32 v77, v2
	v_mov_b32_e32 v78, v2
	v_mov_b32_e32 v79, v2
	v_mov_b32_e32 v80, v2
	v_mov_b32_e32 v81, v2
	v_mov_b32_e32 v82, v2
	v_mov_b32_e32 v83, v2
	v_mov_b32_e32 v84, v2
	v_mov_b32_e32 v85, v2
	v_mov_b32_e32 v86, v2
	v_mov_b32_e32 v87, v2
	v_mov_b32_e32 v88, v2
	v_mov_b32_e32 v89, v2
	v_mov_b32_e32 v90, v2
	v_mov_b32_e32 v91, v2
	v_mov_b32_e32 v92, v2
	v_mov_b32_e32 v93, v2
	v_mov_b32_e32 v94, v2
	v_mov_b32_e32 v95, v2
	v_mov_b32_e32 v96, v2
	v_mov_b32_e32 v97, v2
	v_mov_b32_e32 v34, v2
	v_mov_b32_e32 v35, v2
	v_mov_b32_e32 v36, v2
	v_mov_b32_e32 v37, v2
	v_mov_b32_e32 v38, v2
	v_mov_b32_e32 v39, v2
	v_mov_b32_e32 v40, v2
	v_mov_b32_e32 v41, v2
	v_mov_b32_e32 v42, v2
	v_mov_b32_e32 v43, v2
	v_mov_b32_e32 v44, v2
	v_mov_b32_e32 v45, v2
	v_mov_b32_e32 v46, v2
	v_mov_b32_e32 v47, v2
	v_mov_b32_e32 v48, v2
	v_mov_b32_e32 v49, v2
	v_mov_b32_e32 v50, v2
	v_mov_b32_e32 v51, v2
	v_mov_b32_e32 v52, v2
	v_mov_b32_e32 v53, v2
	v_mov_b32_e32 v54, v2
	v_mov_b32_e32 v55, v2
	v_mov_b32_e32 v56, v2
	v_mov_b32_e32 v57, v2
	v_mov_b32_e32 v58, v2
	v_mov_b32_e32 v59, v2
	v_mov_b32_e32 v60, v2
	v_mov_b32_e32 v61, v2
	v_mov_b32_e32 v62, v2
	v_mov_b32_e32 v63, v2
	v_mov_b32_e32 v64, v2
	v_mov_b32_e32 v65, v2
	v_mov_b32_e32 v98, v2
	v_mov_b32_e32 v99, v2
	v_mov_b32_e32 v100, v2
	v_mov_b32_e32 v101, v2
	v_mov_b32_e32 v102, v2
	v_mov_b32_e32 v103, v2
	v_mov_b32_e32 v104, v2
	v_mov_b32_e32 v105, v2
	v_mov_b32_e32 v106, v2
	v_mov_b32_e32 v107, v2
	v_mov_b32_e32 v108, v2
	v_mov_b32_e32 v109, v2
	v_mov_b32_e32 v110, v2
	v_mov_b32_e32 v111, v2
	v_mov_b32_e32 v112, v2
	v_mov_b32_e32 v113, v2
	v_mov_b32_e32 v114, v2
	v_mov_b32_e32 v115, v2
	v_mov_b32_e32 v116, v2
	v_mov_b32_e32 v117, v2
	v_mov_b32_e32 v118, v2
	v_mov_b32_e32 v119, v2
	v_mov_b32_e32 v120, v2
	v_mov_b32_e32 v121, v2
	v_mov_b32_e32 v122, v2
	v_mov_b32_e32 v123, v2
	v_mov_b32_e32 v124, v2
	v_mov_b32_e32 v125, v2
	v_mov_b32_e32 v126, v2
	v_mov_b32_e32 v127, v2
	v_mov_b32_e32 v128, v2
	v_mov_b32_e32 v129, v2
.LBB0_366:
	s_add_u32 s2, s0, 0xfffc0080
	s_addc_u32 s3, s1, -1
	s_add_i32 s12, 0, 0x10000
	v_add_u32_e32 v142, s12, v227
	ds_read_b128 v[130:133], v142
	ds_read_b128 v[134:137], v142 offset:1024
	ds_read_b128 v[138:141], v142 offset:2048
	ds_read_b128 v[142:145], v142 offset:3072
	s_cmp_eq_u32 s47, 12
	s_cselect_b32 s17, s15, s3
	s_cselect_b32 s16, s19, s2
	s_cselect_b32 s3, s43, s46
	s_cselect_b32 s2, s44, s45
	v_lshl_add_u64 v[190:191], s[0:1], 0, v[162:163]
	s_add_i32 m0, s54, 0xc000
	ds_read_b128 v[146:149], v233
	ds_read_b128 v[150:153], v233 offset:1024
	ds_read_b128 v[166:169], v233 offset:2048
	ds_read_b128 v[170:173], v233 offset:3072
	ds_read_b128 v[174:177], v233 offset:4096
	ds_read_b128 v[178:181], v233 offset:5120
	ds_read_b128 v[182:185], v233 offset:6144
	ds_read_b128 v[186:189], v233 offset:7168
	global_load_lds_dwordx4 v[190:191], off
	v_lshl_add_u64 v[190:191], s[0:1], 0, v[164:165]
	s_add_i32 m0, s54, 0xe000
	s_nop 0
	global_load_lds_dwordx4 v[190:191], off
	s_waitcnt lgkmcnt(8)
	s_barrier
	s_waitcnt lgkmcnt(0)
	s_setprio 1
	s_waitcnt lgkmcnt(0)
	v_mfma_f32_16x16x32_bf16 v[126:129], v[130:133], v[146:149], v[126:129]
	v_mfma_f32_16x16x32_bf16 v[122:125], v[138:141], v[146:149], v[122:125]
	v_mfma_f32_16x16x32_bf16 v[118:121], v[130:133], v[166:169], v[118:121]
	v_mfma_f32_16x16x32_bf16 v[114:117], v[138:141], v[166:169], v[114:117]
	v_mfma_f32_16x16x32_bf16 v[110:113], v[130:133], v[174:177], v[110:113]
	v_mfma_f32_16x16x32_bf16 v[106:109], v[138:141], v[174:177], v[106:109]
	v_mfma_f32_16x16x32_bf16 v[102:105], v[130:133], v[182:185], v[102:105]
	v_mfma_f32_16x16x32_bf16 v[98:101], v[138:141], v[182:185], v[98:101]
	v_mfma_f32_16x16x32_bf16 v[126:129], v[134:137], v[150:153], v[126:129]
	v_mfma_f32_16x16x32_bf16 v[122:125], v[142:145], v[150:153], v[122:125]
	v_mfma_f32_16x16x32_bf16 v[118:121], v[134:137], v[170:173], v[118:121]
	v_mfma_f32_16x16x32_bf16 v[114:117], v[142:145], v[170:173], v[114:117]
	v_mfma_f32_16x16x32_bf16 v[110:113], v[134:137], v[178:181], v[110:113]
	v_mfma_f32_16x16x32_bf16 v[106:109], v[142:145], v[178:181], v[106:109]
	v_mfma_f32_16x16x32_bf16 v[102:105], v[134:137], v[186:189], v[102:105]
	v_mfma_f32_16x16x32_bf16 v[98:101], v[142:145], v[186:189], v[98:101]
	s_setprio 0
	s_barrier
	s_add_i32 s13, 0, 0x14000
	s_add_i32 s12, s12, s35
	v_add_u32_e32 v234, s13, v227
	v_lshl_add_u64 v[242:243], s[2:3], 0, v[0:1]
	s_mov_b32 m0, s12
	ds_read_b128 v[190:193], v234
	ds_read_b128 v[194:197], v234 offset:1024
	ds_read_b128 v[198:201], v234 offset:2048
	ds_read_b128 v[234:237], v234 offset:3072
	global_load_lds_dwordx4 v[242:243], off
	v_lshl_add_u64 v[244:245], s[2:3], 0, v[154:155]
	s_add_i32 m0, s12, 0x2000
	s_nop 0
	global_load_lds_dwordx4 v[244:245], off
	s_barrier
	s_waitcnt lgkmcnt(0)
	s_setprio 1
	s_waitcnt lgkmcnt(0)
	v_mfma_f32_16x16x32_bf16 v[62:65], v[190:193], v[146:149], v[62:65]
	v_mfma_f32_16x16x32_bf16 v[58:61], v[198:201], v[146:149], v[58:61]
	v_mfma_f32_16x16x32_bf16 v[54:57], v[190:193], v[166:169], v[54:57]
	v_mfma_f32_16x16x32_bf16 v[50:53], v[198:201], v[166:169], v[50:53]
	v_mfma_f32_16x16x32_bf16 v[46:49], v[190:193], v[174:177], v[46:49]
	v_mfma_f32_16x16x32_bf16 v[42:45], v[198:201], v[174:177], v[42:45]
	v_mfma_f32_16x16x32_bf16 v[38:41], v[190:193], v[182:185], v[38:41]
	v_mfma_f32_16x16x32_bf16 v[34:37], v[198:201], v[182:185], v[34:37]
	v_mfma_f32_16x16x32_bf16 v[62:65], v[194:197], v[150:153], v[62:65]
	v_mfma_f32_16x16x32_bf16 v[58:61], v[234:237], v[150:153], v[58:61]
	v_mfma_f32_16x16x32_bf16 v[54:57], v[194:197], v[170:173], v[54:57]
	v_mfma_f32_16x16x32_bf16 v[50:53], v[234:237], v[170:173], v[50:53]
	v_mfma_f32_16x16x32_bf16 v[46:49], v[194:197], v[178:181], v[46:49]
	v_mfma_f32_16x16x32_bf16 v[42:45], v[234:237], v[178:181], v[42:45]
	v_mfma_f32_16x16x32_bf16 v[38:41], v[194:197], v[186:189], v[38:41]
	v_mfma_f32_16x16x32_bf16 v[34:37], v[234:237], v[186:189], v[34:37]
	s_setprio 0
	s_mov_b32 m0, s54
	s_nop 0
	s_barrier
	ds_read_b128 v[146:149], v233 offset:16384
	ds_read_b128 v[150:153], v233 offset:17408
	ds_read_b128 v[166:169], v233 offset:18432
	ds_read_b128 v[170:173], v233 offset:19456
	ds_read_b128 v[174:177], v233 offset:20480
	ds_read_b128 v[178:181], v233 offset:21504
	ds_read_b128 v[182:185], v233 offset:22528
	ds_read_b128 v[186:189], v233 offset:23552
	global_load_lds_dwordx4 v250, s[16:17]
	s_nop 0
	s_mov_b32 m0, s55
	s_nop 0
	global_load_lds_dwordx4 v251, s[16:17]
	s_barrier
	s_waitcnt lgkmcnt(0)
	s_setprio 1
	s_waitcnt lgkmcnt(0)
	v_mfma_f32_16x16x32_bf16 v[94:97], v[130:133], v[146:149], v[94:97]
	v_mfma_f32_16x16x32_bf16 v[90:93], v[138:141], v[146:149], v[90:93]
	v_mfma_f32_16x16x32_bf16 v[86:89], v[130:133], v[166:169], v[86:89]
	v_mfma_f32_16x16x32_bf16 v[82:85], v[138:141], v[166:169], v[82:85]
	v_mfma_f32_16x16x32_bf16 v[78:81], v[130:133], v[174:177], v[78:81]
	v_mfma_f32_16x16x32_bf16 v[74:77], v[138:141], v[174:177], v[74:77]
	v_mfma_f32_16x16x32_bf16 v[70:73], v[130:133], v[182:185], v[70:73]
	v_mfma_f32_16x16x32_bf16 v[66:69], v[138:141], v[182:185], v[66:69]
	v_mfma_f32_16x16x32_bf16 v[94:97], v[134:137], v[150:153], v[94:97]
	v_mfma_f32_16x16x32_bf16 v[90:93], v[142:145], v[150:153], v[90:93]
	v_mfma_f32_16x16x32_bf16 v[86:89], v[134:137], v[170:173], v[86:89]
	v_mfma_f32_16x16x32_bf16 v[82:85], v[142:145], v[170:173], v[82:85]
	v_mfma_f32_16x16x32_bf16 v[78:81], v[134:137], v[178:181], v[78:81]
	v_mfma_f32_16x16x32_bf16 v[74:77], v[142:145], v[178:181], v[74:77]
	v_mfma_f32_16x16x32_bf16 v[70:73], v[134:137], v[186:189], v[70:73]
	v_mfma_f32_16x16x32_bf16 v[66:69], v[142:145], v[186:189], v[66:69]
	s_setprio 0
	s_barrier
	s_add_u32 s78, s2, 0x40000
	s_addc_u32 s79, s3, 0
	s_add_i32 s12, s13, s35
	v_lshl_add_u64 v[130:131], s[78:79], 0, v[0:1]
	s_mov_b32 m0, s12
	s_nop 0
	global_load_lds_dwordx4 v[130:131], off
	v_lshl_add_u64 v[130:131], s[78:79], 0, v[154:155]
	s_add_i32 m0, s12, 0x2000
	s_nop 0
	global_load_lds_dwordx4 v[130:131], off
	s_waitcnt vmcnt(6)
	s_barrier
	s_setprio 1
	v_mfma_f32_16x16x32_bf16 v[30:33], v[190:193], v[146:149], v[30:33]
	v_mfma_f32_16x16x32_bf16 v[26:29], v[198:201], v[146:149], v[26:29]
	v_mfma_f32_16x16x32_bf16 v[22:25], v[190:193], v[166:169], v[22:25]
	v_mfma_f32_16x16x32_bf16 v[18:21], v[198:201], v[166:169], v[18:21]
	v_mfma_f32_16x16x32_bf16 v[14:17], v[190:193], v[174:177], v[14:17]
	v_mfma_f32_16x16x32_bf16 v[10:13], v[198:201], v[174:177], v[10:13]
	v_mfma_f32_16x16x32_bf16 v[6:9], v[190:193], v[182:185], v[6:9]
	v_mfma_f32_16x16x32_bf16 v[2:5], v[198:201], v[182:185], v[2:5]
	v_mfma_f32_16x16x32_bf16 v[30:33], v[194:197], v[150:153], v[30:33]
	v_mfma_f32_16x16x32_bf16 v[26:29], v[234:237], v[150:153], v[26:29]
	v_mfma_f32_16x16x32_bf16 v[22:25], v[194:197], v[170:173], v[22:25]
	v_mfma_f32_16x16x32_bf16 v[18:21], v[234:237], v[170:173], v[18:21]
	v_mfma_f32_16x16x32_bf16 v[14:17], v[194:197], v[178:181], v[14:17]
	v_mfma_f32_16x16x32_bf16 v[10:13], v[234:237], v[178:181], v[10:13]
	v_mfma_f32_16x16x32_bf16 v[6:9], v[194:197], v[186:189], v[6:9]
	v_mfma_f32_16x16x32_bf16 v[2:5], v[234:237], v[186:189], v[2:5]
	s_setprio 0
	s_add_i32 s12, 0, 0x18000
	v_add_u32_e32 v142, s12, v227
	s_barrier
	ds_read_b128 v[130:133], v142
	ds_read_b128 v[134:137], v142 offset:1024
	ds_read_b128 v[138:141], v142 offset:2048
	ds_read_b128 v[142:145], v142 offset:3072
	s_add_u32 s16, s16, 0x40000
	s_addc_u32 s17, s17, 0
	s_mov_b32 m0, s58
	s_nop 0
	ds_read_b128 v[146:149], v233 offset:32768
	ds_read_b128 v[150:153], v233 offset:33792
	ds_read_b128 v[166:169], v233 offset:34816
	ds_read_b128 v[170:173], v233 offset:35840
	ds_read_b128 v[174:177], v233 offset:36864
	ds_read_b128 v[178:181], v233 offset:37888
	ds_read_b128 v[182:185], v233 offset:38912
	ds_read_b128 v[186:189], v233 offset:39936
	global_load_lds_dwordx4 v250, s[16:17]
	s_nop 0
	s_mov_b32 m0, s59
	s_nop 0
	global_load_lds_dwordx4 v251, s[16:17]
	s_waitcnt lgkmcnt(8)
	s_barrier
	s_waitcnt lgkmcnt(0)
	s_setprio 1
	s_waitcnt lgkmcnt(0)
	v_mfma_f32_16x16x32_bf16 v[126:129], v[130:133], v[146:149], v[126:129]
	v_mfma_f32_16x16x32_bf16 v[122:125], v[138:141], v[146:149], v[122:125]
	v_mfma_f32_16x16x32_bf16 v[118:121], v[130:133], v[166:169], v[118:121]
	v_mfma_f32_16x16x32_bf16 v[114:117], v[138:141], v[166:169], v[114:117]
	v_mfma_f32_16x16x32_bf16 v[110:113], v[130:133], v[174:177], v[110:113]
	v_mfma_f32_16x16x32_bf16 v[106:109], v[138:141], v[174:177], v[106:109]
	v_mfma_f32_16x16x32_bf16 v[102:105], v[130:133], v[182:185], v[102:105]
	v_mfma_f32_16x16x32_bf16 v[98:101], v[138:141], v[182:185], v[98:101]
	v_mfma_f32_16x16x32_bf16 v[126:129], v[134:137], v[150:153], v[126:129]
	v_mfma_f32_16x16x32_bf16 v[122:125], v[142:145], v[150:153], v[122:125]
	v_mfma_f32_16x16x32_bf16 v[118:121], v[134:137], v[170:173], v[118:121]
	v_mfma_f32_16x16x32_bf16 v[114:117], v[142:145], v[170:173], v[114:117]
	v_mfma_f32_16x16x32_bf16 v[110:113], v[134:137], v[178:181], v[110:113]
	v_mfma_f32_16x16x32_bf16 v[106:109], v[142:145], v[178:181], v[106:109]
	v_mfma_f32_16x16x32_bf16 v[102:105], v[134:137], v[186:189], v[102:105]
	v_mfma_f32_16x16x32_bf16 v[98:101], v[142:145], v[186:189], v[98:101]
	s_setprio 0
	s_barrier
	s_add_i32 s13, 0, 0x1c000
	s_add_i32 s12, s12, s35
	v_add_u32_e32 v234, s13, v227
	v_lshl_add_u64 v[242:243], v[242:243], 0, s[20:21]
	s_mov_b32 m0, s12
	ds_read_b128 v[190:193], v234
	ds_read_b128 v[194:197], v234 offset:1024
	ds_read_b128 v[198:201], v234 offset:2048
	ds_read_b128 v[234:237], v234 offset:3072
	global_load_lds_dwordx4 v[242:243], off
	v_lshl_add_u64 v[242:243], v[244:245], 0, s[20:21]
	s_add_i32 m0, s12, 0x2000
	s_nop 0
	global_load_lds_dwordx4 v[242:243], off
	s_barrier
	s_waitcnt lgkmcnt(0)
	s_setprio 1
	s_waitcnt lgkmcnt(0)
	v_mfma_f32_16x16x32_bf16 v[62:65], v[190:193], v[146:149], v[62:65]
	v_mfma_f32_16x16x32_bf16 v[58:61], v[198:201], v[146:149], v[58:61]
	v_mfma_f32_16x16x32_bf16 v[54:57], v[190:193], v[166:169], v[54:57]
	v_mfma_f32_16x16x32_bf16 v[50:53], v[198:201], v[166:169], v[50:53]
	v_mfma_f32_16x16x32_bf16 v[46:49], v[190:193], v[174:177], v[46:49]
	v_mfma_f32_16x16x32_bf16 v[42:45], v[198:201], v[174:177], v[42:45]
	v_mfma_f32_16x16x32_bf16 v[38:41], v[190:193], v[182:185], v[38:41]
	v_mfma_f32_16x16x32_bf16 v[34:37], v[198:201], v[182:185], v[34:37]
	v_mfma_f32_16x16x32_bf16 v[62:65], v[194:197], v[150:153], v[62:65]
	v_mfma_f32_16x16x32_bf16 v[58:61], v[234:237], v[150:153], v[58:61]
	v_mfma_f32_16x16x32_bf16 v[54:57], v[194:197], v[170:173], v[54:57]
	v_mfma_f32_16x16x32_bf16 v[50:53], v[234:237], v[170:173], v[50:53]
	v_mfma_f32_16x16x32_bf16 v[46:49], v[194:197], v[178:181], v[46:49]
	v_mfma_f32_16x16x32_bf16 v[42:45], v[234:237], v[178:181], v[42:45]
	v_mfma_f32_16x16x32_bf16 v[38:41], v[194:197], v[186:189], v[38:41]
	v_mfma_f32_16x16x32_bf16 v[34:37], v[234:237], v[186:189], v[34:37]
	s_setprio 0
	s_mov_b32 m0, s96
	s_add_u32 s78, s16, 0xfffc0080
	s_addc_u32 s79, s17, -1
	s_barrier
	ds_read_b128 v[146:149], v233 offset:49152
	ds_read_b128 v[150:153], v233 offset:50176
	ds_read_b128 v[166:169], v233 offset:51200
	ds_read_b128 v[170:173], v233 offset:52224
	ds_read_b128 v[174:177], v233 offset:53248
	ds_read_b128 v[178:181], v233 offset:54272
	ds_read_b128 v[182:185], v233 offset:55296
	ds_read_b128 v[186:189], v233 offset:56320
	global_load_lds_dwordx4 v250, s[78:79]
	s_nop 0
	s_mov_b32 m0, s97
	s_nop 0
	global_load_lds_dwordx4 v251, s[78:79]
	s_barrier
	s_waitcnt lgkmcnt(0)
	s_setprio 1
	s_waitcnt lgkmcnt(0)
	v_mfma_f32_16x16x32_bf16 v[94:97], v[130:133], v[146:149], v[94:97]
	v_mfma_f32_16x16x32_bf16 v[90:93], v[138:141], v[146:149], v[90:93]
	v_mfma_f32_16x16x32_bf16 v[86:89], v[130:133], v[166:169], v[86:89]
	v_mfma_f32_16x16x32_bf16 v[82:85], v[138:141], v[166:169], v[82:85]
	v_mfma_f32_16x16x32_bf16 v[78:81], v[130:133], v[174:177], v[78:81]
	v_mfma_f32_16x16x32_bf16 v[74:77], v[138:141], v[174:177], v[74:77]
	v_mfma_f32_16x16x32_bf16 v[70:73], v[130:133], v[182:185], v[70:73]
	v_mfma_f32_16x16x32_bf16 v[66:69], v[138:141], v[182:185], v[66:69]
	v_mfma_f32_16x16x32_bf16 v[94:97], v[134:137], v[150:153], v[94:97]
	v_mfma_f32_16x16x32_bf16 v[90:93], v[142:145], v[150:153], v[90:93]
	v_mfma_f32_16x16x32_bf16 v[86:89], v[134:137], v[170:173], v[86:89]
	v_mfma_f32_16x16x32_bf16 v[82:85], v[142:145], v[170:173], v[82:85]
	v_mfma_f32_16x16x32_bf16 v[78:81], v[134:137], v[178:181], v[78:81]
	v_mfma_f32_16x16x32_bf16 v[74:77], v[142:145], v[178:181], v[74:77]
	v_mfma_f32_16x16x32_bf16 v[70:73], v[134:137], v[186:189], v[70:73]
	v_mfma_f32_16x16x32_bf16 v[66:69], v[142:145], v[186:189], v[66:69]
	s_setprio 0
	s_barrier
	s_add_u32 s2, s2, 0x40080
	s_addc_u32 s3, s3, 0
	s_add_i32 s12, s13, s35
	v_lshl_add_u64 v[130:131], s[2:3], 0, v[0:1]
	s_mov_b32 m0, s12
	s_nop 0
	global_load_lds_dwordx4 v[130:131], off
	v_lshl_add_u64 v[130:131], s[2:3], 0, v[154:155]
	s_add_i32 m0, s12, 0x2000
	s_nop 0
	global_load_lds_dwordx4 v[130:131], off
	s_waitcnt vmcnt(6)
	s_barrier
	s_setprio 1
	v_mfma_f32_16x16x32_bf16 v[30:33], v[190:193], v[146:149], v[30:33]
	v_mfma_f32_16x16x32_bf16 v[26:29], v[198:201], v[146:149], v[26:29]
	v_mfma_f32_16x16x32_bf16 v[22:25], v[190:193], v[166:169], v[22:25]
	v_mfma_f32_16x16x32_bf16 v[18:21], v[198:201], v[166:169], v[18:21]
	v_mfma_f32_16x16x32_bf16 v[14:17], v[190:193], v[174:177], v[14:17]
	v_mfma_f32_16x16x32_bf16 v[10:13], v[198:201], v[174:177], v[10:13]
	v_mfma_f32_16x16x32_bf16 v[6:9], v[190:193], v[182:185], v[6:9]
	v_mfma_f32_16x16x32_bf16 v[2:5], v[198:201], v[182:185], v[2:5]
	v_mfma_f32_16x16x32_bf16 v[30:33], v[194:197], v[150:153], v[30:33]
	v_mfma_f32_16x16x32_bf16 v[26:29], v[234:237], v[150:153], v[26:29]
	v_mfma_f32_16x16x32_bf16 v[22:25], v[194:197], v[170:173], v[22:25]
	v_mfma_f32_16x16x32_bf16 v[18:21], v[234:237], v[170:173], v[18:21]
	v_mfma_f32_16x16x32_bf16 v[14:17], v[194:197], v[178:181], v[14:17]
	v_mfma_f32_16x16x32_bf16 v[10:13], v[234:237], v[178:181], v[10:13]
	v_mfma_f32_16x16x32_bf16 v[6:9], v[194:197], v[186:189], v[6:9]
	v_mfma_f32_16x16x32_bf16 v[2:5], v[234:237], v[186:189], v[2:5]
	s_setprio 0
	s_add_i32 s47, s47, 2
	s_add_u32 s0, s0, 0x100
	s_addc_u32 s1, s1, 0
	s_add_u32 s45, s45, 0x100
	s_addc_u32 s46, s46, 0
	s_cmp_gt_u32 s47, 13
	s_barrier
	s_cbranch_scc0 .LBB0_366
	s_lshl_b32 s2, s42, 8
	s_add_i32 s2, s2, s92
	s_lshl_b32 s3, s14, 8
	s_or_b32 s3, s3, s93
	v_readlane_b32 s44, v255, 8
	v_readlane_b32 s45, v255, 9
	s_add_u32 s60, s8, 0xc404000
	s_addc_u32 s61, s9, 0
	v_lshl_add_u32 v166, v226, 2, s2
	s_cmp_lt_i32 s42, 64
	s_cselect_b32 s47, 1, 0
	v_mul_lo_u32 v167, v166, s57
	s_nop 0
	v_lshl_add_u32 v167, v228, 1, v167
	s_cmpk_gt_i32 s3, 0xb7f
	s_cbranch_scc1 .Lip0_end
	s_lshl_b32 s12, s3, 1
	v_add_u32_e32 v169, s12, v167
	s_add_i32 s0, s3, 0xfffffc00
	s_add_i32 s1, s3, 0xfffff780
	s_min_u32 s12, s0, s1
	s_cmpk_lt_u32 s12, 0x180
	s_cbranch_scc1 .Lip0_V
	s_add_i32 s12, s3, 0xfffffa80
	s_cmpk_lt_u32 s12, 0x300
	s_cbranch_scc1 .Lip0_R
	s_add_i32 s12, s3, 0xffffff00
	s_cmpk_lt_u32 s12, 0x180
	s_cbranch_scc0 .Lip0_nonq
	v_mul_f32_e32 v126, 0x3e38aa3b, v126
	v_mul_f32_e32 v127, 0x3e38aa3b, v127
	v_mul_f32_e32 v128, 0x3e38aa3b, v128
	v_mul_f32_e32 v129, 0x3e38aa3b, v129
	v_mul_f32_e32 v122, 0x3e38aa3b, v122
	v_mul_f32_e32 v123, 0x3e38aa3b, v123
	v_mul_f32_e32 v124, 0x3e38aa3b, v124
	v_mul_f32_e32 v125, 0x3e38aa3b, v125
	v_mul_f32_e32 v118, 0x3e38aa3b, v118
	v_mul_f32_e32 v119, 0x3e38aa3b, v119
	v_mul_f32_e32 v120, 0x3e38aa3b, v120
	v_mul_f32_e32 v121, 0x3e38aa3b, v121
	v_mul_f32_e32 v114, 0x3e38aa3b, v114
	v_mul_f32_e32 v115, 0x3e38aa3b, v115
	v_mul_f32_e32 v116, 0x3e38aa3b, v116
	v_mul_f32_e32 v117, 0x3e38aa3b, v117
	v_mul_f32_e32 v110, 0x3e38aa3b, v110
	v_mul_f32_e32 v111, 0x3e38aa3b, v111
	v_mul_f32_e32 v112, 0x3e38aa3b, v112
	v_mul_f32_e32 v113, 0x3e38aa3b, v113
	v_mul_f32_e32 v106, 0x3e38aa3b, v106
	v_mul_f32_e32 v107, 0x3e38aa3b, v107
	v_mul_f32_e32 v108, 0x3e38aa3b, v108
	v_mul_f32_e32 v109, 0x3e38aa3b, v109
	v_mul_f32_e32 v102, 0x3e38aa3b, v102
	v_mul_f32_e32 v103, 0x3e38aa3b, v103
	v_mul_f32_e32 v104, 0x3e38aa3b, v104
	v_mul_f32_e32 v105, 0x3e38aa3b, v105
	v_mul_f32_e32 v98, 0x3e38aa3b, v98
	v_mul_f32_e32 v99, 0x3e38aa3b, v99
	v_mul_f32_e32 v100, 0x3e38aa3b, v100
	v_mul_f32_e32 v101, 0x3e38aa3b, v101
	v_mul_f32_e32 v94, 0x3e38aa3b, v94
	v_mul_f32_e32 v95, 0x3e38aa3b, v95
	v_mul_f32_e32 v96, 0x3e38aa3b, v96
	v_mul_f32_e32 v97, 0x3e38aa3b, v97
	v_mul_f32_e32 v90, 0x3e38aa3b, v90
	v_mul_f32_e32 v91, 0x3e38aa3b, v91
	v_mul_f32_e32 v92, 0x3e38aa3b, v92
	v_mul_f32_e32 v93, 0x3e38aa3b, v93
	v_mul_f32_e32 v86, 0x3e38aa3b, v86
	v_mul_f32_e32 v87, 0x3e38aa3b, v87
	v_mul_f32_e32 v88, 0x3e38aa3b, v88
	v_mul_f32_e32 v89, 0x3e38aa3b, v89
	v_mul_f32_e32 v82, 0x3e38aa3b, v82
	v_mul_f32_e32 v83, 0x3e38aa3b, v83
	v_mul_f32_e32 v84, 0x3e38aa3b, v84
	v_mul_f32_e32 v85, 0x3e38aa3b, v85
	v_mul_f32_e32 v78, 0x3e38aa3b, v78
	v_mul_f32_e32 v79, 0x3e38aa3b, v79
	v_mul_f32_e32 v80, 0x3e38aa3b, v80
	v_mul_f32_e32 v81, 0x3e38aa3b, v81
	v_mul_f32_e32 v74, 0x3e38aa3b, v74
	v_mul_f32_e32 v75, 0x3e38aa3b, v75
	v_mul_f32_e32 v76, 0x3e38aa3b, v76
	v_mul_f32_e32 v77, 0x3e38aa3b, v77
	v_mul_f32_e32 v70, 0x3e38aa3b, v70
	v_mul_f32_e32 v71, 0x3e38aa3b, v71
	v_mul_f32_e32 v72, 0x3e38aa3b, v72
	v_mul_f32_e32 v73, 0x3e38aa3b, v73
	v_mul_f32_e32 v66, 0x3e38aa3b, v66
	v_mul_f32_e32 v67, 0x3e38aa3b, v67
	v_mul_f32_e32 v68, 0x3e38aa3b, v68
	v_mul_f32_e32 v69, 0x3e38aa3b, v69
.Lip0_nonq:
	s_cmpk_lt_i32 s3, 0xa00
	s_cbranch_scc1 .Lip0_nogate
	v_mul_f32_e32 v130, 0xbfb8aa3b, v126
	v_mul_f32_e32 v131, 0xbfb8aa3b, v127
	v_mul_f32_e32 v132, 0xbfb8aa3b, v128
	v_mul_f32_e32 v133, 0xbfb8aa3b, v129
	v_mul_f32_e32 v134, 0xbfb8aa3b, v122
	v_mul_f32_e32 v135, 0xbfb8aa3b, v123
	v_mul_f32_e32 v136, 0xbfb8aa3b, v124
	v_mul_f32_e32 v137, 0xbfb8aa3b, v125
	v_exp_f32_e32 v130, v130
	v_exp_f32_e32 v131, v131
	v_exp_f32_e32 v132, v132
	v_exp_f32_e32 v133, v133
	v_exp_f32_e32 v134, v134
	v_exp_f32_e32 v135, v135
	v_exp_f32_e32 v136, v136
	v_exp_f32_e32 v137, v137
	v_add_f32_e32 v130, 1.0, v130
	v_add_f32_e32 v131, 1.0, v131
	v_add_f32_e32 v132, 1.0, v132
	v_add_f32_e32 v133, 1.0, v133
	v_add_f32_e32 v134, 1.0, v134
	v_add_f32_e32 v135, 1.0, v135
	v_add_f32_e32 v136, 1.0, v136
	v_add_f32_e32 v137, 1.0, v137
	v_rcp_f32_e32 v130, v130
	v_rcp_f32_e32 v131, v131
	v_rcp_f32_e32 v132, v132
	v_rcp_f32_e32 v133, v133
	v_rcp_f32_e32 v134, v134
	v_rcp_f32_e32 v135, v135
	v_rcp_f32_e32 v136, v136
	v_rcp_f32_e32 v137, v137
	v_mul_f32_e32 v126, v126, v130
	v_mul_f32_e32 v127, v127, v131
	v_mul_f32_e32 v128, v128, v132
	v_mul_f32_e32 v129, v129, v133
	v_mul_f32_e32 v122, v122, v134
	v_mul_f32_e32 v123, v123, v135
	v_mul_f32_e32 v124, v124, v136
	v_mul_f32_e32 v125, v125, v137
	v_mul_f32_e32 v130, 0xbfb8aa3b, v118
	v_mul_f32_e32 v131, 0xbfb8aa3b, v119
	v_mul_f32_e32 v132, 0xbfb8aa3b, v120
	v_mul_f32_e32 v133, 0xbfb8aa3b, v121
	v_mul_f32_e32 v134, 0xbfb8aa3b, v114
	v_mul_f32_e32 v135, 0xbfb8aa3b, v115
	v_mul_f32_e32 v136, 0xbfb8aa3b, v116
	v_mul_f32_e32 v137, 0xbfb8aa3b, v117
	v_exp_f32_e32 v130, v130
	v_exp_f32_e32 v131, v131
	v_exp_f32_e32 v132, v132
	v_exp_f32_e32 v133, v133
	v_exp_f32_e32 v134, v134
	v_exp_f32_e32 v135, v135
	v_exp_f32_e32 v136, v136
	v_exp_f32_e32 v137, v137
	v_add_f32_e32 v130, 1.0, v130
	v_add_f32_e32 v131, 1.0, v131
	v_add_f32_e32 v132, 1.0, v132
	v_add_f32_e32 v133, 1.0, v133
	v_add_f32_e32 v134, 1.0, v134
	v_add_f32_e32 v135, 1.0, v135
	v_add_f32_e32 v136, 1.0, v136
	v_add_f32_e32 v137, 1.0, v137
	v_rcp_f32_e32 v130, v130
	v_rcp_f32_e32 v131, v131
	v_rcp_f32_e32 v132, v132
	v_rcp_f32_e32 v133, v133
	v_rcp_f32_e32 v134, v134
	v_rcp_f32_e32 v135, v135
	v_rcp_f32_e32 v136, v136
	v_rcp_f32_e32 v137, v137
	v_mul_f32_e32 v118, v118, v130
	v_mul_f32_e32 v119, v119, v131
	v_mul_f32_e32 v120, v120, v132
	v_mul_f32_e32 v121, v121, v133
	v_mul_f32_e32 v114, v114, v134
	v_mul_f32_e32 v115, v115, v135
	v_mul_f32_e32 v116, v116, v136
	v_mul_f32_e32 v117, v117, v137
	v_mul_f32_e32 v130, 0xbfb8aa3b, v110
	v_mul_f32_e32 v131, 0xbfb8aa3b, v111
	v_mul_f32_e32 v132, 0xbfb8aa3b, v112
	v_mul_f32_e32 v133, 0xbfb8aa3b, v113
	v_mul_f32_e32 v134, 0xbfb8aa3b, v106
	v_mul_f32_e32 v135, 0xbfb8aa3b, v107
	v_mul_f32_e32 v136, 0xbfb8aa3b, v108
	v_mul_f32_e32 v137, 0xbfb8aa3b, v109
	v_exp_f32_e32 v130, v130
	v_exp_f32_e32 v131, v131
	v_exp_f32_e32 v132, v132
	v_exp_f32_e32 v133, v133
	v_exp_f32_e32 v134, v134
	v_exp_f32_e32 v135, v135
	v_exp_f32_e32 v136, v136
	v_exp_f32_e32 v137, v137
	v_add_f32_e32 v130, 1.0, v130
	v_add_f32_e32 v131, 1.0, v131
	v_add_f32_e32 v132, 1.0, v132
	v_add_f32_e32 v133, 1.0, v133
	v_add_f32_e32 v134, 1.0, v134
	v_add_f32_e32 v135, 1.0, v135
	v_add_f32_e32 v136, 1.0, v136
	v_add_f32_e32 v137, 1.0, v137
	v_rcp_f32_e32 v130, v130
	v_rcp_f32_e32 v131, v131
	v_rcp_f32_e32 v132, v132
	v_rcp_f32_e32 v133, v133
	v_rcp_f32_e32 v134, v134
	v_rcp_f32_e32 v135, v135
	v_rcp_f32_e32 v136, v136
	v_rcp_f32_e32 v137, v137
	v_mul_f32_e32 v110, v110, v130
	v_mul_f32_e32 v111, v111, v131
	v_mul_f32_e32 v112, v112, v132
	v_mul_f32_e32 v113, v113, v133
	v_mul_f32_e32 v106, v106, v134
	v_mul_f32_e32 v107, v107, v135
	v_mul_f32_e32 v108, v108, v136
	v_mul_f32_e32 v109, v109, v137
	v_mul_f32_e32 v130, 0xbfb8aa3b, v102
	v_mul_f32_e32 v131, 0xbfb8aa3b, v103
	v_mul_f32_e32 v132, 0xbfb8aa3b, v104
	v_mul_f32_e32 v133, 0xbfb8aa3b, v105
	v_mul_f32_e32 v134, 0xbfb8aa3b, v98
	v_mul_f32_e32 v135, 0xbfb8aa3b, v99
	v_mul_f32_e32 v136, 0xbfb8aa3b, v100
	v_mul_f32_e32 v137, 0xbfb8aa3b, v101
	v_exp_f32_e32 v130, v130
	v_exp_f32_e32 v131, v131
	v_exp_f32_e32 v132, v132
	v_exp_f32_e32 v133, v133
	v_exp_f32_e32 v134, v134
	v_exp_f32_e32 v135, v135
	v_exp_f32_e32 v136, v136
	v_exp_f32_e32 v137, v137
	v_add_f32_e32 v130, 1.0, v130
	v_add_f32_e32 v131, 1.0, v131
	v_add_f32_e32 v132, 1.0, v132
	v_add_f32_e32 v133, 1.0, v133
	v_add_f32_e32 v134, 1.0, v134
	v_add_f32_e32 v135, 1.0, v135
	v_add_f32_e32 v136, 1.0, v136
	v_add_f32_e32 v137, 1.0, v137
	v_rcp_f32_e32 v130, v130
	v_rcp_f32_e32 v131, v131
	v_rcp_f32_e32 v132, v132
	v_rcp_f32_e32 v133, v133
	v_rcp_f32_e32 v134, v134
	v_rcp_f32_e32 v135, v135
	v_rcp_f32_e32 v136, v136
	v_rcp_f32_e32 v137, v137
	v_mul_f32_e32 v102, v102, v130
	v_mul_f32_e32 v103, v103, v131
	v_mul_f32_e32 v104, v104, v132
	v_mul_f32_e32 v105, v105, v133
	v_mul_f32_e32 v98, v98, v134
	v_mul_f32_e32 v99, v99, v135
	v_mul_f32_e32 v100, v100, v136
	v_mul_f32_e32 v101, v101, v137
	v_mul_f32_e32 v130, 0xbfb8aa3b, v94
	v_mul_f32_e32 v131, 0xbfb8aa3b, v95
	v_mul_f32_e32 v132, 0xbfb8aa3b, v96
	v_mul_f32_e32 v133, 0xbfb8aa3b, v97
	v_mul_f32_e32 v134, 0xbfb8aa3b, v90
	v_mul_f32_e32 v135, 0xbfb8aa3b, v91
	v_mul_f32_e32 v136, 0xbfb8aa3b, v92
	v_mul_f32_e32 v137, 0xbfb8aa3b, v93
	v_exp_f32_e32 v130, v130
	v_exp_f32_e32 v131, v131
	v_exp_f32_e32 v132, v132
	v_exp_f32_e32 v133, v133
	v_exp_f32_e32 v134, v134
	v_exp_f32_e32 v135, v135
	v_exp_f32_e32 v136, v136
	v_exp_f32_e32 v137, v137
	v_add_f32_e32 v130, 1.0, v130
	v_add_f32_e32 v131, 1.0, v131
	v_add_f32_e32 v132, 1.0, v132
	v_add_f32_e32 v133, 1.0, v133
	v_add_f32_e32 v134, 1.0, v134
	v_add_f32_e32 v135, 1.0, v135
	v_add_f32_e32 v136, 1.0, v136
	v_add_f32_e32 v137, 1.0, v137
	v_rcp_f32_e32 v130, v130
	v_rcp_f32_e32 v131, v131
	v_rcp_f32_e32 v132, v132
	v_rcp_f32_e32 v133, v133
	v_rcp_f32_e32 v134, v134
	v_rcp_f32_e32 v135, v135
	v_rcp_f32_e32 v136, v136
	v_rcp_f32_e32 v137, v137
	v_mul_f32_e32 v94, v94, v130
	v_mul_f32_e32 v95, v95, v131
	v_mul_f32_e32 v96, v96, v132
	v_mul_f32_e32 v97, v97, v133
	v_mul_f32_e32 v90, v90, v134
	v_mul_f32_e32 v91, v91, v135
	v_mul_f32_e32 v92, v92, v136
	v_mul_f32_e32 v93, v93, v137
	v_mul_f32_e32 v130, 0xbfb8aa3b, v86
	v_mul_f32_e32 v131, 0xbfb8aa3b, v87
	v_mul_f32_e32 v132, 0xbfb8aa3b, v88
	v_mul_f32_e32 v133, 0xbfb8aa3b, v89
	v_mul_f32_e32 v134, 0xbfb8aa3b, v82
	v_mul_f32_e32 v135, 0xbfb8aa3b, v83
	v_mul_f32_e32 v136, 0xbfb8aa3b, v84
	v_mul_f32_e32 v137, 0xbfb8aa3b, v85
	v_exp_f32_e32 v130, v130
	v_exp_f32_e32 v131, v131
	v_exp_f32_e32 v132, v132
	v_exp_f32_e32 v133, v133
	v_exp_f32_e32 v134, v134
	v_exp_f32_e32 v135, v135
	v_exp_f32_e32 v136, v136
	v_exp_f32_e32 v137, v137
	v_add_f32_e32 v130, 1.0, v130
	v_add_f32_e32 v131, 1.0, v131
	v_add_f32_e32 v132, 1.0, v132
	v_add_f32_e32 v133, 1.0, v133
	v_add_f32_e32 v134, 1.0, v134
	v_add_f32_e32 v135, 1.0, v135
	v_add_f32_e32 v136, 1.0, v136
	v_add_f32_e32 v137, 1.0, v137
	v_rcp_f32_e32 v130, v130
	v_rcp_f32_e32 v131, v131
	v_rcp_f32_e32 v132, v132
	v_rcp_f32_e32 v133, v133
	v_rcp_f32_e32 v134, v134
	v_rcp_f32_e32 v135, v135
	v_rcp_f32_e32 v136, v136
	v_rcp_f32_e32 v137, v137
	v_mul_f32_e32 v86, v86, v130
	v_mul_f32_e32 v87, v87, v131
	v_mul_f32_e32 v88, v88, v132
	v_mul_f32_e32 v89, v89, v133
	v_mul_f32_e32 v82, v82, v134
	v_mul_f32_e32 v83, v83, v135
	v_mul_f32_e32 v84, v84, v136
	v_mul_f32_e32 v85, v85, v137
	v_mul_f32_e32 v130, 0xbfb8aa3b, v78
	v_mul_f32_e32 v131, 0xbfb8aa3b, v79
	v_mul_f32_e32 v132, 0xbfb8aa3b, v80
	v_mul_f32_e32 v133, 0xbfb8aa3b, v81
	v_mul_f32_e32 v134, 0xbfb8aa3b, v74
	v_mul_f32_e32 v135, 0xbfb8aa3b, v75
	v_mul_f32_e32 v136, 0xbfb8aa3b, v76
	v_mul_f32_e32 v137, 0xbfb8aa3b, v77
	v_exp_f32_e32 v130, v130
	v_exp_f32_e32 v131, v131
	v_exp_f32_e32 v132, v132
	v_exp_f32_e32 v133, v133
	v_exp_f32_e32 v134, v134
	v_exp_f32_e32 v135, v135
	v_exp_f32_e32 v136, v136
	v_exp_f32_e32 v137, v137
	v_add_f32_e32 v130, 1.0, v130
	v_add_f32_e32 v131, 1.0, v131
	v_add_f32_e32 v132, 1.0, v132
	v_add_f32_e32 v133, 1.0, v133
	v_add_f32_e32 v134, 1.0, v134
	v_add_f32_e32 v135, 1.0, v135
	v_add_f32_e32 v136, 1.0, v136
	v_add_f32_e32 v137, 1.0, v137
	v_rcp_f32_e32 v130, v130
	v_rcp_f32_e32 v131, v131
	v_rcp_f32_e32 v132, v132
	v_rcp_f32_e32 v133, v133
	v_rcp_f32_e32 v134, v134
	v_rcp_f32_e32 v135, v135
	v_rcp_f32_e32 v136, v136
	v_rcp_f32_e32 v137, v137
	v_mul_f32_e32 v78, v78, v130
	v_mul_f32_e32 v79, v79, v131
	v_mul_f32_e32 v80, v80, v132
	v_mul_f32_e32 v81, v81, v133
	v_mul_f32_e32 v74, v74, v134
	v_mul_f32_e32 v75, v75, v135
	v_mul_f32_e32 v76, v76, v136
	v_mul_f32_e32 v77, v77, v137
	v_mul_f32_e32 v130, 0xbfb8aa3b, v70
	v_mul_f32_e32 v131, 0xbfb8aa3b, v71
	v_mul_f32_e32 v132, 0xbfb8aa3b, v72
	v_mul_f32_e32 v133, 0xbfb8aa3b, v73
	v_mul_f32_e32 v134, 0xbfb8aa3b, v66
	v_mul_f32_e32 v135, 0xbfb8aa3b, v67
	v_mul_f32_e32 v136, 0xbfb8aa3b, v68
	v_mul_f32_e32 v137, 0xbfb8aa3b, v69
	v_exp_f32_e32 v130, v130
	v_exp_f32_e32 v131, v131
	v_exp_f32_e32 v132, v132
	v_exp_f32_e32 v133, v133
	v_exp_f32_e32 v134, v134
	v_exp_f32_e32 v135, v135
	v_exp_f32_e32 v136, v136
	v_exp_f32_e32 v137, v137
	v_add_f32_e32 v130, 1.0, v130
	v_add_f32_e32 v131, 1.0, v131
	v_add_f32_e32 v132, 1.0, v132
	v_add_f32_e32 v133, 1.0, v133
	v_add_f32_e32 v134, 1.0, v134
	v_add_f32_e32 v135, 1.0, v135
	v_add_f32_e32 v136, 1.0, v136
	v_add_f32_e32 v137, 1.0, v137
	v_rcp_f32_e32 v130, v130
	v_rcp_f32_e32 v131, v131
	v_rcp_f32_e32 v132, v132
	v_rcp_f32_e32 v133, v133
	v_rcp_f32_e32 v134, v134
	v_rcp_f32_e32 v135, v135
	v_rcp_f32_e32 v136, v136
	v_rcp_f32_e32 v137, v137
	v_mul_f32_e32 v70, v70, v130
	v_mul_f32_e32 v71, v71, v131
	v_mul_f32_e32 v72, v72, v132
	v_mul_f32_e32 v73, v73, v133
	v_mul_f32_e32 v66, v66, v134
	v_mul_f32_e32 v67, v67, v135
	v_mul_f32_e32 v68, v68, v136
	v_mul_f32_e32 v69, v69, v137
.Lip0_nogate:
	v_cvt_pk_bf16_f32 v138, v126, v127
	v_cvt_pk_bf16_f32 v139, v128, v129
	global_store_dwordx2 v169, v[138:139], s[60:61]
	v_cvt_pk_bf16_f32 v140, v122, v123
	v_cvt_pk_bf16_f32 v141, v124, v125
	global_store_dwordx2 v169, v[140:141], s[60:61] offset:32
	v_add_u32_e32 v170, 0x1700, v169
	v_cvt_pk_bf16_f32 v142, v118, v119
	v_cvt_pk_bf16_f32 v143, v120, v121
	global_store_dwordx2 v170, v[142:143], s[60:61]
	v_cvt_pk_bf16_f32 v144, v114, v115
	v_cvt_pk_bf16_f32 v145, v116, v117
	global_store_dwordx2 v170, v[144:145], s[60:61] offset:32
	v_add_u32_e32 v171, 0x2e00, v169
	v_cvt_pk_bf16_f32 v146, v110, v111
	v_cvt_pk_bf16_f32 v147, v112, v113
	global_store_dwordx2 v171, v[146:147], s[60:61]
	v_cvt_pk_bf16_f32 v148, v106, v107
	v_cvt_pk_bf16_f32 v149, v108, v109
	global_store_dwordx2 v171, v[148:149], s[60:61] offset:32
	v_add_u32_e32 v172, 0x4500, v169
	v_cvt_pk_bf16_f32 v150, v102, v103
	v_cvt_pk_bf16_f32 v151, v104, v105
	global_store_dwordx2 v172, v[150:151], s[60:61]
	v_cvt_pk_bf16_f32 v152, v98, v99
	v_cvt_pk_bf16_f32 v153, v100, v101
	global_store_dwordx2 v172, v[152:153], s[60:61] offset:32
	v_add_u32_e32 v173, 0xb8000, v169
	v_cvt_pk_bf16_f32 v138, v94, v95
	v_cvt_pk_bf16_f32 v139, v96, v97
	global_store_dwordx2 v173, v[138:139], s[60:61]
	v_cvt_pk_bf16_f32 v140, v90, v91
	v_cvt_pk_bf16_f32 v141, v92, v93
	global_store_dwordx2 v173, v[140:141], s[60:61] offset:32
	v_add_u32_e32 v174, 0xb9700, v169
	v_cvt_pk_bf16_f32 v142, v86, v87
	v_cvt_pk_bf16_f32 v143, v88, v89
	global_store_dwordx2 v174, v[142:143], s[60:61]
	v_cvt_pk_bf16_f32 v144, v82, v83
	v_cvt_pk_bf16_f32 v145, v84, v85
	global_store_dwordx2 v174, v[144:145], s[60:61] offset:32
	v_add_u32_e32 v175, 0xbae00, v169
	v_cvt_pk_bf16_f32 v146, v78, v79
	v_cvt_pk_bf16_f32 v147, v80, v81
	global_store_dwordx2 v175, v[146:147], s[60:61]
	v_cvt_pk_bf16_f32 v148, v74, v75
	v_cvt_pk_bf16_f32 v149, v76, v77
	global_store_dwordx2 v175, v[148:149], s[60:61] offset:32
	v_add_u32_e32 v176, 0xbc500, v169
	v_cvt_pk_bf16_f32 v150, v70, v71
	v_cvt_pk_bf16_f32 v151, v72, v73
	global_store_dwordx2 v176, v[150:151], s[60:61]
	v_cvt_pk_bf16_f32 v152, v66, v67
	v_cvt_pk_bf16_f32 v153, v68, v69
	global_store_dwordx2 v176, v[152:153], s[60:61] offset:32
	s_branch .Lip0_end
.Lip0_V:
	s_cmpk_lt_u32 s0, 0x180
	s_cselect_b32 s12, s0, s1
	s_mov_b32 s15, 0x12da4000
	s_cselect_b32 s15, 0x12174000, s15
	s_add_u32 s64, s8, s15
	s_addc_u32 s65, s9, 0
	v_add_u32_e32 v168, s12, v228
	v_mul_u32_u24_e32 v168, 0x8200, v168
	v_lshl_add_u32 v168, v166, 1, v168
	v_cvt_pk_bf16_f32 v138, v126, v118
	v_cvt_pk_bf16_f32 v139, v110, v102
	global_store_dwordx2 v168, v[138:139], s[64:65]
	v_add_u32_e32 v170, 0x8200, v168
	v_cvt_pk_bf16_f32 v140, v127, v119
	v_cvt_pk_bf16_f32 v141, v111, v103
	global_store_dwordx2 v170, v[140:141], s[64:65]
	v_add_u32_e32 v171, 0x10400, v168
	v_cvt_pk_bf16_f32 v142, v128, v120
	v_cvt_pk_bf16_f32 v143, v112, v104
	global_store_dwordx2 v171, v[142:143], s[64:65]
	v_add_u32_e32 v172, 0x18600, v168
	v_cvt_pk_bf16_f32 v144, v129, v121
	v_cvt_pk_bf16_f32 v145, v113, v105
	global_store_dwordx2 v172, v[144:145], s[64:65]
	v_add_u32_e32 v173, 0x82000, v168
	v_cvt_pk_bf16_f32 v146, v122, v114
	v_cvt_pk_bf16_f32 v147, v106, v98
	global_store_dwordx2 v173, v[146:147], s[64:65]
	v_add_u32_e32 v174, 0x8a200, v168
	v_cvt_pk_bf16_f32 v148, v123, v115
	v_cvt_pk_bf16_f32 v149, v107, v99
	global_store_dwordx2 v174, v[148:149], s[64:65]
	v_add_u32_e32 v175, 0x92400, v168
	v_cvt_pk_bf16_f32 v150, v124, v116
	v_cvt_pk_bf16_f32 v151, v108, v100
	global_store_dwordx2 v175, v[150:151], s[64:65]
	v_add_u32_e32 v176, 0x9a600, v168
	v_cvt_pk_bf16_f32 v152, v125, v117
	v_cvt_pk_bf16_f32 v153, v109, v101
	global_store_dwordx2 v176, v[152:153], s[64:65]
	v_cvt_pk_bf16_f32 v138, v94, v86
	v_cvt_pk_bf16_f32 v139, v78, v70
	global_store_dwordx2 v168, v[138:139], s[64:65] offset:256
	v_add_u32_e32 v177, 0x8200, v168
	v_cvt_pk_bf16_f32 v140, v95, v87
	v_cvt_pk_bf16_f32 v141, v79, v71
	global_store_dwordx2 v177, v[140:141], s[64:65] offset:256
	v_add_u32_e32 v170, 0x10400, v168
	v_cvt_pk_bf16_f32 v142, v96, v88
	v_cvt_pk_bf16_f32 v143, v80, v72
	global_store_dwordx2 v170, v[142:143], s[64:65] offset:256
	v_add_u32_e32 v171, 0x18600, v168
	v_cvt_pk_bf16_f32 v144, v97, v89
	v_cvt_pk_bf16_f32 v145, v81, v73
	global_store_dwordx2 v171, v[144:145], s[64:65] offset:256
	v_add_u32_e32 v172, 0x82000, v168
	v_cvt_pk_bf16_f32 v146, v90, v82
	v_cvt_pk_bf16_f32 v147, v74, v66
	global_store_dwordx2 v172, v[146:147], s[64:65] offset:256
	v_add_u32_e32 v173, 0x8a200, v168
	v_cvt_pk_bf16_f32 v148, v91, v83
	v_cvt_pk_bf16_f32 v149, v75, v67
	global_store_dwordx2 v173, v[148:149], s[64:65] offset:256
	v_add_u32_e32 v174, 0x92400, v168
	v_cvt_pk_bf16_f32 v150, v92, v84
	v_cvt_pk_bf16_f32 v151, v76, v68
	global_store_dwordx2 v174, v[150:151], s[64:65] offset:256
	v_add_u32_e32 v175, 0x9a600, v168
	v_cvt_pk_bf16_f32 v152, v93, v85
	v_cvt_pk_bf16_f32 v153, v77, v69
	global_store_dwordx2 v175, v[152:153], s[64:65] offset:256
	s_branch .Lip0_end
.Lip0_R:
	s_cmpk_gt_i32 s3, 0x6ff
	s_cselect_b32 s46, 1, 0
	v_lshlrev_b32_e32 v130, 8, v226
	v_lshl_add_u32 v130, v228, 2, v130
	v_lshl_add_u32 v131, v228, 2, s2
	s_bitcmp1_b32 s3, 5
	s_cselect_b32 s12, 64, 0
	s_cselect_b32 s15, 0, 0x80
	s_cselect_b64 vcc, -1, 0
	s_add_u32 s16, s44, 0x4000
	s_addc_u32 s17, s45, 0
	v_cndmask_b32_e32 v130, v131, v130, vcc
	v_add_u32_e32 v131, s12, v130
	v_add_u32_e32 v132, s12, v131
	v_add_u32_e32 v133, s12, v132
	s_cmp_lg_u32 s47, 0
	s_cbranch_scc0 .Lip0_Rnoload
	global_load_dwordx4 v[170:173], v130, s[44:45]
	global_load_dwordx4 v[186:189], v130, s[16:17]
	global_load_dwordx4 v[174:177], v131, s[44:45]
	global_load_dwordx4 v[190:193], v131, s[16:17]
	global_load_dwordx4 v[178:181], v132, s[44:45]
	global_load_dwordx4 v[194:197], v132, s[16:17]
	global_load_dwordx4 v[182:185], v133, s[44:45]
	global_load_dwordx4 v[198:201], v133, s[16:17]
.Lip0_Rnoload:
	s_cmp_lg_u32 s46, 0
	s_cbranch_scc0 .Lip0_Rnodec
	s_add_i32 s0, s3, 0xfffff900
	s_ashr_i32 s1, s0, 6
	s_add_i32 s1, s1, s81
	s_lshl_b32 s1, s1, 2
	v_readlane_b32 s64, v254, 13
	v_readlane_b32 s65, v254, 14
	v_readlane_b32 s66, v254, 15
	v_readlane_b32 s67, v254, 16
	v_add_u32_e32 v168, s0, v228
	v_mul_u32_u24_e32 v168, 0x8200, v168
	v_lshl_add_u32 v168, v166, 1, v168
	v_lshl_add_u32 v142, v226, 2, s92
	s_nop 0
	s_load_dword s42, s[64:65], s1
	s_load_dword s43, s[66:67], s1
	v_add_u32_e32 v143, 0, v142
	v_sub_u32_e32 v144, 0x7f, v143
	v_cvt_f32_i32_e32 v134, v144
	v_cvt_f32_i32_e32 v138, v143
	v_add_u32_e32 v143, 1, v142
	v_sub_u32_e32 v144, 0x7f, v143
	v_cvt_f32_i32_e32 v135, v144
	v_cvt_f32_i32_e32 v139, v143
	v_add_u32_e32 v143, 2, v142
	v_sub_u32_e32 v144, 0x7f, v143
	v_cvt_f32_i32_e32 v136, v144
	v_cvt_f32_i32_e32 v140, v143
	v_add_u32_e32 v143, 3, v142
	v_sub_u32_e32 v144, 0x7f, v143
	v_cvt_f32_i32_e32 v137, v144
	v_cvt_f32_i32_e32 v141, v143
	s_waitcnt lgkmcnt(0)
	v_mul_f32_e32 v134, s42, v134
	v_mul_f32_e32 v138, s43, v138
	v_mul_f32_e32 v135, s42, v135
	v_mul_f32_e32 v139, s43, v139
	v_mul_f32_e32 v136, s42, v136
	v_mul_f32_e32 v140, s43, v140
	v_mul_f32_e32 v137, s42, v137
	v_mul_f32_e32 v141, s43, v141
	v_mul_f32_e32 v134, 0x3fb8aa3b, v134
	v_mul_f32_e32 v138, 0x3fb8aa3b, v138
	v_mul_f32_e32 v135, 0x3fb8aa3b, v135
	v_mul_f32_e32 v139, 0x3fb8aa3b, v139
	v_mul_f32_e32 v136, 0x3fb8aa3b, v136
	v_mul_f32_e32 v140, 0x3fb8aa3b, v140
	v_mul_f32_e32 v137, 0x3fb8aa3b, v137
	v_mul_f32_e32 v141, 0x3fb8aa3b, v141
	v_exp_f32_e32 v134, v134
	v_exp_f32_e32 v138, v138
	v_exp_f32_e32 v135, v135
	v_exp_f32_e32 v139, v139
	v_exp_f32_e32 v136, v136
	v_exp_f32_e32 v140, v140
	v_exp_f32_e32 v137, v137
	v_exp_f32_e32 v141, v141
.Lip0_Rnodec:
	s_cmp_lg_u32 s47, 0
	s_cbranch_scc0 .Lip0_a0_norot
	s_waitcnt vmcnt(0)
	v_mul_f32_e32 v142, v122, v186
	v_mul_f32_e32 v122, v122, v170
	v_fmac_f32_e32 v122, v126, v186
	v_fma_f32 v126, v126, v170, -v142
	v_mul_f32_e32 v143, v123, v187
	v_mul_f32_e32 v123, v123, v171
	v_fmac_f32_e32 v123, v127, v187
	v_fma_f32 v127, v127, v171, -v143
	v_mul_f32_e32 v144, v124, v188
	v_mul_f32_e32 v124, v124, v172
	v_fmac_f32_e32 v124, v128, v188
	v_fma_f32 v128, v128, v172, -v144
	v_mul_f32_e32 v145, v125, v189
	v_mul_f32_e32 v125, v125, v173
	v_fmac_f32_e32 v125, v129, v189
	v_fma_f32 v129, v129, v173, -v145
	v_mul_f32_e32 v142, v114, v190
	v_mul_f32_e32 v114, v114, v174
	v_fmac_f32_e32 v114, v118, v190
	v_fma_f32 v118, v118, v174, -v142
	v_mul_f32_e32 v143, v115, v191
	v_mul_f32_e32 v115, v115, v175
	v_fmac_f32_e32 v115, v119, v191
	v_fma_f32 v119, v119, v175, -v143
	v_mul_f32_e32 v144, v116, v192
	v_mul_f32_e32 v116, v116, v176
	v_fmac_f32_e32 v116, v120, v192
	v_fma_f32 v120, v120, v176, -v144
	v_mul_f32_e32 v145, v117, v193
	v_mul_f32_e32 v117, v117, v177
	v_fmac_f32_e32 v117, v121, v193
	v_fma_f32 v121, v121, v177, -v145
	v_mul_f32_e32 v142, v106, v194
	v_mul_f32_e32 v106, v106, v178
	v_fmac_f32_e32 v106, v110, v194
	v_fma_f32 v110, v110, v178, -v142
	v_mul_f32_e32 v143, v107, v195
	v_mul_f32_e32 v107, v107, v179
	v_fmac_f32_e32 v107, v111, v195
	v_fma_f32 v111, v111, v179, -v143
	v_mul_f32_e32 v144, v108, v196
	v_mul_f32_e32 v108, v108, v180
	v_fmac_f32_e32 v108, v112, v196
	v_fma_f32 v112, v112, v180, -v144
	v_mul_f32_e32 v145, v109, v197
	v_mul_f32_e32 v109, v109, v181
	v_fmac_f32_e32 v109, v113, v197
	v_fma_f32 v113, v113, v181, -v145
	v_mul_f32_e32 v142, v98, v198
	v_mul_f32_e32 v98, v98, v182
	v_fmac_f32_e32 v98, v102, v198
	v_fma_f32 v102, v102, v182, -v142
	v_mul_f32_e32 v143, v99, v199
	v_mul_f32_e32 v99, v99, v183
	v_fmac_f32_e32 v99, v103, v199
	v_fma_f32 v103, v103, v183, -v143
	v_mul_f32_e32 v144, v100, v200
	v_mul_f32_e32 v100, v100, v184
	v_fmac_f32_e32 v100, v104, v200
	v_fma_f32 v104, v104, v184, -v144
	v_mul_f32_e32 v145, v101, v201
	v_mul_f32_e32 v101, v101, v185
	v_fmac_f32_e32 v101, v105, v201
	v_fma_f32 v105, v105, v185, -v145
	v_add_u32_e32 v130, s15, v130
	v_add_u32_e32 v131, s15, v131
	v_add_u32_e32 v132, s15, v132
	v_add_u32_e32 v133, s15, v133
	global_load_dwordx4 v[170:173], v130, s[44:45]
	global_load_dwordx4 v[186:189], v130, s[16:17]
	global_load_dwordx4 v[174:177], v131, s[44:45]
	global_load_dwordx4 v[190:193], v131, s[16:17]
	global_load_dwordx4 v[178:181], v132, s[44:45]
	global_load_dwordx4 v[194:197], v132, s[16:17]
	global_load_dwordx4 v[182:185], v133, s[44:45]
	global_load_dwordx4 v[198:201], v133, s[16:17]
.Lip0_a0_norot:
	s_cmp_lg_u32 s46, 0
	s_cbranch_scc0 .Lip0_a0_noscale
	v_mul_f32_e32 v126, 0x3e000000, v126
	v_mul_f32_e32 v127, 0x3e000000, v127
	v_mul_f32_e32 v128, 0x3e000000, v128
	v_mul_f32_e32 v129, 0x3e000000, v129
	v_mul_f32_e32 v122, 0x3e000000, v122
	v_mul_f32_e32 v123, 0x3e000000, v123
	v_mul_f32_e32 v124, 0x3e000000, v124
	v_mul_f32_e32 v125, 0x3e000000, v125
	v_mul_f32_e32 v118, 0x3e000000, v118
	v_mul_f32_e32 v119, 0x3e000000, v119
	v_mul_f32_e32 v120, 0x3e000000, v120
	v_mul_f32_e32 v121, 0x3e000000, v121
	v_mul_f32_e32 v114, 0x3e000000, v114
	v_mul_f32_e32 v115, 0x3e000000, v115
	v_mul_f32_e32 v116, 0x3e000000, v116
	v_mul_f32_e32 v117, 0x3e000000, v117
	v_mul_f32_e32 v110, 0x3e000000, v110
	v_mul_f32_e32 v111, 0x3e000000, v111
	v_mul_f32_e32 v112, 0x3e000000, v112
	v_mul_f32_e32 v113, 0x3e000000, v113
	v_mul_f32_e32 v106, 0x3e000000, v106
	v_mul_f32_e32 v107, 0x3e000000, v107
	v_mul_f32_e32 v108, 0x3e000000, v108
	v_mul_f32_e32 v109, 0x3e000000, v109
	v_mul_f32_e32 v102, 0x3e000000, v102
	v_mul_f32_e32 v103, 0x3e000000, v103
	v_mul_f32_e32 v104, 0x3e000000, v104
	v_mul_f32_e32 v105, 0x3e000000, v105
	v_mul_f32_e32 v98, 0x3e000000, v98
	v_mul_f32_e32 v99, 0x3e000000, v99
	v_mul_f32_e32 v100, 0x3e000000, v100
	v_mul_f32_e32 v101, 0x3e000000, v101
.Lip0_a0_noscale:
	v_cvt_pk_bf16_f32 v146, v126, v127
	v_cvt_pk_bf16_f32 v147, v128, v129
	global_store_dwordx2 v169, v[146:147], s[60:61]
	v_cvt_pk_bf16_f32 v148, v122, v123
	v_cvt_pk_bf16_f32 v149, v124, v125
	global_store_dwordx2 v169, v[148:149], s[60:61] offset:32
	v_add_u32_e32 v234, 0x1700, v169
	v_cvt_pk_bf16_f32 v150, v118, v119
	v_cvt_pk_bf16_f32 v151, v120, v121
	global_store_dwordx2 v234, v[150:151], s[60:61]
	v_cvt_pk_bf16_f32 v152, v114, v115
	v_cvt_pk_bf16_f32 v153, v116, v117
	global_store_dwordx2 v234, v[152:153], s[60:61] offset:32
	v_add_u32_e32 v235, 0x2e00, v169
	v_cvt_pk_bf16_f32 v146, v110, v111
	v_cvt_pk_bf16_f32 v147, v112, v113
	global_store_dwordx2 v235, v[146:147], s[60:61]
	v_cvt_pk_bf16_f32 v148, v106, v107
	v_cvt_pk_bf16_f32 v149, v108, v109
	global_store_dwordx2 v235, v[148:149], s[60:61] offset:32
	v_add_u32_e32 v236, 0x4500, v169
	v_cvt_pk_bf16_f32 v150, v102, v103
	v_cvt_pk_bf16_f32 v151, v104, v105
	global_store_dwordx2 v236, v[150:151], s[60:61]
	v_cvt_pk_bf16_f32 v152, v98, v99
	v_cvt_pk_bf16_f32 v153, v100, v101
	global_store_dwordx2 v236, v[152:153], s[60:61] offset:32
	s_cmp_lg_u32 s46, 0
	s_cbranch_scc0 .Lip0_a0_nokt
	v_mul_f32_e32 v142, v126, v134
	v_mul_f32_e32 v143, v118, v135
	v_mul_f32_e32 v144, v110, v136
	v_mul_f32_e32 v145, v102, v137
	v_cvt_pk_bf16_f32 v146, v142, v143
	v_cvt_pk_bf16_f32 v147, v144, v145
	global_store_dwordx2 v168, v[146:147], s[24:25]
	v_add_u32_e32 v237, 0x8200, v168
	v_mul_f32_e32 v142, v127, v134
	v_mul_f32_e32 v143, v119, v135
	v_mul_f32_e32 v144, v111, v136
	v_mul_f32_e32 v145, v103, v137
	v_cvt_pk_bf16_f32 v148, v142, v143
	v_cvt_pk_bf16_f32 v149, v144, v145
	global_store_dwordx2 v237, v[148:149], s[24:25]
	v_add_u32_e32 v242, 0x10400, v168
	v_mul_f32_e32 v142, v128, v134
	v_mul_f32_e32 v143, v120, v135
	v_mul_f32_e32 v144, v112, v136
	v_mul_f32_e32 v145, v104, v137
	v_cvt_pk_bf16_f32 v150, v142, v143
	v_cvt_pk_bf16_f32 v151, v144, v145
	global_store_dwordx2 v242, v[150:151], s[24:25]
	v_add_u32_e32 v243, 0x18600, v168
	v_mul_f32_e32 v142, v129, v134
	v_mul_f32_e32 v143, v121, v135
	v_mul_f32_e32 v144, v113, v136
	v_mul_f32_e32 v145, v105, v137
	v_cvt_pk_bf16_f32 v152, v142, v143
	v_cvt_pk_bf16_f32 v153, v144, v145
	global_store_dwordx2 v243, v[152:153], s[24:25]
	v_add_u32_e32 v244, 0x82000, v168
	v_mul_f32_e32 v142, v122, v134
	v_mul_f32_e32 v143, v114, v135
	v_mul_f32_e32 v144, v106, v136
	v_mul_f32_e32 v145, v98, v137
	v_cvt_pk_bf16_f32 v146, v142, v143
	v_cvt_pk_bf16_f32 v147, v144, v145
	global_store_dwordx2 v244, v[146:147], s[24:25]
	v_add_u32_e32 v245, 0x8a200, v168
	v_mul_f32_e32 v142, v123, v134
	v_mul_f32_e32 v143, v115, v135
	v_mul_f32_e32 v144, v107, v136
	v_mul_f32_e32 v145, v99, v137
	v_cvt_pk_bf16_f32 v148, v142, v143
	v_cvt_pk_bf16_f32 v149, v144, v145
	global_store_dwordx2 v245, v[148:149], s[24:25]
	v_add_u32_e32 v234, 0x92400, v168
	v_mul_f32_e32 v142, v124, v134
	v_mul_f32_e32 v143, v116, v135
	v_mul_f32_e32 v144, v108, v136
	v_mul_f32_e32 v145, v100, v137
	v_cvt_pk_bf16_f32 v150, v142, v143
	v_cvt_pk_bf16_f32 v151, v144, v145
	global_store_dwordx2 v234, v[150:151], s[24:25]
	v_add_u32_e32 v235, 0x9a600, v168
	v_mul_f32_e32 v142, v125, v134
	v_mul_f32_e32 v143, v117, v135
	v_mul_f32_e32 v144, v109, v136
	v_mul_f32_e32 v145, v101, v137
	v_cvt_pk_bf16_f32 v152, v142, v143
	v_cvt_pk_bf16_f32 v153, v144, v145
	global_store_dwordx2 v235, v[152:153], s[24:25]
	v_mul_f32_e32 v142, v126, v138
	v_mul_f32_e32 v143, v118, v139
	v_mul_f32_e32 v144, v110, v140
	v_mul_f32_e32 v145, v102, v141
	v_cvt_pk_bf16_f32 v146, v142, v143
	v_cvt_pk_bf16_f32 v147, v144, v145
	global_store_dwordx2 v168, v[146:147], s[82:83]
	v_add_u32_e32 v236, 0x8200, v168
	v_mul_f32_e32 v142, v127, v138
	v_mul_f32_e32 v143, v119, v139
	v_mul_f32_e32 v144, v111, v140
	v_mul_f32_e32 v145, v103, v141
	v_cvt_pk_bf16_f32 v148, v142, v143
	v_cvt_pk_bf16_f32 v149, v144, v145
	global_store_dwordx2 v236, v[148:149], s[82:83]
	v_add_u32_e32 v237, 0x10400, v168
	v_mul_f32_e32 v142, v128, v138
	v_mul_f32_e32 v143, v120, v139
	v_mul_f32_e32 v144, v112, v140
	v_mul_f32_e32 v145, v104, v141
	v_cvt_pk_bf16_f32 v150, v142, v143
	v_cvt_pk_bf16_f32 v151, v144, v145
	global_store_dwordx2 v237, v[150:151], s[82:83]
	v_add_u32_e32 v242, 0x18600, v168
	v_mul_f32_e32 v142, v129, v138
	v_mul_f32_e32 v143, v121, v139
	v_mul_f32_e32 v144, v113, v140
	v_mul_f32_e32 v145, v105, v141
	v_cvt_pk_bf16_f32 v152, v142, v143
	v_cvt_pk_bf16_f32 v153, v144, v145
	global_store_dwordx2 v242, v[152:153], s[82:83]
	v_add_u32_e32 v243, 0x82000, v168
	v_mul_f32_e32 v142, v122, v138
	v_mul_f32_e32 v143, v114, v139
	v_mul_f32_e32 v144, v106, v140
	v_mul_f32_e32 v145, v98, v141
	v_cvt_pk_bf16_f32 v146, v142, v143
	v_cvt_pk_bf16_f32 v147, v144, v145
	global_store_dwordx2 v243, v[146:147], s[82:83]
	v_add_u32_e32 v244, 0x8a200, v168
	v_mul_f32_e32 v142, v123, v138
	v_mul_f32_e32 v143, v115, v139
	v_mul_f32_e32 v144, v107, v140
	v_mul_f32_e32 v145, v99, v141
	v_cvt_pk_bf16_f32 v148, v142, v143
	v_cvt_pk_bf16_f32 v149, v144, v145
	global_store_dwordx2 v244, v[148:149], s[82:83]
	v_add_u32_e32 v245, 0x92400, v168
	v_mul_f32_e32 v142, v124, v138
	v_mul_f32_e32 v143, v116, v139
	v_mul_f32_e32 v144, v108, v140
	v_mul_f32_e32 v145, v100, v141
	v_cvt_pk_bf16_f32 v150, v142, v143
	v_cvt_pk_bf16_f32 v151, v144, v145
	global_store_dwordx2 v245, v[150:151], s[82:83]
	v_add_u32_e32 v234, 0x9a600, v168
	v_mul_f32_e32 v142, v125, v138
	v_mul_f32_e32 v143, v117, v139
	v_mul_f32_e32 v144, v109, v140
	v_mul_f32_e32 v145, v101, v141
	v_cvt_pk_bf16_f32 v152, v142, v143
	v_cvt_pk_bf16_f32 v153, v144, v145
	global_store_dwordx2 v234, v[152:153], s[82:83]
.Lip0_a0_nokt:
	s_cmp_lg_u32 s47, 0
	s_cbranch_scc0 .Lip0_a1_norot
	s_waitcnt vmcnt(0)
	v_mul_f32_e32 v142, v90, v186
	v_mul_f32_e32 v90, v90, v170
	v_fmac_f32_e32 v90, v94, v186
	v_fma_f32 v94, v94, v170, -v142
	v_mul_f32_e32 v143, v91, v187
	v_mul_f32_e32 v91, v91, v171
	v_fmac_f32_e32 v91, v95, v187
	v_fma_f32 v95, v95, v171, -v143
	v_mul_f32_e32 v144, v92, v188
	v_mul_f32_e32 v92, v92, v172
	v_fmac_f32_e32 v92, v96, v188
	v_fma_f32 v96, v96, v172, -v144
	v_mul_f32_e32 v145, v93, v189
	v_mul_f32_e32 v93, v93, v173
	v_fmac_f32_e32 v93, v97, v189
	v_fma_f32 v97, v97, v173, -v145
	v_mul_f32_e32 v142, v82, v190
	v_mul_f32_e32 v82, v82, v174
	v_fmac_f32_e32 v82, v86, v190
	v_fma_f32 v86, v86, v174, -v142
	v_mul_f32_e32 v143, v83, v191
	v_mul_f32_e32 v83, v83, v175
	v_fmac_f32_e32 v83, v87, v191
	v_fma_f32 v87, v87, v175, -v143
	v_mul_f32_e32 v144, v84, v192
	v_mul_f32_e32 v84, v84, v176
	v_fmac_f32_e32 v84, v88, v192
	v_fma_f32 v88, v88, v176, -v144
	v_mul_f32_e32 v145, v85, v193
	v_mul_f32_e32 v85, v85, v177
	v_fmac_f32_e32 v85, v89, v193
	v_fma_f32 v89, v89, v177, -v145
	v_mul_f32_e32 v142, v74, v194
	v_mul_f32_e32 v74, v74, v178
	v_fmac_f32_e32 v74, v78, v194
	v_fma_f32 v78, v78, v178, -v142
	v_mul_f32_e32 v143, v75, v195
	v_mul_f32_e32 v75, v75, v179
	v_fmac_f32_e32 v75, v79, v195
	v_fma_f32 v79, v79, v179, -v143
	v_mul_f32_e32 v144, v76, v196
	v_mul_f32_e32 v76, v76, v180
	v_fmac_f32_e32 v76, v80, v196
	v_fma_f32 v80, v80, v180, -v144
	v_mul_f32_e32 v145, v77, v197
	v_mul_f32_e32 v77, v77, v181
	v_fmac_f32_e32 v77, v81, v197
	v_fma_f32 v81, v81, v181, -v145
	v_mul_f32_e32 v142, v66, v198
	v_mul_f32_e32 v66, v66, v182
	v_fmac_f32_e32 v66, v70, v198
	v_fma_f32 v70, v70, v182, -v142
	v_mul_f32_e32 v143, v67, v199
	v_mul_f32_e32 v67, v67, v183
	v_fmac_f32_e32 v67, v71, v199
	v_fma_f32 v71, v71, v183, -v143
	v_mul_f32_e32 v144, v68, v200
	v_mul_f32_e32 v68, v68, v184
	v_fmac_f32_e32 v68, v72, v200
	v_fma_f32 v72, v72, v184, -v144
	v_mul_f32_e32 v145, v69, v201
	v_mul_f32_e32 v69, v69, v185
	v_fmac_f32_e32 v69, v73, v201
	v_fma_f32 v73, v73, v185, -v145
.Lip0_a1_norot:
	s_cmp_lg_u32 s46, 0
	s_cbranch_scc0 .Lip0_a1_noscale
	v_mul_f32_e32 v94, 0x3e000000, v94
	v_mul_f32_e32 v95, 0x3e000000, v95
	v_mul_f32_e32 v96, 0x3e000000, v96
	v_mul_f32_e32 v97, 0x3e000000, v97
	v_mul_f32_e32 v90, 0x3e000000, v90
	v_mul_f32_e32 v91, 0x3e000000, v91
	v_mul_f32_e32 v92, 0x3e000000, v92
	v_mul_f32_e32 v93, 0x3e000000, v93
	v_mul_f32_e32 v86, 0x3e000000, v86
	v_mul_f32_e32 v87, 0x3e000000, v87
	v_mul_f32_e32 v88, 0x3e000000, v88
	v_mul_f32_e32 v89, 0x3e000000, v89
	v_mul_f32_e32 v82, 0x3e000000, v82
	v_mul_f32_e32 v83, 0x3e000000, v83
	v_mul_f32_e32 v84, 0x3e000000, v84
	v_mul_f32_e32 v85, 0x3e000000, v85
	v_mul_f32_e32 v78, 0x3e000000, v78
	v_mul_f32_e32 v79, 0x3e000000, v79
	v_mul_f32_e32 v80, 0x3e000000, v80
	v_mul_f32_e32 v81, 0x3e000000, v81
	v_mul_f32_e32 v74, 0x3e000000, v74
	v_mul_f32_e32 v75, 0x3e000000, v75
	v_mul_f32_e32 v76, 0x3e000000, v76
	v_mul_f32_e32 v77, 0x3e000000, v77
	v_mul_f32_e32 v70, 0x3e000000, v70
	v_mul_f32_e32 v71, 0x3e000000, v71
	v_mul_f32_e32 v72, 0x3e000000, v72
	v_mul_f32_e32 v73, 0x3e000000, v73
	v_mul_f32_e32 v66, 0x3e000000, v66
	v_mul_f32_e32 v67, 0x3e000000, v67
	v_mul_f32_e32 v68, 0x3e000000, v68
	v_mul_f32_e32 v69, 0x3e000000, v69
.Lip0_a1_noscale:
	v_add_u32_e32 v234, 0xb8000, v169
	v_cvt_pk_bf16_f32 v146, v94, v95
	v_cvt_pk_bf16_f32 v147, v96, v97
	global_store_dwordx2 v234, v[146:147], s[60:61]
	v_cvt_pk_bf16_f32 v148, v90, v91
	v_cvt_pk_bf16_f32 v149, v92, v93
	global_store_dwordx2 v234, v[148:149], s[60:61] offset:32
	v_add_u32_e32 v235, 0xb9700, v169
	v_cvt_pk_bf16_f32 v150, v86, v87
	v_cvt_pk_bf16_f32 v151, v88, v89
	global_store_dwordx2 v235, v[150:151], s[60:61]
	v_cvt_pk_bf16_f32 v152, v82, v83
	v_cvt_pk_bf16_f32 v153, v84, v85
	global_store_dwordx2 v235, v[152:153], s[60:61] offset:32
	v_add_u32_e32 v236, 0xbae00, v169
	v_cvt_pk_bf16_f32 v146, v78, v79
	v_cvt_pk_bf16_f32 v147, v80, v81
	global_store_dwordx2 v236, v[146:147], s[60:61]
	v_cvt_pk_bf16_f32 v148, v74, v75
	v_cvt_pk_bf16_f32 v149, v76, v77
	global_store_dwordx2 v236, v[148:149], s[60:61] offset:32
	v_add_u32_e32 v237, 0xbc500, v169
	v_cvt_pk_bf16_f32 v150, v70, v71
	v_cvt_pk_bf16_f32 v151, v72, v73
	global_store_dwordx2 v237, v[150:151], s[60:61]
	v_cvt_pk_bf16_f32 v152, v66, v67
	v_cvt_pk_bf16_f32 v153, v68, v69
	global_store_dwordx2 v237, v[152:153], s[60:61] offset:32
	s_cmp_lg_u32 s46, 0
	s_cbranch_scc0 .Lip0_a1_nokt
	v_mul_f32_e32 v142, v94, v134
	v_mul_f32_e32 v143, v86, v135
	v_mul_f32_e32 v144, v78, v136
	v_mul_f32_e32 v145, v70, v137
	v_cvt_pk_bf16_f32 v146, v142, v143
	v_cvt_pk_bf16_f32 v147, v144, v145
	global_store_dwordx2 v168, v[146:147], s[24:25] offset:256
	v_add_u32_e32 v242, 0x8200, v168
	v_mul_f32_e32 v142, v95, v134
	v_mul_f32_e32 v143, v87, v135
	v_mul_f32_e32 v144, v79, v136
	v_mul_f32_e32 v145, v71, v137
	v_cvt_pk_bf16_f32 v148, v142, v143
	v_cvt_pk_bf16_f32 v149, v144, v145
	global_store_dwordx2 v242, v[148:149], s[24:25] offset:256
	v_add_u32_e32 v243, 0x10400, v168
	v_mul_f32_e32 v142, v96, v134
	v_mul_f32_e32 v143, v88, v135
	v_mul_f32_e32 v144, v80, v136
	v_mul_f32_e32 v145, v72, v137
	v_cvt_pk_bf16_f32 v150, v142, v143
	v_cvt_pk_bf16_f32 v151, v144, v145
	global_store_dwordx2 v243, v[150:151], s[24:25] offset:256
	v_add_u32_e32 v244, 0x18600, v168
	v_mul_f32_e32 v142, v97, v134
	v_mul_f32_e32 v143, v89, v135
	v_mul_f32_e32 v144, v81, v136
	v_mul_f32_e32 v145, v73, v137
	v_cvt_pk_bf16_f32 v152, v142, v143
	v_cvt_pk_bf16_f32 v153, v144, v145
	global_store_dwordx2 v244, v[152:153], s[24:25] offset:256
	v_add_u32_e32 v245, 0x82000, v168
	v_mul_f32_e32 v142, v90, v134
	v_mul_f32_e32 v143, v82, v135
	v_mul_f32_e32 v144, v74, v136
	v_mul_f32_e32 v145, v66, v137
	v_cvt_pk_bf16_f32 v146, v142, v143
	v_cvt_pk_bf16_f32 v147, v144, v145
	global_store_dwordx2 v245, v[146:147], s[24:25] offset:256
	v_add_u32_e32 v234, 0x8a200, v168
	v_mul_f32_e32 v142, v91, v134
	v_mul_f32_e32 v143, v83, v135
	v_mul_f32_e32 v144, v75, v136
	v_mul_f32_e32 v145, v67, v137
	v_cvt_pk_bf16_f32 v148, v142, v143
	v_cvt_pk_bf16_f32 v149, v144, v145
	global_store_dwordx2 v234, v[148:149], s[24:25] offset:256
	v_add_u32_e32 v235, 0x92400, v168
	v_mul_f32_e32 v142, v92, v134
	v_mul_f32_e32 v143, v84, v135
	v_mul_f32_e32 v144, v76, v136
	v_mul_f32_e32 v145, v68, v137
	v_cvt_pk_bf16_f32 v150, v142, v143
	v_cvt_pk_bf16_f32 v151, v144, v145
	global_store_dwordx2 v235, v[150:151], s[24:25] offset:256
	v_add_u32_e32 v236, 0x9a600, v168
	v_mul_f32_e32 v142, v93, v134
	v_mul_f32_e32 v143, v85, v135
	v_mul_f32_e32 v144, v77, v136
	v_mul_f32_e32 v145, v69, v137
	v_cvt_pk_bf16_f32 v152, v142, v143
	v_cvt_pk_bf16_f32 v153, v144, v145
	global_store_dwordx2 v236, v[152:153], s[24:25] offset:256
	v_mul_f32_e32 v142, v94, v138
	v_mul_f32_e32 v143, v86, v139
	v_mul_f32_e32 v144, v78, v140
	v_mul_f32_e32 v145, v70, v141
	v_cvt_pk_bf16_f32 v146, v142, v143
	v_cvt_pk_bf16_f32 v147, v144, v145
	global_store_dwordx2 v168, v[146:147], s[82:83] offset:256
	v_add_u32_e32 v237, 0x8200, v168
	v_mul_f32_e32 v142, v95, v138
	v_mul_f32_e32 v143, v87, v139
	v_mul_f32_e32 v144, v79, v140
	v_mul_f32_e32 v145, v71, v141
	v_cvt_pk_bf16_f32 v148, v142, v143
	v_cvt_pk_bf16_f32 v149, v144, v145
	global_store_dwordx2 v237, v[148:149], s[82:83] offset:256
	v_add_u32_e32 v242, 0x10400, v168
	v_mul_f32_e32 v142, v96, v138
	v_mul_f32_e32 v143, v88, v139
	v_mul_f32_e32 v144, v80, v140
	v_mul_f32_e32 v145, v72, v141
	v_cvt_pk_bf16_f32 v150, v142, v143
	v_cvt_pk_bf16_f32 v151, v144, v145
	global_store_dwordx2 v242, v[150:151], s[82:83] offset:256
	v_add_u32_e32 v243, 0x18600, v168
	v_mul_f32_e32 v142, v97, v138
	v_mul_f32_e32 v143, v89, v139
	v_mul_f32_e32 v144, v81, v140
	v_mul_f32_e32 v145, v73, v141
	v_cvt_pk_bf16_f32 v152, v142, v143
	v_cvt_pk_bf16_f32 v153, v144, v145
	global_store_dwordx2 v243, v[152:153], s[82:83] offset:256
	v_add_u32_e32 v244, 0x82000, v168
	v_mul_f32_e32 v142, v90, v138
	v_mul_f32_e32 v143, v82, v139
	v_mul_f32_e32 v144, v74, v140
	v_mul_f32_e32 v145, v66, v141
	v_cvt_pk_bf16_f32 v146, v142, v143
	v_cvt_pk_bf16_f32 v147, v144, v145
	global_store_dwordx2 v244, v[146:147], s[82:83] offset:256
	v_add_u32_e32 v245, 0x8a200, v168
	v_mul_f32_e32 v142, v91, v138
	v_mul_f32_e32 v143, v83, v139
	v_mul_f32_e32 v144, v75, v140
	v_mul_f32_e32 v145, v67, v141
	v_cvt_pk_bf16_f32 v148, v142, v143
	v_cvt_pk_bf16_f32 v149, v144, v145
	global_store_dwordx2 v245, v[148:149], s[82:83] offset:256
	v_add_u32_e32 v234, 0x92400, v168
	v_mul_f32_e32 v142, v92, v138
	v_mul_f32_e32 v143, v84, v139
	v_mul_f32_e32 v144, v76, v140
	v_mul_f32_e32 v145, v68, v141
	v_cvt_pk_bf16_f32 v150, v142, v143
	v_cvt_pk_bf16_f32 v151, v144, v145
	global_store_dwordx2 v234, v[150:151], s[82:83] offset:256
	v_add_u32_e32 v235, 0x9a600, v168
	v_mul_f32_e32 v142, v93, v138
	v_mul_f32_e32 v143, v85, v139
	v_mul_f32_e32 v144, v77, v140
	v_mul_f32_e32 v145, v69, v141
	v_cvt_pk_bf16_f32 v152, v142, v143
	v_cvt_pk_bf16_f32 v153, v144, v145
	global_store_dwordx2 v235, v[152:153], s[82:83] offset:256
.Lip0_a1_nokt:
.Lip0_end:
	s_add_i32 s3, s3, 0x80
	s_cmpk_gt_i32 s3, 0xb7f
	s_cbranch_scc1 .Lip1_end
	s_lshl_b32 s12, s3, 1
	v_add_u32_e32 v169, s12, v167
	s_add_i32 s0, s3, 0xfffffc00
	s_add_i32 s1, s3, 0xfffff780
	s_min_u32 s12, s0, s1
	s_cmpk_lt_u32 s12, 0x180
	s_cbranch_scc1 .Lip1_V
	s_add_i32 s12, s3, 0xfffffa80
	s_cmpk_lt_u32 s12, 0x300
	s_cbranch_scc1 .Lip1_R
	s_add_i32 s12, s3, 0xffffff00
	s_cmpk_lt_u32 s12, 0x180
	s_cbranch_scc0 .Lip1_nonq
	v_mul_f32_e32 v62, 0x3e38aa3b, v62
	v_mul_f32_e32 v63, 0x3e38aa3b, v63
	v_mul_f32_e32 v64, 0x3e38aa3b, v64
	v_mul_f32_e32 v65, 0x3e38aa3b, v65
	v_mul_f32_e32 v58, 0x3e38aa3b, v58
	v_mul_f32_e32 v59, 0x3e38aa3b, v59
	v_mul_f32_e32 v60, 0x3e38aa3b, v60
	v_mul_f32_e32 v61, 0x3e38aa3b, v61
	v_mul_f32_e32 v54, 0x3e38aa3b, v54
	v_mul_f32_e32 v55, 0x3e38aa3b, v55
	v_mul_f32_e32 v56, 0x3e38aa3b, v56
	v_mul_f32_e32 v57, 0x3e38aa3b, v57
	v_mul_f32_e32 v50, 0x3e38aa3b, v50
	v_mul_f32_e32 v51, 0x3e38aa3b, v51
	v_mul_f32_e32 v52, 0x3e38aa3b, v52
	v_mul_f32_e32 v53, 0x3e38aa3b, v53
	v_mul_f32_e32 v46, 0x3e38aa3b, v46
	v_mul_f32_e32 v47, 0x3e38aa3b, v47
	v_mul_f32_e32 v48, 0x3e38aa3b, v48
	v_mul_f32_e32 v49, 0x3e38aa3b, v49
	v_mul_f32_e32 v42, 0x3e38aa3b, v42
	v_mul_f32_e32 v43, 0x3e38aa3b, v43
	v_mul_f32_e32 v44, 0x3e38aa3b, v44
	v_mul_f32_e32 v45, 0x3e38aa3b, v45
	v_mul_f32_e32 v38, 0x3e38aa3b, v38
	v_mul_f32_e32 v39, 0x3e38aa3b, v39
	v_mul_f32_e32 v40, 0x3e38aa3b, v40
	v_mul_f32_e32 v41, 0x3e38aa3b, v41
	v_mul_f32_e32 v34, 0x3e38aa3b, v34
	v_mul_f32_e32 v35, 0x3e38aa3b, v35
	v_mul_f32_e32 v36, 0x3e38aa3b, v36
	v_mul_f32_e32 v37, 0x3e38aa3b, v37
	v_mul_f32_e32 v30, 0x3e38aa3b, v30
	v_mul_f32_e32 v31, 0x3e38aa3b, v31
	v_mul_f32_e32 v32, 0x3e38aa3b, v32
	v_mul_f32_e32 v33, 0x3e38aa3b, v33
	v_mul_f32_e32 v26, 0x3e38aa3b, v26
	v_mul_f32_e32 v27, 0x3e38aa3b, v27
	v_mul_f32_e32 v28, 0x3e38aa3b, v28
	v_mul_f32_e32 v29, 0x3e38aa3b, v29
	v_mul_f32_e32 v22, 0x3e38aa3b, v22
	v_mul_f32_e32 v23, 0x3e38aa3b, v23
	v_mul_f32_e32 v24, 0x3e38aa3b, v24
	v_mul_f32_e32 v25, 0x3e38aa3b, v25
	v_mul_f32_e32 v18, 0x3e38aa3b, v18
	v_mul_f32_e32 v19, 0x3e38aa3b, v19
	v_mul_f32_e32 v20, 0x3e38aa3b, v20
	v_mul_f32_e32 v21, 0x3e38aa3b, v21
	v_mul_f32_e32 v14, 0x3e38aa3b, v14
	v_mul_f32_e32 v15, 0x3e38aa3b, v15
	v_mul_f32_e32 v16, 0x3e38aa3b, v16
	v_mul_f32_e32 v17, 0x3e38aa3b, v17
	v_mul_f32_e32 v10, 0x3e38aa3b, v10
	v_mul_f32_e32 v11, 0x3e38aa3b, v11
	v_mul_f32_e32 v12, 0x3e38aa3b, v12
	v_mul_f32_e32 v13, 0x3e38aa3b, v13
	v_mul_f32_e32 v6, 0x3e38aa3b, v6
	v_mul_f32_e32 v7, 0x3e38aa3b, v7
	v_mul_f32_e32 v8, 0x3e38aa3b, v8
	v_mul_f32_e32 v9, 0x3e38aa3b, v9
	v_mul_f32_e32 v2, 0x3e38aa3b, v2
	v_mul_f32_e32 v3, 0x3e38aa3b, v3
	v_mul_f32_e32 v4, 0x3e38aa3b, v4
	v_mul_f32_e32 v5, 0x3e38aa3b, v5
.Lip1_nonq:
	s_cmpk_lt_i32 s3, 0xa00
	s_cbranch_scc1 .Lip1_nogate
	v_mul_f32_e32 v130, 0xbfb8aa3b, v62
	v_mul_f32_e32 v131, 0xbfb8aa3b, v63
	v_mul_f32_e32 v132, 0xbfb8aa3b, v64
	v_mul_f32_e32 v133, 0xbfb8aa3b, v65
	v_mul_f32_e32 v134, 0xbfb8aa3b, v58
	v_mul_f32_e32 v135, 0xbfb8aa3b, v59
	v_mul_f32_e32 v136, 0xbfb8aa3b, v60
	v_mul_f32_e32 v137, 0xbfb8aa3b, v61
	v_exp_f32_e32 v130, v130
	v_exp_f32_e32 v131, v131
	v_exp_f32_e32 v132, v132
	v_exp_f32_e32 v133, v133
	v_exp_f32_e32 v134, v134
	v_exp_f32_e32 v135, v135
	v_exp_f32_e32 v136, v136
	v_exp_f32_e32 v137, v137
	v_add_f32_e32 v130, 1.0, v130
	v_add_f32_e32 v131, 1.0, v131
	v_add_f32_e32 v132, 1.0, v132
	v_add_f32_e32 v133, 1.0, v133
	v_add_f32_e32 v134, 1.0, v134
	v_add_f32_e32 v135, 1.0, v135
	v_add_f32_e32 v136, 1.0, v136
	v_add_f32_e32 v137, 1.0, v137
	v_rcp_f32_e32 v130, v130
	v_rcp_f32_e32 v131, v131
	v_rcp_f32_e32 v132, v132
	v_rcp_f32_e32 v133, v133
	v_rcp_f32_e32 v134, v134
	v_rcp_f32_e32 v135, v135
	v_rcp_f32_e32 v136, v136
	v_rcp_f32_e32 v137, v137
	v_mul_f32_e32 v62, v62, v130
	v_mul_f32_e32 v63, v63, v131
	v_mul_f32_e32 v64, v64, v132
	v_mul_f32_e32 v65, v65, v133
	v_mul_f32_e32 v58, v58, v134
	v_mul_f32_e32 v59, v59, v135
	v_mul_f32_e32 v60, v60, v136
	v_mul_f32_e32 v61, v61, v137
	v_mul_f32_e32 v130, 0xbfb8aa3b, v54
	v_mul_f32_e32 v131, 0xbfb8aa3b, v55
	v_mul_f32_e32 v132, 0xbfb8aa3b, v56
	v_mul_f32_e32 v133, 0xbfb8aa3b, v57
	v_mul_f32_e32 v134, 0xbfb8aa3b, v50
	v_mul_f32_e32 v135, 0xbfb8aa3b, v51
	v_mul_f32_e32 v136, 0xbfb8aa3b, v52
	v_mul_f32_e32 v137, 0xbfb8aa3b, v53
	v_exp_f32_e32 v130, v130
	v_exp_f32_e32 v131, v131
	v_exp_f32_e32 v132, v132
	v_exp_f32_e32 v133, v133
	v_exp_f32_e32 v134, v134
	v_exp_f32_e32 v135, v135
	v_exp_f32_e32 v136, v136
	v_exp_f32_e32 v137, v137
	v_add_f32_e32 v130, 1.0, v130
	v_add_f32_e32 v131, 1.0, v131
	v_add_f32_e32 v132, 1.0, v132
	v_add_f32_e32 v133, 1.0, v133
	v_add_f32_e32 v134, 1.0, v134
	v_add_f32_e32 v135, 1.0, v135
	v_add_f32_e32 v136, 1.0, v136
	v_add_f32_e32 v137, 1.0, v137
	v_rcp_f32_e32 v130, v130
	v_rcp_f32_e32 v131, v131
	v_rcp_f32_e32 v132, v132
	v_rcp_f32_e32 v133, v133
	v_rcp_f32_e32 v134, v134
	v_rcp_f32_e32 v135, v135
	v_rcp_f32_e32 v136, v136
	v_rcp_f32_e32 v137, v137
	v_mul_f32_e32 v54, v54, v130
	v_mul_f32_e32 v55, v55, v131
	v_mul_f32_e32 v56, v56, v132
	v_mul_f32_e32 v57, v57, v133
	v_mul_f32_e32 v50, v50, v134
	v_mul_f32_e32 v51, v51, v135
	v_mul_f32_e32 v52, v52, v136
	v_mul_f32_e32 v53, v53, v137
	v_mul_f32_e32 v130, 0xbfb8aa3b, v46
	v_mul_f32_e32 v131, 0xbfb8aa3b, v47
	v_mul_f32_e32 v132, 0xbfb8aa3b, v48
	v_mul_f32_e32 v133, 0xbfb8aa3b, v49
	v_mul_f32_e32 v134, 0xbfb8aa3b, v42
	v_mul_f32_e32 v135, 0xbfb8aa3b, v43
	v_mul_f32_e32 v136, 0xbfb8aa3b, v44
	v_mul_f32_e32 v137, 0xbfb8aa3b, v45
	v_exp_f32_e32 v130, v130
	v_exp_f32_e32 v131, v131
	v_exp_f32_e32 v132, v132
	v_exp_f32_e32 v133, v133
	v_exp_f32_e32 v134, v134
	v_exp_f32_e32 v135, v135
	v_exp_f32_e32 v136, v136
	v_exp_f32_e32 v137, v137
	v_add_f32_e32 v130, 1.0, v130
	v_add_f32_e32 v131, 1.0, v131
	v_add_f32_e32 v132, 1.0, v132
	v_add_f32_e32 v133, 1.0, v133
	v_add_f32_e32 v134, 1.0, v134
	v_add_f32_e32 v135, 1.0, v135
	v_add_f32_e32 v136, 1.0, v136
	v_add_f32_e32 v137, 1.0, v137
	v_rcp_f32_e32 v130, v130
	v_rcp_f32_e32 v131, v131
	v_rcp_f32_e32 v132, v132
	v_rcp_f32_e32 v133, v133
	v_rcp_f32_e32 v134, v134
	v_rcp_f32_e32 v135, v135
	v_rcp_f32_e32 v136, v136
	v_rcp_f32_e32 v137, v137
	v_mul_f32_e32 v46, v46, v130
	v_mul_f32_e32 v47, v47, v131
	v_mul_f32_e32 v48, v48, v132
	v_mul_f32_e32 v49, v49, v133
	v_mul_f32_e32 v42, v42, v134
	v_mul_f32_e32 v43, v43, v135
	v_mul_f32_e32 v44, v44, v136
	v_mul_f32_e32 v45, v45, v137
	v_mul_f32_e32 v130, 0xbfb8aa3b, v38
	v_mul_f32_e32 v131, 0xbfb8aa3b, v39
	v_mul_f32_e32 v132, 0xbfb8aa3b, v40
	v_mul_f32_e32 v133, 0xbfb8aa3b, v41
	v_mul_f32_e32 v134, 0xbfb8aa3b, v34
	v_mul_f32_e32 v135, 0xbfb8aa3b, v35
	v_mul_f32_e32 v136, 0xbfb8aa3b, v36
	v_mul_f32_e32 v137, 0xbfb8aa3b, v37
	v_exp_f32_e32 v130, v130
	v_exp_f32_e32 v131, v131
	v_exp_f32_e32 v132, v132
	v_exp_f32_e32 v133, v133
	v_exp_f32_e32 v134, v134
	v_exp_f32_e32 v135, v135
	v_exp_f32_e32 v136, v136
	v_exp_f32_e32 v137, v137
	v_add_f32_e32 v130, 1.0, v130
	v_add_f32_e32 v131, 1.0, v131
	v_add_f32_e32 v132, 1.0, v132
	v_add_f32_e32 v133, 1.0, v133
	v_add_f32_e32 v134, 1.0, v134
	v_add_f32_e32 v135, 1.0, v135
	v_add_f32_e32 v136, 1.0, v136
	v_add_f32_e32 v137, 1.0, v137
	v_rcp_f32_e32 v130, v130
	v_rcp_f32_e32 v131, v131
	v_rcp_f32_e32 v132, v132
	v_rcp_f32_e32 v133, v133
	v_rcp_f32_e32 v134, v134
	v_rcp_f32_e32 v135, v135
	v_rcp_f32_e32 v136, v136
	v_rcp_f32_e32 v137, v137
	v_mul_f32_e32 v38, v38, v130
	v_mul_f32_e32 v39, v39, v131
	v_mul_f32_e32 v40, v40, v132
	v_mul_f32_e32 v41, v41, v133
	v_mul_f32_e32 v34, v34, v134
	v_mul_f32_e32 v35, v35, v135
	v_mul_f32_e32 v36, v36, v136
	v_mul_f32_e32 v37, v37, v137
	v_mul_f32_e32 v130, 0xbfb8aa3b, v30
	v_mul_f32_e32 v131, 0xbfb8aa3b, v31
	v_mul_f32_e32 v132, 0xbfb8aa3b, v32
	v_mul_f32_e32 v133, 0xbfb8aa3b, v33
	v_mul_f32_e32 v134, 0xbfb8aa3b, v26
	v_mul_f32_e32 v135, 0xbfb8aa3b, v27
	v_mul_f32_e32 v136, 0xbfb8aa3b, v28
	v_mul_f32_e32 v137, 0xbfb8aa3b, v29
	v_exp_f32_e32 v130, v130
	v_exp_f32_e32 v131, v131
	v_exp_f32_e32 v132, v132
	v_exp_f32_e32 v133, v133
	v_exp_f32_e32 v134, v134
	v_exp_f32_e32 v135, v135
	v_exp_f32_e32 v136, v136
	v_exp_f32_e32 v137, v137
	v_add_f32_e32 v130, 1.0, v130
	v_add_f32_e32 v131, 1.0, v131
	v_add_f32_e32 v132, 1.0, v132
	v_add_f32_e32 v133, 1.0, v133
	v_add_f32_e32 v134, 1.0, v134
	v_add_f32_e32 v135, 1.0, v135
	v_add_f32_e32 v136, 1.0, v136
	v_add_f32_e32 v137, 1.0, v137
	v_rcp_f32_e32 v130, v130
	v_rcp_f32_e32 v131, v131
	v_rcp_f32_e32 v132, v132
	v_rcp_f32_e32 v133, v133
	v_rcp_f32_e32 v134, v134
	v_rcp_f32_e32 v135, v135
	v_rcp_f32_e32 v136, v136
	v_rcp_f32_e32 v137, v137
	v_mul_f32_e32 v30, v30, v130
	v_mul_f32_e32 v31, v31, v131
	v_mul_f32_e32 v32, v32, v132
	v_mul_f32_e32 v33, v33, v133
	v_mul_f32_e32 v26, v26, v134
	v_mul_f32_e32 v27, v27, v135
	v_mul_f32_e32 v28, v28, v136
	v_mul_f32_e32 v29, v29, v137
	v_mul_f32_e32 v130, 0xbfb8aa3b, v22
	v_mul_f32_e32 v131, 0xbfb8aa3b, v23
	v_mul_f32_e32 v132, 0xbfb8aa3b, v24
	v_mul_f32_e32 v133, 0xbfb8aa3b, v25
	v_mul_f32_e32 v134, 0xbfb8aa3b, v18
	v_mul_f32_e32 v135, 0xbfb8aa3b, v19
	v_mul_f32_e32 v136, 0xbfb8aa3b, v20
	v_mul_f32_e32 v137, 0xbfb8aa3b, v21
	v_exp_f32_e32 v130, v130
	v_exp_f32_e32 v131, v131
	v_exp_f32_e32 v132, v132
	v_exp_f32_e32 v133, v133
	v_exp_f32_e32 v134, v134
	v_exp_f32_e32 v135, v135
	v_exp_f32_e32 v136, v136
	v_exp_f32_e32 v137, v137
	v_add_f32_e32 v130, 1.0, v130
	v_add_f32_e32 v131, 1.0, v131
	v_add_f32_e32 v132, 1.0, v132
	v_add_f32_e32 v133, 1.0, v133
	v_add_f32_e32 v134, 1.0, v134
	v_add_f32_e32 v135, 1.0, v135
	v_add_f32_e32 v136, 1.0, v136
	v_add_f32_e32 v137, 1.0, v137
	v_rcp_f32_e32 v130, v130
	v_rcp_f32_e32 v131, v131
	v_rcp_f32_e32 v132, v132
	v_rcp_f32_e32 v133, v133
	v_rcp_f32_e32 v134, v134
	v_rcp_f32_e32 v135, v135
	v_rcp_f32_e32 v136, v136
	v_rcp_f32_e32 v137, v137
	v_mul_f32_e32 v22, v22, v130
	v_mul_f32_e32 v23, v23, v131
	v_mul_f32_e32 v24, v24, v132
	v_mul_f32_e32 v25, v25, v133
	v_mul_f32_e32 v18, v18, v134
	v_mul_f32_e32 v19, v19, v135
	v_mul_f32_e32 v20, v20, v136
	v_mul_f32_e32 v21, v21, v137
	v_mul_f32_e32 v130, 0xbfb8aa3b, v14
	v_mul_f32_e32 v131, 0xbfb8aa3b, v15
	v_mul_f32_e32 v132, 0xbfb8aa3b, v16
	v_mul_f32_e32 v133, 0xbfb8aa3b, v17
	v_mul_f32_e32 v134, 0xbfb8aa3b, v10
	v_mul_f32_e32 v135, 0xbfb8aa3b, v11
	v_mul_f32_e32 v136, 0xbfb8aa3b, v12
	v_mul_f32_e32 v137, 0xbfb8aa3b, v13
	v_exp_f32_e32 v130, v130
	v_exp_f32_e32 v131, v131
	v_exp_f32_e32 v132, v132
	v_exp_f32_e32 v133, v133
	v_exp_f32_e32 v134, v134
	v_exp_f32_e32 v135, v135
	v_exp_f32_e32 v136, v136
	v_exp_f32_e32 v137, v137
	v_add_f32_e32 v130, 1.0, v130
	v_add_f32_e32 v131, 1.0, v131
	v_add_f32_e32 v132, 1.0, v132
	v_add_f32_e32 v133, 1.0, v133
	v_add_f32_e32 v134, 1.0, v134
	v_add_f32_e32 v135, 1.0, v135
	v_add_f32_e32 v136, 1.0, v136
	v_add_f32_e32 v137, 1.0, v137
	v_rcp_f32_e32 v130, v130
	v_rcp_f32_e32 v131, v131
	v_rcp_f32_e32 v132, v132
	v_rcp_f32_e32 v133, v133
	v_rcp_f32_e32 v134, v134
	v_rcp_f32_e32 v135, v135
	v_rcp_f32_e32 v136, v136
	v_rcp_f32_e32 v137, v137
	v_mul_f32_e32 v14, v14, v130
	v_mul_f32_e32 v15, v15, v131
	v_mul_f32_e32 v16, v16, v132
	v_mul_f32_e32 v17, v17, v133
	v_mul_f32_e32 v10, v10, v134
	v_mul_f32_e32 v11, v11, v135
	v_mul_f32_e32 v12, v12, v136
	v_mul_f32_e32 v13, v13, v137
	v_mul_f32_e32 v130, 0xbfb8aa3b, v6
	v_mul_f32_e32 v131, 0xbfb8aa3b, v7
	v_mul_f32_e32 v132, 0xbfb8aa3b, v8
	v_mul_f32_e32 v133, 0xbfb8aa3b, v9
	v_mul_f32_e32 v134, 0xbfb8aa3b, v2
	v_mul_f32_e32 v135, 0xbfb8aa3b, v3
	v_mul_f32_e32 v136, 0xbfb8aa3b, v4
	v_mul_f32_e32 v137, 0xbfb8aa3b, v5
	v_exp_f32_e32 v130, v130
	v_exp_f32_e32 v131, v131
	v_exp_f32_e32 v132, v132
	v_exp_f32_e32 v133, v133
	v_exp_f32_e32 v134, v134
	v_exp_f32_e32 v135, v135
	v_exp_f32_e32 v136, v136
	v_exp_f32_e32 v137, v137
	v_add_f32_e32 v130, 1.0, v130
	v_add_f32_e32 v131, 1.0, v131
	v_add_f32_e32 v132, 1.0, v132
	v_add_f32_e32 v133, 1.0, v133
	v_add_f32_e32 v134, 1.0, v134
	v_add_f32_e32 v135, 1.0, v135
	v_add_f32_e32 v136, 1.0, v136
	v_add_f32_e32 v137, 1.0, v137
	v_rcp_f32_e32 v130, v130
	v_rcp_f32_e32 v131, v131
	v_rcp_f32_e32 v132, v132
	v_rcp_f32_e32 v133, v133
	v_rcp_f32_e32 v134, v134
	v_rcp_f32_e32 v135, v135
	v_rcp_f32_e32 v136, v136
	v_rcp_f32_e32 v137, v137
	v_mul_f32_e32 v6, v6, v130
	v_mul_f32_e32 v7, v7, v131
	v_mul_f32_e32 v8, v8, v132
	v_mul_f32_e32 v9, v9, v133
	v_mul_f32_e32 v2, v2, v134
	v_mul_f32_e32 v3, v3, v135
	v_mul_f32_e32 v4, v4, v136
	v_mul_f32_e32 v5, v5, v137
.Lip1_nogate:
	v_cvt_pk_bf16_f32 v138, v62, v63
	v_cvt_pk_bf16_f32 v139, v64, v65
	global_store_dwordx2 v169, v[138:139], s[60:61]
	v_cvt_pk_bf16_f32 v140, v58, v59
	v_cvt_pk_bf16_f32 v141, v60, v61
	global_store_dwordx2 v169, v[140:141], s[60:61] offset:32
	v_add_u32_e32 v170, 0x1700, v169
	v_cvt_pk_bf16_f32 v142, v54, v55
	v_cvt_pk_bf16_f32 v143, v56, v57
	global_store_dwordx2 v170, v[142:143], s[60:61]
	v_cvt_pk_bf16_f32 v144, v50, v51
	v_cvt_pk_bf16_f32 v145, v52, v53
	global_store_dwordx2 v170, v[144:145], s[60:61] offset:32
	v_add_u32_e32 v171, 0x2e00, v169
	v_cvt_pk_bf16_f32 v146, v46, v47
	v_cvt_pk_bf16_f32 v147, v48, v49
	global_store_dwordx2 v171, v[146:147], s[60:61]
	v_cvt_pk_bf16_f32 v148, v42, v43
	v_cvt_pk_bf16_f32 v149, v44, v45
	global_store_dwordx2 v171, v[148:149], s[60:61] offset:32
	v_add_u32_e32 v172, 0x4500, v169
	v_cvt_pk_bf16_f32 v150, v38, v39
	v_cvt_pk_bf16_f32 v151, v40, v41
	global_store_dwordx2 v172, v[150:151], s[60:61]
	v_cvt_pk_bf16_f32 v152, v34, v35
	v_cvt_pk_bf16_f32 v153, v36, v37
	global_store_dwordx2 v172, v[152:153], s[60:61] offset:32
	v_add_u32_e32 v173, 0xb8000, v169
	v_cvt_pk_bf16_f32 v138, v30, v31
	v_cvt_pk_bf16_f32 v139, v32, v33
	global_store_dwordx2 v173, v[138:139], s[60:61]
	v_cvt_pk_bf16_f32 v140, v26, v27
	v_cvt_pk_bf16_f32 v141, v28, v29
	global_store_dwordx2 v173, v[140:141], s[60:61] offset:32
	v_add_u32_e32 v174, 0xb9700, v169
	v_cvt_pk_bf16_f32 v142, v22, v23
	v_cvt_pk_bf16_f32 v143, v24, v25
	global_store_dwordx2 v174, v[142:143], s[60:61]
	v_cvt_pk_bf16_f32 v144, v18, v19
	v_cvt_pk_bf16_f32 v145, v20, v21
	global_store_dwordx2 v174, v[144:145], s[60:61] offset:32
	v_add_u32_e32 v175, 0xbae00, v169
	v_cvt_pk_bf16_f32 v146, v14, v15
	v_cvt_pk_bf16_f32 v147, v16, v17
	global_store_dwordx2 v175, v[146:147], s[60:61]
	v_cvt_pk_bf16_f32 v148, v10, v11
	v_cvt_pk_bf16_f32 v149, v12, v13
	global_store_dwordx2 v175, v[148:149], s[60:61] offset:32
	v_add_u32_e32 v176, 0xbc500, v169
	v_cvt_pk_bf16_f32 v150, v6, v7
	v_cvt_pk_bf16_f32 v151, v8, v9
	global_store_dwordx2 v176, v[150:151], s[60:61]
	v_cvt_pk_bf16_f32 v152, v2, v3
	v_cvt_pk_bf16_f32 v153, v4, v5
	global_store_dwordx2 v176, v[152:153], s[60:61] offset:32
	s_branch .Lip1_end
.Lip1_V:
	s_cmpk_lt_u32 s0, 0x180
	s_cselect_b32 s12, s0, s1
	s_mov_b32 s15, 0x12da4000
	s_cselect_b32 s15, 0x12174000, s15
	s_add_u32 s64, s8, s15
	s_addc_u32 s65, s9, 0
	v_add_u32_e32 v168, s12, v228
	v_mul_u32_u24_e32 v168, 0x8200, v168
	v_lshl_add_u32 v168, v166, 1, v168
	v_cvt_pk_bf16_f32 v138, v62, v54
	v_cvt_pk_bf16_f32 v139, v46, v38
	global_store_dwordx2 v168, v[138:139], s[64:65]
	v_add_u32_e32 v170, 0x8200, v168
	v_cvt_pk_bf16_f32 v140, v63, v55
	v_cvt_pk_bf16_f32 v141, v47, v39
	global_store_dwordx2 v170, v[140:141], s[64:65]
	v_add_u32_e32 v171, 0x10400, v168
	v_cvt_pk_bf16_f32 v142, v64, v56
	v_cvt_pk_bf16_f32 v143, v48, v40
	global_store_dwordx2 v171, v[142:143], s[64:65]
	v_add_u32_e32 v172, 0x18600, v168
	v_cvt_pk_bf16_f32 v144, v65, v57
	v_cvt_pk_bf16_f32 v145, v49, v41
	global_store_dwordx2 v172, v[144:145], s[64:65]
	v_add_u32_e32 v173, 0x82000, v168
	v_cvt_pk_bf16_f32 v146, v58, v50
	v_cvt_pk_bf16_f32 v147, v42, v34
	global_store_dwordx2 v173, v[146:147], s[64:65]
	v_add_u32_e32 v174, 0x8a200, v168
	v_cvt_pk_bf16_f32 v148, v59, v51
	v_cvt_pk_bf16_f32 v149, v43, v35
	global_store_dwordx2 v174, v[148:149], s[64:65]
	v_add_u32_e32 v175, 0x92400, v168
	v_cvt_pk_bf16_f32 v150, v60, v52
	v_cvt_pk_bf16_f32 v151, v44, v36
	global_store_dwordx2 v175, v[150:151], s[64:65]
	v_add_u32_e32 v176, 0x9a600, v168
	v_cvt_pk_bf16_f32 v152, v61, v53
	v_cvt_pk_bf16_f32 v153, v45, v37
	global_store_dwordx2 v176, v[152:153], s[64:65]
	v_cvt_pk_bf16_f32 v138, v30, v22
	v_cvt_pk_bf16_f32 v139, v14, v6
	global_store_dwordx2 v168, v[138:139], s[64:65] offset:256
	v_add_u32_e32 v177, 0x8200, v168
	v_cvt_pk_bf16_f32 v140, v31, v23
	v_cvt_pk_bf16_f32 v141, v15, v7
	global_store_dwordx2 v177, v[140:141], s[64:65] offset:256
	v_add_u32_e32 v170, 0x10400, v168
	v_cvt_pk_bf16_f32 v142, v32, v24
	v_cvt_pk_bf16_f32 v143, v16, v8
	global_store_dwordx2 v170, v[142:143], s[64:65] offset:256
	v_add_u32_e32 v171, 0x18600, v168
	v_cvt_pk_bf16_f32 v144, v33, v25
	v_cvt_pk_bf16_f32 v145, v17, v9
	global_store_dwordx2 v171, v[144:145], s[64:65] offset:256
	v_add_u32_e32 v172, 0x82000, v168
	v_cvt_pk_bf16_f32 v146, v26, v18
	v_cvt_pk_bf16_f32 v147, v10, v2
	global_store_dwordx2 v172, v[146:147], s[64:65] offset:256
	v_add_u32_e32 v173, 0x8a200, v168
	v_cvt_pk_bf16_f32 v148, v27, v19
	v_cvt_pk_bf16_f32 v149, v11, v3
	global_store_dwordx2 v173, v[148:149], s[64:65] offset:256
	v_add_u32_e32 v174, 0x92400, v168
	v_cvt_pk_bf16_f32 v150, v28, v20
	v_cvt_pk_bf16_f32 v151, v12, v4
	global_store_dwordx2 v174, v[150:151], s[64:65] offset:256
	v_add_u32_e32 v175, 0x9a600, v168
	v_cvt_pk_bf16_f32 v152, v29, v21
	v_cvt_pk_bf16_f32 v153, v13, v5
	global_store_dwordx2 v175, v[152:153], s[64:65] offset:256
	s_branch .Lip1_end

.Lip1_Rnodec:
	s_cmp_lg_u32 s47, 0
	s_cbranch_scc0 .Lip1_a0_norot
	s_waitcnt vmcnt(0)
	v_mul_f32_e32 v142, v58, v186
	v_mul_f32_e32 v58, v58, v170
	v_fmac_f32_e32 v58, v62, v186
	v_fma_f32 v62, v62, v170, -v142
	v_mul_f32_e32 v143, v59, v187
	v_mul_f32_e32 v59, v59, v171
	v_fmac_f32_e32 v59, v63, v187
	v_fma_f32 v63, v63, v171, -v143
	v_mul_f32_e32 v144, v60, v188
	v_mul_f32_e32 v60, v60, v172
	v_fmac_f32_e32 v60, v64, v188
	v_fma_f32 v64, v64, v172, -v144
	v_mul_f32_e32 v145, v61, v189
	v_mul_f32_e32 v61, v61, v173
	v_fmac_f32_e32 v61, v65, v189
	v_fma_f32 v65, v65, v173, -v145
	v_mul_f32_e32 v142, v50, v190
	v_mul_f32_e32 v50, v50, v174
	v_fmac_f32_e32 v50, v54, v190
	v_fma_f32 v54, v54, v174, -v142
	v_mul_f32_e32 v143, v51, v191
	v_mul_f32_e32 v51, v51, v175
	v_fmac_f32_e32 v51, v55, v191
	v_fma_f32 v55, v55, v175, -v143
	v_mul_f32_e32 v144, v52, v192
	v_mul_f32_e32 v52, v52, v176
	v_fmac_f32_e32 v52, v56, v192
	v_fma_f32 v56, v56, v176, -v144
	v_mul_f32_e32 v145, v53, v193
	v_mul_f32_e32 v53, v53, v177
	v_fmac_f32_e32 v53, v57, v193
	v_fma_f32 v57, v57, v177, -v145
	v_mul_f32_e32 v142, v42, v194
	v_mul_f32_e32 v42, v42, v178
	v_fmac_f32_e32 v42, v46, v194
	v_fma_f32 v46, v46, v178, -v142
	v_mul_f32_e32 v143, v43, v195
	v_mul_f32_e32 v43, v43, v179
	v_fmac_f32_e32 v43, v47, v195
	v_fma_f32 v47, v47, v179, -v143
	v_mul_f32_e32 v144, v44, v196
	v_mul_f32_e32 v44, v44, v180
	v_fmac_f32_e32 v44, v48, v196
	v_fma_f32 v48, v48, v180, -v144
	v_mul_f32_e32 v145, v45, v197
	v_mul_f32_e32 v45, v45, v181
	v_fmac_f32_e32 v45, v49, v197
	v_fma_f32 v49, v49, v181, -v145
	v_mul_f32_e32 v142, v34, v198
	v_mul_f32_e32 v34, v34, v182
	v_fmac_f32_e32 v34, v38, v198
	v_fma_f32 v38, v38, v182, -v142
	v_mul_f32_e32 v143, v35, v199
	v_mul_f32_e32 v35, v35, v183
	v_fmac_f32_e32 v35, v39, v199
	v_fma_f32 v39, v39, v183, -v143
	v_mul_f32_e32 v144, v36, v200
	v_mul_f32_e32 v36, v36, v184
	v_fmac_f32_e32 v36, v40, v200
	v_fma_f32 v40, v40, v184, -v144
	v_mul_f32_e32 v145, v37, v201
	v_mul_f32_e32 v37, v37, v185
	v_fmac_f32_e32 v37, v41, v201
	v_fma_f32 v41, v41, v185, -v145
	v_add_u32_e32 v130, s15, v130
	v_add_u32_e32 v131, s15, v131
	v_add_u32_e32 v132, s15, v132
	v_add_u32_e32 v133, s15, v133
	global_load_dwordx4 v[170:173], v130, s[44:45]
	global_load_dwordx4 v[186:189], v130, s[16:17]
	global_load_dwordx4 v[174:177], v131, s[44:45]
	global_load_dwordx4 v[190:193], v131, s[16:17]
	global_load_dwordx4 v[178:181], v132, s[44:45]
	global_load_dwordx4 v[194:197], v132, s[16:17]
	global_load_dwordx4 v[182:185], v133, s[44:45]
	global_load_dwordx4 v[198:201], v133, s[16:17]
.Lip1_a0_norot:
	s_cmp_lg_u32 s46, 0
	s_cbranch_scc0 .Lip1_a0_noscale
	v_mul_f32_e32 v62, 0x3e000000, v62
	v_mul_f32_e32 v63, 0x3e000000, v63
	v_mul_f32_e32 v64, 0x3e000000, v64
	v_mul_f32_e32 v65, 0x3e000000, v65
	v_mul_f32_e32 v58, 0x3e000000, v58
	v_mul_f32_e32 v59, 0x3e000000, v59
	v_mul_f32_e32 v60, 0x3e000000, v60
	v_mul_f32_e32 v61, 0x3e000000, v61
	v_mul_f32_e32 v54, 0x3e000000, v54
	v_mul_f32_e32 v55, 0x3e000000, v55
	v_mul_f32_e32 v56, 0x3e000000, v56
	v_mul_f32_e32 v57, 0x3e000000, v57
	v_mul_f32_e32 v50, 0x3e000000, v50
	v_mul_f32_e32 v51, 0x3e000000, v51
	v_mul_f32_e32 v52, 0x3e000000, v52
	v_mul_f32_e32 v53, 0x3e000000, v53
	v_mul_f32_e32 v46, 0x3e000000, v46
	v_mul_f32_e32 v47, 0x3e000000, v47
	v_mul_f32_e32 v48, 0x3e000000, v48
	v_mul_f32_e32 v49, 0x3e000000, v49
	v_mul_f32_e32 v42, 0x3e000000, v42
	v_mul_f32_e32 v43, 0x3e000000, v43
	v_mul_f32_e32 v44, 0x3e000000, v44
	v_mul_f32_e32 v45, 0x3e000000, v45
	v_mul_f32_e32 v38, 0x3e000000, v38
	v_mul_f32_e32 v39, 0x3e000000, v39
	v_mul_f32_e32 v40, 0x3e000000, v40
	v_mul_f32_e32 v41, 0x3e000000, v41
	v_mul_f32_e32 v34, 0x3e000000, v34
	v_mul_f32_e32 v35, 0x3e000000, v35
	v_mul_f32_e32 v36, 0x3e000000, v36
	v_mul_f32_e32 v37, 0x3e000000, v37
.Lip1_a0_noscale:
	v_cvt_pk_bf16_f32 v146, v62, v63
	v_cvt_pk_bf16_f32 v147, v64, v65
	global_store_dwordx2 v169, v[146:147], s[60:61]
	v_cvt_pk_bf16_f32 v148, v58, v59
	v_cvt_pk_bf16_f32 v149, v60, v61
	global_store_dwordx2 v169, v[148:149], s[60:61] offset:32
	v_add_u32_e32 v234, 0x1700, v169
	v_cvt_pk_bf16_f32 v150, v54, v55
	v_cvt_pk_bf16_f32 v151, v56, v57
	global_store_dwordx2 v234, v[150:151], s[60:61]
	v_cvt_pk_bf16_f32 v152, v50, v51
	v_cvt_pk_bf16_f32 v153, v52, v53
	global_store_dwordx2 v234, v[152:153], s[60:61] offset:32
	v_add_u32_e32 v235, 0x2e00, v169
	v_cvt_pk_bf16_f32 v146, v46, v47
	v_cvt_pk_bf16_f32 v147, v48, v49
	global_store_dwordx2 v235, v[146:147], s[60:61]
	v_cvt_pk_bf16_f32 v148, v42, v43
	v_cvt_pk_bf16_f32 v149, v44, v45
	global_store_dwordx2 v235, v[148:149], s[60:61] offset:32
	v_add_u32_e32 v236, 0x4500, v169
	v_cvt_pk_bf16_f32 v150, v38, v39
	v_cvt_pk_bf16_f32 v151, v40, v41
	global_store_dwordx2 v236, v[150:151], s[60:61]
	v_cvt_pk_bf16_f32 v152, v34, v35
	v_cvt_pk_bf16_f32 v153, v36, v37
	global_store_dwordx2 v236, v[152:153], s[60:61] offset:32
	s_cmp_lg_u32 s46, 0
	s_cbranch_scc0 .Lip1_a0_nokt
	v_mul_f32_e32 v142, v62, v134
	v_mul_f32_e32 v143, v54, v135
	v_mul_f32_e32 v144, v46, v136
	v_mul_f32_e32 v145, v38, v137
	v_cvt_pk_bf16_f32 v146, v142, v143
	v_cvt_pk_bf16_f32 v147, v144, v145
	global_store_dwordx2 v168, v[146:147], s[24:25]
	v_add_u32_e32 v237, 0x8200, v168
	v_mul_f32_e32 v142, v63, v134
	v_mul_f32_e32 v143, v55, v135
	v_mul_f32_e32 v144, v47, v136
	v_mul_f32_e32 v145, v39, v137
	v_cvt_pk_bf16_f32 v148, v142, v143
	v_cvt_pk_bf16_f32 v149, v144, v145
	global_store_dwordx2 v237, v[148:149], s[24:25]
	v_add_u32_e32 v242, 0x10400, v168
	v_mul_f32_e32 v142, v64, v134
	v_mul_f32_e32 v143, v56, v135
	v_mul_f32_e32 v144, v48, v136
	v_mul_f32_e32 v145, v40, v137
	v_cvt_pk_bf16_f32 v150, v142, v143
	v_cvt_pk_bf16_f32 v151, v144, v145
	global_store_dwordx2 v242, v[150:151], s[24:25]
	v_add_u32_e32 v243, 0x18600, v168
	v_mul_f32_e32 v142, v65, v134
	v_mul_f32_e32 v143, v57, v135
	v_mul_f32_e32 v144, v49, v136
	v_mul_f32_e32 v145, v41, v137
	v_cvt_pk_bf16_f32 v152, v142, v143
	v_cvt_pk_bf16_f32 v153, v144, v145
	global_store_dwordx2 v243, v[152:153], s[24:25]
	v_add_u32_e32 v244, 0x82000, v168
	v_mul_f32_e32 v142, v58, v134
	v_mul_f32_e32 v143, v50, v135
	v_mul_f32_e32 v144, v42, v136
	v_mul_f32_e32 v145, v34, v137
	v_cvt_pk_bf16_f32 v146, v142, v143
	v_cvt_pk_bf16_f32 v147, v144, v145
	global_store_dwordx2 v244, v[146:147], s[24:25]
	v_add_u32_e32 v245, 0x8a200, v168
	v_mul_f32_e32 v142, v59, v134
	v_mul_f32_e32 v143, v51, v135
	v_mul_f32_e32 v144, v43, v136
	v_mul_f32_e32 v145, v35, v137
	v_cvt_pk_bf16_f32 v148, v142, v143
	v_cvt_pk_bf16_f32 v149, v144, v145
	global_store_dwordx2 v245, v[148:149], s[24:25]
	v_add_u32_e32 v234, 0x92400, v168
	v_mul_f32_e32 v142, v60, v134
	v_mul_f32_e32 v143, v52, v135
	v_mul_f32_e32 v144, v44, v136
	v_mul_f32_e32 v145, v36, v137
	v_cvt_pk_bf16_f32 v150, v142, v143
	v_cvt_pk_bf16_f32 v151, v144, v145
	global_store_dwordx2 v234, v[150:151], s[24:25]
	v_add_u32_e32 v235, 0x9a600, v168
	v_mul_f32_e32 v142, v61, v134
	v_mul_f32_e32 v143, v53, v135
	v_mul_f32_e32 v144, v45, v136
	v_mul_f32_e32 v145, v37, v137
	v_cvt_pk_bf16_f32 v152, v142, v143
	v_cvt_pk_bf16_f32 v153, v144, v145
	global_store_dwordx2 v235, v[152:153], s[24:25]
	v_mul_f32_e32 v142, v62, v138
	v_mul_f32_e32 v143, v54, v139
	v_mul_f32_e32 v144, v46, v140
	v_mul_f32_e32 v145, v38, v141
	v_cvt_pk_bf16_f32 v146, v142, v143
	v_cvt_pk_bf16_f32 v147, v144, v145
	global_store_dwordx2 v168, v[146:147], s[82:83]
	v_add_u32_e32 v236, 0x8200, v168
	v_mul_f32_e32 v142, v63, v138
	v_mul_f32_e32 v143, v55, v139
	v_mul_f32_e32 v144, v47, v140
	v_mul_f32_e32 v145, v39, v141
	v_cvt_pk_bf16_f32 v148, v142, v143
	v_cvt_pk_bf16_f32 v149, v144, v145
	global_store_dwordx2 v236, v[148:149], s[82:83]
	v_add_u32_e32 v237, 0x10400, v168
	v_mul_f32_e32 v142, v64, v138
	v_mul_f32_e32 v143, v56, v139
	v_mul_f32_e32 v144, v48, v140
	v_mul_f32_e32 v145, v40, v141
	v_cvt_pk_bf16_f32 v150, v142, v143
	v_cvt_pk_bf16_f32 v151, v144, v145
	global_store_dwordx2 v237, v[150:151], s[82:83]
	v_add_u32_e32 v242, 0x18600, v168
	v_mul_f32_e32 v142, v65, v138
	v_mul_f32_e32 v143, v57, v139
	v_mul_f32_e32 v144, v49, v140
	v_mul_f32_e32 v145, v41, v141
	v_cvt_pk_bf16_f32 v152, v142, v143
	v_cvt_pk_bf16_f32 v153, v144, v145
	global_store_dwordx2 v242, v[152:153], s[82:83]
	v_add_u32_e32 v243, 0x82000, v168
	v_mul_f32_e32 v142, v58, v138
	v_mul_f32_e32 v143, v50, v139
	v_mul_f32_e32 v144, v42, v140
	v_mul_f32_e32 v145, v34, v141
	v_cvt_pk_bf16_f32 v146, v142, v143
	v_cvt_pk_bf16_f32 v147, v144, v145
	global_store_dwordx2 v243, v[146:147], s[82:83]
	v_add_u32_e32 v244, 0x8a200, v168
	v_mul_f32_e32 v142, v59, v138
	v_mul_f32_e32 v143, v51, v139
	v_mul_f32_e32 v144, v43, v140
	v_mul_f32_e32 v145, v35, v141
	v_cvt_pk_bf16_f32 v148, v142, v143
	v_cvt_pk_bf16_f32 v149, v144, v145
	global_store_dwordx2 v244, v[148:149], s[82:83]
	v_add_u32_e32 v245, 0x92400, v168
	v_mul_f32_e32 v142, v60, v138
	v_mul_f32_e32 v143, v52, v139
	v_mul_f32_e32 v144, v44, v140
	v_mul_f32_e32 v145, v36, v141
	v_cvt_pk_bf16_f32 v150, v142, v143
	v_cvt_pk_bf16_f32 v151, v144, v145
	global_store_dwordx2 v245, v[150:151], s[82:83]
	v_add_u32_e32 v234, 0x9a600, v168
	v_mul_f32_e32 v142, v61, v138
	v_mul_f32_e32 v143, v53, v139
	v_mul_f32_e32 v144, v45, v140
	v_mul_f32_e32 v145, v37, v141
	v_cvt_pk_bf16_f32 v152, v142, v143
	v_cvt_pk_bf16_f32 v153, v144, v145
	global_store_dwordx2 v234, v[152:153], s[82:83]
.Lip1_a0_nokt:
	s_cmp_lg_u32 s47, 0
	s_cbranch_scc0 .Lip1_a1_norot
	s_waitcnt vmcnt(0)
	v_mul_f32_e32 v142, v26, v186
	v_mul_f32_e32 v26, v26, v170
	v_fmac_f32_e32 v26, v30, v186
	v_fma_f32 v30, v30, v170, -v142
	v_mul_f32_e32 v143, v27, v187
	v_mul_f32_e32 v27, v27, v171
	v_fmac_f32_e32 v27, v31, v187
	v_fma_f32 v31, v31, v171, -v143
	v_mul_f32_e32 v144, v28, v188
	v_mul_f32_e32 v28, v28, v172
	v_fmac_f32_e32 v28, v32, v188
	v_fma_f32 v32, v32, v172, -v144
	v_mul_f32_e32 v145, v29, v189
	v_mul_f32_e32 v29, v29, v173
	v_fmac_f32_e32 v29, v33, v189
	v_fma_f32 v33, v33, v173, -v145
	v_mul_f32_e32 v142, v18, v190
	v_mul_f32_e32 v18, v18, v174
	v_fmac_f32_e32 v18, v22, v190
	v_fma_f32 v22, v22, v174, -v142
	v_mul_f32_e32 v143, v19, v191
	v_mul_f32_e32 v19, v19, v175
	v_fmac_f32_e32 v19, v23, v191
	v_fma_f32 v23, v23, v175, -v143
	v_mul_f32_e32 v144, v20, v192
	v_mul_f32_e32 v20, v20, v176
	v_fmac_f32_e32 v20, v24, v192
	v_fma_f32 v24, v24, v176, -v144
	v_mul_f32_e32 v145, v21, v193
	v_mul_f32_e32 v21, v21, v177
	v_fmac_f32_e32 v21, v25, v193
	v_fma_f32 v25, v25, v177, -v145
	v_mul_f32_e32 v142, v10, v194
	v_mul_f32_e32 v10, v10, v178
	v_fmac_f32_e32 v10, v14, v194
	v_fma_f32 v14, v14, v178, -v142
	v_mul_f32_e32 v143, v11, v195
	v_mul_f32_e32 v11, v11, v179
	v_fmac_f32_e32 v11, v15, v195
	v_fma_f32 v15, v15, v179, -v143
	v_mul_f32_e32 v144, v12, v196
	v_mul_f32_e32 v12, v12, v180
	v_fmac_f32_e32 v12, v16, v196
	v_fma_f32 v16, v16, v180, -v144
	v_mul_f32_e32 v145, v13, v197
	v_mul_f32_e32 v13, v13, v181
	v_fmac_f32_e32 v13, v17, v197
	v_fma_f32 v17, v17, v181, -v145
	v_mul_f32_e32 v142, v2, v198
	v_mul_f32_e32 v2, v2, v182
	v_fmac_f32_e32 v2, v6, v198
	v_fma_f32 v6, v6, v182, -v142
	v_mul_f32_e32 v143, v3, v199
	v_mul_f32_e32 v3, v3, v183
	v_fmac_f32_e32 v3, v7, v199
	v_fma_f32 v7, v7, v183, -v143
	v_mul_f32_e32 v144, v4, v200
	v_mul_f32_e32 v4, v4, v184
	v_fmac_f32_e32 v4, v8, v200
	v_fma_f32 v8, v8, v184, -v144
	v_mul_f32_e32 v145, v5, v201
	v_mul_f32_e32 v5, v5, v185
	v_fmac_f32_e32 v5, v9, v201
	v_fma_f32 v9, v9, v185, -v145
.Lip1_a1_norot:
	s_cmp_lg_u32 s46, 0
	s_cbranch_scc0 .Lip1_a1_noscale
	v_mul_f32_e32 v30, 0x3e000000, v30
	v_mul_f32_e32 v31, 0x3e000000, v31
	v_mul_f32_e32 v32, 0x3e000000, v32
	v_mul_f32_e32 v33, 0x3e000000, v33
	v_mul_f32_e32 v26, 0x3e000000, v26
	v_mul_f32_e32 v27, 0x3e000000, v27
	v_mul_f32_e32 v28, 0x3e000000, v28
	v_mul_f32_e32 v29, 0x3e000000, v29
	v_mul_f32_e32 v22, 0x3e000000, v22
	v_mul_f32_e32 v23, 0x3e000000, v23
	v_mul_f32_e32 v24, 0x3e000000, v24
	v_mul_f32_e32 v25, 0x3e000000, v25
	v_mul_f32_e32 v18, 0x3e000000, v18
	v_mul_f32_e32 v19, 0x3e000000, v19
	v_mul_f32_e32 v20, 0x3e000000, v20
	v_mul_f32_e32 v21, 0x3e000000, v21
	v_mul_f32_e32 v14, 0x3e000000, v14
	v_mul_f32_e32 v15, 0x3e000000, v15
	v_mul_f32_e32 v16, 0x3e000000, v16
	v_mul_f32_e32 v17, 0x3e000000, v17
	v_mul_f32_e32 v10, 0x3e000000, v10
	v_mul_f32_e32 v11, 0x3e000000, v11
	v_mul_f32_e32 v12, 0x3e000000, v12
	v_mul_f32_e32 v13, 0x3e000000, v13
	v_mul_f32_e32 v6, 0x3e000000, v6
	v_mul_f32_e32 v7, 0x3e000000, v7
	v_mul_f32_e32 v8, 0x3e000000, v8
	v_mul_f32_e32 v9, 0x3e000000, v9
	v_mul_f32_e32 v2, 0x3e000000, v2
	v_mul_f32_e32 v3, 0x3e000000, v3
	v_mul_f32_e32 v4, 0x3e000000, v4
	v_mul_f32_e32 v5, 0x3e000000, v5
.Lip1_a1_noscale:
	v_add_u32_e32 v234, 0xb8000, v169
	v_cvt_pk_bf16_f32 v146, v30, v31
	v_cvt_pk_bf16_f32 v147, v32, v33
	global_store_dwordx2 v234, v[146:147], s[60:61]
	v_cvt_pk_bf16_f32 v148, v26, v27
	v_cvt_pk_bf16_f32 v149, v28, v29
	global_store_dwordx2 v234, v[148:149], s[60:61] offset:32
	v_add_u32_e32 v235, 0xb9700, v169
	v_cvt_pk_bf16_f32 v150, v22, v23
	v_cvt_pk_bf16_f32 v151, v24, v25
	global_store_dwordx2 v235, v[150:151], s[60:61]
	v_cvt_pk_bf16_f32 v152, v18, v19
	v_cvt_pk_bf16_f32 v153, v20, v21
	global_store_dwordx2 v235, v[152:153], s[60:61] offset:32
	v_add_u32_e32 v236, 0xbae00, v169
	v_cvt_pk_bf16_f32 v146, v14, v15
	v_cvt_pk_bf16_f32 v147, v16, v17
	global_store_dwordx2 v236, v[146:147], s[60:61]
	v_cvt_pk_bf16_f32 v148, v10, v11
	v_cvt_pk_bf16_f32 v149, v12, v13
	global_store_dwordx2 v236, v[148:149], s[60:61] offset:32
	v_add_u32_e32 v237, 0xbc500, v169
	v_cvt_pk_bf16_f32 v150, v6, v7
	v_cvt_pk_bf16_f32 v151, v8, v9
	global_store_dwordx2 v237, v[150:151], s[60:61]
	v_cvt_pk_bf16_f32 v152, v2, v3
	v_cvt_pk_bf16_f32 v153, v4, v5
	global_store_dwordx2 v237, v[152:153], s[60:61] offset:32
	s_cmp_lg_u32 s46, 0
	s_cbranch_scc0 .Lip1_a1_nokt
	v_mul_f32_e32 v142, v30, v134
	v_mul_f32_e32 v143, v22, v135
	v_mul_f32_e32 v144, v14, v136
	v_mul_f32_e32 v145, v6, v137
	v_cvt_pk_bf16_f32 v146, v142, v143
	v_cvt_pk_bf16_f32 v147, v144, v145
	global_store_dwordx2 v168, v[146:147], s[24:25] offset:256
	v_add_u32_e32 v242, 0x8200, v168
	v_mul_f32_e32 v142, v31, v134
	v_mul_f32_e32 v143, v23, v135
	v_mul_f32_e32 v144, v15, v136
	v_mul_f32_e32 v145, v7, v137
	v_cvt_pk_bf16_f32 v148, v142, v143
	v_cvt_pk_bf16_f32 v149, v144, v145
	global_store_dwordx2 v242, v[148:149], s[24:25] offset:256
	v_add_u32_e32 v243, 0x10400, v168
	v_mul_f32_e32 v142, v32, v134
	v_mul_f32_e32 v143, v24, v135
	v_mul_f32_e32 v144, v16, v136
	v_mul_f32_e32 v145, v8, v137
	v_cvt_pk_bf16_f32 v150, v142, v143
	v_cvt_pk_bf16_f32 v151, v144, v145
	global_store_dwordx2 v243, v[150:151], s[24:25] offset:256
	v_add_u32_e32 v244, 0x18600, v168
	v_mul_f32_e32 v142, v33, v134
	v_mul_f32_e32 v143, v25, v135
	v_mul_f32_e32 v144, v17, v136
	v_mul_f32_e32 v145, v9, v137
	v_cvt_pk_bf16_f32 v152, v142, v143
	v_cvt_pk_bf16_f32 v153, v144, v145
	global_store_dwordx2 v244, v[152:153], s[24:25] offset:256
	v_add_u32_e32 v245, 0x82000, v168
	v_mul_f32_e32 v142, v26, v134
	v_mul_f32_e32 v143, v18, v135
	v_mul_f32_e32 v144, v10, v136
	v_mul_f32_e32 v145, v2, v137
	v_cvt_pk_bf16_f32 v146, v142, v143
	v_cvt_pk_bf16_f32 v147, v144, v145
	global_store_dwordx2 v245, v[146:147], s[24:25] offset:256
	v_add_u32_e32 v234, 0x8a200, v168
	v_mul_f32_e32 v142, v27, v134
	v_mul_f32_e32 v143, v19, v135
	v_mul_f32_e32 v144, v11, v136
	v_mul_f32_e32 v145, v3, v137
	v_cvt_pk_bf16_f32 v148, v142, v143
	v_cvt_pk_bf16_f32 v149, v144, v145
	global_store_dwordx2 v234, v[148:149], s[24:25] offset:256
	v_add_u32_e32 v235, 0x92400, v168
	v_mul_f32_e32 v142, v28, v134
	v_mul_f32_e32 v143, v20, v135
	v_mul_f32_e32 v144, v12, v136
	v_mul_f32_e32 v145, v4, v137
	v_cvt_pk_bf16_f32 v150, v142, v143
	v_cvt_pk_bf16_f32 v151, v144, v145
	global_store_dwordx2 v235, v[150:151], s[24:25] offset:256
	v_add_u32_e32 v236, 0x9a600, v168
	v_mul_f32_e32 v142, v29, v134
	v_mul_f32_e32 v143, v21, v135
	v_mul_f32_e32 v144, v13, v136
	v_mul_f32_e32 v145, v5, v137
	v_cvt_pk_bf16_f32 v152, v142, v143
	v_cvt_pk_bf16_f32 v153, v144, v145
	global_store_dwordx2 v236, v[152:153], s[24:25] offset:256
	v_mul_f32_e32 v142, v30, v138
	v_mul_f32_e32 v143, v22, v139
	v_mul_f32_e32 v144, v14, v140
	v_mul_f32_e32 v145, v6, v141
	v_cvt_pk_bf16_f32 v146, v142, v143
	v_cvt_pk_bf16_f32 v147, v144, v145
	global_store_dwordx2 v168, v[146:147], s[82:83] offset:256
	v_add_u32_e32 v237, 0x8200, v168
	v_mul_f32_e32 v142, v31, v138
	v_mul_f32_e32 v143, v23, v139
	v_mul_f32_e32 v144, v15, v140
	v_mul_f32_e32 v145, v7, v141
	v_cvt_pk_bf16_f32 v148, v142, v143
	v_cvt_pk_bf16_f32 v149, v144, v145
	global_store_dwordx2 v237, v[148:149], s[82:83] offset:256
	v_add_u32_e32 v242, 0x10400, v168
	v_mul_f32_e32 v142, v32, v138
	v_mul_f32_e32 v143, v24, v139
	v_mul_f32_e32 v144, v16, v140
	v_mul_f32_e32 v145, v8, v141
	v_cvt_pk_bf16_f32 v150, v142, v143
	v_cvt_pk_bf16_f32 v151, v144, v145
	global_store_dwordx2 v242, v[150:151], s[82:83] offset:256
	v_add_u32_e32 v243, 0x18600, v168
	v_mul_f32_e32 v142, v33, v138
	v_mul_f32_e32 v143, v25, v139
	v_mul_f32_e32 v144, v17, v140
	v_mul_f32_e32 v145, v9, v141
	v_cvt_pk_bf16_f32 v152, v142, v143
	v_cvt_pk_bf16_f32 v153, v144, v145
	global_store_dwordx2 v243, v[152:153], s[82:83] offset:256
	v_add_u32_e32 v244, 0x82000, v168
	v_mul_f32_e32 v142, v26, v138
	v_mul_f32_e32 v143, v18, v139
	v_mul_f32_e32 v144, v10, v140
	v_mul_f32_e32 v145, v2, v141
	v_cvt_pk_bf16_f32 v146, v142, v143
	v_cvt_pk_bf16_f32 v147, v144, v145
	global_store_dwordx2 v244, v[146:147], s[82:83] offset:256
	v_add_u32_e32 v245, 0x8a200, v168
	v_mul_f32_e32 v142, v27, v138
	v_mul_f32_e32 v143, v19, v139
	v_mul_f32_e32 v144, v11, v140
	v_mul_f32_e32 v145, v3, v141
	v_cvt_pk_bf16_f32 v148, v142, v143
	v_cvt_pk_bf16_f32 v149, v144, v145
	global_store_dwordx2 v245, v[148:149], s[82:83] offset:256
	v_add_u32_e32 v234, 0x92400, v168
	v_mul_f32_e32 v142, v28, v138
	v_mul_f32_e32 v143, v20, v139
	v_mul_f32_e32 v144, v12, v140
	v_mul_f32_e32 v145, v4, v141
	v_cvt_pk_bf16_f32 v150, v142, v143
	v_cvt_pk_bf16_f32 v151, v144, v145
	global_store_dwordx2 v234, v[150:151], s[82:83] offset:256
	v_add_u32_e32 v235, 0x9a600, v168
	v_mul_f32_e32 v142, v29, v138
	v_mul_f32_e32 v143, v21, v139
	v_mul_f32_e32 v144, v13, v140
	v_mul_f32_e32 v145, v5, v141
	v_cvt_pk_bf16_f32 v152, v142, v143
	v_cvt_pk_bf16_f32 v153, v144, v145
	global_store_dwordx2 v235, v[152:153], s[82:83] offset:256
.Lip1_a1_nokt:
.Lip1_end:
	s_branch .LBB0_358
